# combo3: GEMM K-loop LDS-DMA loads use SGPR base + 32-bit VGPR offset (no 64-bit VALU address adds) on top of combo2
# speedup vs baseline: 1.0284x; 1.0027x over previous
; #define PG8_STAGE(bufoff, gbase, voff) do { _Pragma("unroll") for (int _i = 0; _i < 2; ++_i) \
;     __builtin_amdgcn_global_load_lds((const unsigned*)((const char*)(gbase) + (voff)[_i]), (LAS unsigned*)(lds + (bufoff) + ldsw + _i * 8192), 16, 0, 0); } while (0)
; #define PG8_LDA(dst, b, h) do { _Pragma("unroll") for (int m = 0; m < 4; ++m) _Pragma("unroll") for (int k = 0; k < 2; ++k) dst[m][k] = *(const LAS bf16x8*)(lds + PG8_SA(b, h) + aoff + m * 2048 + k * 1024); } while (0)
; #define PG8_LDB(dst, b, h) do { _Pragma("unroll") for (int n = 0; n < 2; ++n) _Pragma("unroll") for (int k = 0; k < 2; ++k) dst[n][k] = *(const LAS bf16x8*)(lds + PG8_SB(b, h) + boff + n * 2048 + k * 1024); } while (0)
; #define PG8_MMA(ai, bj, At, Bt) do { __builtin_amdgcn_s_setprio(1); _Pragma("unroll") for (int m = 0; m < 4; ++m) _Pragma("unroll") for (int n = 0; n < 2; ++n) _Pragma("unroll") for (int k = 0; k < 2; ++k) \
;     acc[ai][bj][m][n] = __builtin_amdgcn_mfma_f32_16x16x32_bf16(Bt[n][k], At[m][k], acc[ai][bj][m][n], 0, 0, 0); __builtin_amdgcn_s_setprio(0); } while (0)
; #define PG8_WAIT_V(n) asm volatile("s_waitcnt vmcnt(" #n ")" ::: "memory")
; #define PG8_WAIT_L(n) asm volatile("s_waitcnt lgkmcnt(" #n ")" ::: "memory")
; #define PG8_BAR __builtin_amdgcn_s_barrier()
; #define PG8_SCHED __builtin_amdgcn_sched_barrier(0)
; template <class Epi, class Sched = StaticOrder>
; DI void gemm_phase(LAS unsigned char* lds, const Gemm g, const Sched& S, const Epi& E) {
;     ...
;     for (int t = 0; t < nt; t += 2) {
;       const bool last = (t == nt - 2);
;       const char* a1 = cA + (size_t)(t + 1) * kstep;
;       const char* a2 = last ? nA : cA + (size_t)(t + 2) * kstep; const char* b2 = last ? nB : cB + (size_t)(t + 2) * kstep;
;       const char* a3 = a2 + kstep; const char* b3 = b2 + kstep;
;       PG8_LDB(B0, 0, 0); PG8_SCHED; PG8_LDA(At, 0, 0); PG8_STAGE(PG8_SA(1, 1), a1 + hstep, voffA);
;       PG8_WAIT_L(8); PG8_BAR; PG8_WAIT_L(0); PG8_MMA(0, 0, At, B0); PG8_BAR; PG8_SCHED;
;       PG8_LDB(B1, 0, 1); PG8_STAGE(PG8_SB(0, 0), b2, voffB);
;       PG8_BAR; PG8_WAIT_L(0); PG8_MMA(0, 1, At, B1); PG8_BAR;
;       PG8_LDA(At, 0, 1); PG8_STAGE(PG8_SA(0, 0), a2, voffA);
;       PG8_BAR; PG8_WAIT_L(0); PG8_MMA(1, 0, At, B0); PG8_BAR; PG8_SCHED;
;       PG8_STAGE(PG8_SB(0, 1), b2 + hstep, voffB);
;       PG8_WAIT_V(6); PG8_BAR; PG8_MMA(1, 1, At, B1); PG8_BAR;
.LBB0_346:
	s_add_u32 s8, s6, 0xfff80080
	s_addc_u32 s9, s7, -1
	s_cmp_eq_u32 s52, 28
	s_cselect_b32 s11, s31, s9
	s_cselect_b32 s10, s42, s8
	s_cselect_b32 s9, s29, s45
	s_cselect_b32 s8, s43, s44
	s_add_i32 m0, s48, 0xc000
	ds_read_b128 v[162:165], v174
	ds_read_b128 v[166:169], v174 offset:1024
	ds_read_b128 v[178:181], v174 offset:2048
	ds_read_b128 v[182:185], v174 offset:3072
	ds_read_b128 v[186:189], v174 offset:4096
	ds_read_b128 v[190:193], v174 offset:5120
	ds_read_b128 v[194:197], v174 offset:6144
	ds_read_b128 v[198:201], v174 offset:7168
	global_load_lds_dwordx4 v146, s[6:7]
	s_add_i32 m0, s48, 0xe000
	s_nop 0
	global_load_lds_dwordx4 v148, s[6:7]
	s_waitcnt lgkmcnt(0)
	s_setprio 1
	s_barrier
	v_mfma_f32_16x16x32_bf16 v[124:127], v[128:131], v[162:165], v[124:127]
	v_mfma_f32_16x16x32_bf16 v[120:123], v[154:157], v[162:165], v[120:123]
	v_mfma_f32_16x16x32_bf16 v[108:111], v[128:131], v[178:181], v[108:111]
	v_mfma_f32_16x16x32_bf16 v[104:107], v[154:157], v[178:181], v[104:107]
	v_mfma_f32_16x16x32_bf16 v[100:103], v[128:131], v[186:189], v[100:103]
	v_mfma_f32_16x16x32_bf16 v[92:95], v[154:157], v[186:189], v[92:95]
	v_mfma_f32_16x16x32_bf16 v[84:87], v[128:131], v[194:197], v[84:87]
	v_mfma_f32_16x16x32_bf16 v[76:79], v[154:157], v[194:197], v[76:79]
	v_mfma_f32_16x16x32_bf16 v[124:127], v[132:135], v[166:169], v[124:127]
	v_mfma_f32_16x16x32_bf16 v[120:123], v[158:161], v[166:169], v[120:123]
	v_mfma_f32_16x16x32_bf16 v[108:111], v[132:135], v[182:185], v[108:111]
	v_mfma_f32_16x16x32_bf16 v[104:107], v[158:161], v[182:185], v[104:107]
	v_mfma_f32_16x16x32_bf16 v[100:103], v[132:135], v[190:193], v[100:103]
	v_mfma_f32_16x16x32_bf16 v[92:95], v[158:161], v[190:193], v[92:95]
	v_mfma_f32_16x16x32_bf16 v[84:87], v[132:135], v[198:201], v[84:87]
	v_mfma_f32_16x16x32_bf16 v[76:79], v[158:161], v[198:201], v[76:79]
	s_barrier
	s_setprio 0
	s_add_i32 s53, s65, s41
	s_add_u32 s98, s8, 0x80
	s_addc_u32 s99, s9, 0
	s_mov_b32 m0, s53
	ds_read_b128 v[202:205], v175
	ds_read_b128 v[206:209], v175 offset:1024
	ds_read_b128 v[212:215], v175 offset:2048
	ds_read_b128 v[216:219], v175 offset:3072
	global_load_lds_dwordx4 v140, s[8:9]
	s_add_i32 m0, s53, 0x2000
	s_nop 0
	global_load_lds_dwordx4 v136, s[8:9]
	s_waitcnt lgkmcnt(0)
	s_setprio 1
	s_barrier
	v_mfma_f32_16x16x32_bf16 v[116:119], v[202:205], v[162:165], v[116:119]
	v_mfma_f32_16x16x32_bf16 v[112:115], v[212:215], v[162:165], v[112:115]
	v_mfma_f32_16x16x32_bf16 v[96:99], v[202:205], v[178:181], v[96:99]
	v_mfma_f32_16x16x32_bf16 v[88:91], v[212:215], v[178:181], v[88:91]
	v_mfma_f32_16x16x32_bf16 v[80:83], v[202:205], v[186:189], v[80:83]
	v_mfma_f32_16x16x32_bf16 v[72:75], v[212:215], v[186:189], v[72:75]
	v_mfma_f32_16x16x32_bf16 v[68:71], v[202:205], v[194:197], v[68:71]
	v_mfma_f32_16x16x32_bf16 v[64:67], v[212:215], v[194:197], v[64:67]
	v_mfma_f32_16x16x32_bf16 v[116:119], v[206:209], v[166:169], v[116:119]
	v_mfma_f32_16x16x32_bf16 v[112:115], v[216:219], v[166:169], v[112:115]
	v_mfma_f32_16x16x32_bf16 v[96:99], v[206:209], v[182:185], v[96:99]
	v_mfma_f32_16x16x32_bf16 v[88:91], v[216:219], v[182:185], v[88:91]
	v_mfma_f32_16x16x32_bf16 v[80:83], v[206:209], v[190:193], v[80:83]
	v_mfma_f32_16x16x32_bf16 v[72:75], v[216:219], v[190:193], v[72:75]
	v_mfma_f32_16x16x32_bf16 v[68:71], v[206:209], v[198:201], v[68:71]
	v_mfma_f32_16x16x32_bf16 v[64:67], v[216:219], v[198:201], v[64:67]
	s_barrier
	s_setprio 0
	s_mov_b32 m0, s48
	s_add_u32 s100, s10, 0x80
	s_addc_u32 s101, s11, 0
	ds_read_b128 v[162:165], v174 offset:16384
	ds_read_b128 v[166:169], v174 offset:17408
	ds_read_b128 v[178:181], v174 offset:18432
	ds_read_b128 v[182:185], v174 offset:19456
	ds_read_b128 v[186:189], v174 offset:20480
	ds_read_b128 v[190:193], v174 offset:21504
	ds_read_b128 v[194:197], v174 offset:22528
	ds_read_b128 v[198:201], v174 offset:23552
	global_load_lds_dwordx4 v142, s[10:11]
	s_mov_b32 m0, s49
	s_nop 0
	global_load_lds_dwordx4 v138, s[10:11]
	s_waitcnt vmcnt(10)
	s_waitcnt lgkmcnt(0)
	s_setprio 1
	s_barrier
	v_mfma_f32_16x16x32_bf16 v[60:63], v[128:131], v[162:165], v[60:63]
	v_mfma_f32_16x16x32_bf16 v[56:59], v[154:157], v[162:165], v[56:59]
	v_mfma_f32_16x16x32_bf16 v[52:55], v[128:131], v[178:181], v[52:55]
	v_mfma_f32_16x16x32_bf16 v[44:47], v[154:157], v[178:181], v[44:47]
	v_mfma_f32_16x16x32_bf16 v[36:39], v[128:131], v[186:189], v[36:39]
	v_mfma_f32_16x16x32_bf16 v[28:31], v[154:157], v[186:189], v[28:31]
	v_mfma_f32_16x16x32_bf16 v[20:23], v[128:131], v[194:197], v[20:23]
	v_mfma_f32_16x16x32_bf16 v[12:15], v[154:157], v[194:197], v[12:15]
	v_mfma_f32_16x16x32_bf16 v[60:63], v[132:135], v[166:169], v[60:63]
	v_mfma_f32_16x16x32_bf16 v[56:59], v[158:161], v[166:169], v[56:59]
	v_mfma_f32_16x16x32_bf16 v[52:55], v[132:135], v[182:185], v[52:55]
	v_mfma_f32_16x16x32_bf16 v[44:47], v[158:161], v[182:185], v[44:47]
	v_mfma_f32_16x16x32_bf16 v[36:39], v[132:135], v[190:193], v[36:39]
	v_mfma_f32_16x16x32_bf16 v[28:31], v[158:161], v[190:193], v[28:31]
	v_mfma_f32_16x16x32_bf16 v[20:23], v[132:135], v[198:201], v[20:23]
	v_mfma_f32_16x16x32_bf16 v[12:15], v[158:161], v[198:201], v[12:15]
	s_barrier
	s_setprio 0
	s_add_u32 s54, s8, 0x80000
	s_addc_u32 s55, s9, 0
	s_add_i32 s53, s72, s41
	s_mov_b32 m0, s53
	s_nop 0
	global_load_lds_dwordx4 v140, s[54:55]
	s_add_i32 m0, s53, 0x2000
	s_nop 0
	global_load_lds_dwordx4 v136, s[54:55]
	s_add_i32 s53, 0, 0x18000
	v_add_u32_e32 v158, s53, v171
	ds_read_b128 v[128:131], v158
	ds_read_b128 v[132:135], v158 offset:1024
	ds_read_b128 v[154:157], v158 offset:2048
	ds_read_b128 v[158:161], v158 offset:3072
	s_waitcnt vmcnt(6)
	s_setprio 1
	s_barrier
; #define PG8_STAGE(bufoff, gbase, voff) do { _Pragma("unroll") for (int _i = 0; _i < 2; ++_i) \
;     __builtin_amdgcn_global_load_lds((const unsigned*)((const char*)(gbase) + (voff)[_i]), (LAS unsigned*)(lds + (bufoff) + ldsw + _i * 8192), 16, 0, 0); } while (0)
; #define PG8_LDA(dst, b, h) do { _Pragma("unroll") for (int m = 0; m < 4; ++m) _Pragma("unroll") for (int k = 0; k < 2; ++k) dst[m][k] = *(const LAS bf16x8*)(lds + PG8_SA(b, h) + aoff + m * 2048 + k * 1024); } while (0)
; #define PG8_LDB(dst, b, h) do { _Pragma("unroll") for (int n = 0; n < 2; ++n) _Pragma("unroll") for (int k = 0; k < 2; ++k) dst[n][k] = *(const LAS bf16x8*)(lds + PG8_SB(b, h) + boff + n * 2048 + k * 1024); } while (0)
; #define PG8_MMA(ai, bj, At, Bt) do { __builtin_amdgcn_s_setprio(1); _Pragma("unroll") for (int m = 0; m < 4; ++m) _Pragma("unroll") for (int n = 0; n < 2; ++n) _Pragma("unroll") for (int k = 0; k < 2; ++k) \
;     acc[ai][bj][m][n] = __builtin_amdgcn_mfma_f32_16x16x32_bf16(Bt[n][k], At[m][k], acc[ai][bj][m][n], 0, 0, 0); __builtin_amdgcn_s_setprio(0); } while (0)
; #define PG8_WAIT_V(n) asm volatile("s_waitcnt vmcnt(" #n ")" ::: "memory")
; #define PG8_WAIT_L(n) asm volatile("s_waitcnt lgkmcnt(" #n ")" ::: "memory")
; #define PG8_BAR __builtin_amdgcn_s_barrier()
; #define PG8_SCHED __builtin_amdgcn_sched_barrier(0)
; template <class Epi, class Sched = StaticOrder>
; DI void gemm_phase(LAS unsigned char* lds, const Gemm g, const Sched& S, const Epi& E) {
;     ...
;       PG8_WAIT_V(6); PG8_BAR; PG8_MMA(1, 1, At, B1); PG8_BAR;
;       PG8_LDB(B0, 1, 0); PG8_SCHED; PG8_LDA(At, 1, 0); PG8_STAGE(PG8_SA(0, 1), a2 + hstep, voffA);
;       PG8_WAIT_L(8); PG8_BAR; PG8_WAIT_L(0); PG8_MMA(0, 0, At, B0); PG8_BAR; PG8_SCHED;
;       PG8_LDB(B1, 1, 1); PG8_STAGE(PG8_SB(1, 0), b3, voffB);
;       PG8_BAR; PG8_WAIT_L(0); PG8_MMA(0, 1, At, B1); PG8_BAR;
;       PG8_LDA(At, 1, 1); PG8_STAGE(PG8_SA(1, 0), a3, voffA);
;       PG8_BAR; PG8_WAIT_L(0); PG8_MMA(1, 0, At, B0); PG8_BAR; PG8_SCHED;
	v_mfma_f32_16x16x32_bf16 v[48:51], v[202:205], v[162:165], v[48:51]
	v_mfma_f32_16x16x32_bf16 v[40:43], v[212:215], v[162:165], v[40:43]
	v_mfma_f32_16x16x32_bf16 v[32:35], v[202:205], v[178:181], v[32:35]
	v_mfma_f32_16x16x32_bf16 v[24:27], v[212:215], v[178:181], v[24:27]
	v_mfma_f32_16x16x32_bf16 v[16:19], v[202:205], v[186:189], v[16:19]
	v_mfma_f32_16x16x32_bf16 v[8:11], v[212:215], v[186:189], v[8:11]
	v_mfma_f32_16x16x32_bf16 v[4:7], v[202:205], v[194:197], v[4:7]
	v_mfma_f32_16x16x32_bf16 v[0:3], v[212:215], v[194:197], v[0:3]
	v_mfma_f32_16x16x32_bf16 v[48:51], v[206:209], v[166:169], v[48:51]
	v_mfma_f32_16x16x32_bf16 v[40:43], v[216:219], v[166:169], v[40:43]
	v_mfma_f32_16x16x32_bf16 v[32:35], v[206:209], v[182:185], v[32:35]
	v_mfma_f32_16x16x32_bf16 v[24:27], v[216:219], v[182:185], v[24:27]
	v_mfma_f32_16x16x32_bf16 v[16:19], v[206:209], v[190:193], v[16:19]
	v_mfma_f32_16x16x32_bf16 v[8:11], v[216:219], v[190:193], v[8:11]
	v_mfma_f32_16x16x32_bf16 v[4:7], v[206:209], v[198:201], v[4:7]
	v_mfma_f32_16x16x32_bf16 v[0:3], v[216:219], v[198:201], v[0:3]
	s_barrier
	s_setprio 0
	s_add_u32 s10, s10, 0x80000
	s_addc_u32 s11, s11, 0
	s_mov_b32 m0, s50
	ds_read_b128 v[162:165], v174 offset:32768
	ds_read_b128 v[166:169], v174 offset:33792
	ds_read_b128 v[178:181], v174 offset:34816
	ds_read_b128 v[182:185], v174 offset:35840
	ds_read_b128 v[186:189], v174 offset:36864
	ds_read_b128 v[190:193], v174 offset:37888
	ds_read_b128 v[194:197], v174 offset:38912
	ds_read_b128 v[198:201], v174 offset:39936
	global_load_lds_dwordx4 v142, s[10:11]
	s_mov_b32 m0, s51
	s_nop 0
	global_load_lds_dwordx4 v138, s[10:11]
	s_waitcnt lgkmcnt(0)
	s_setprio 1
	s_barrier
	v_mfma_f32_16x16x32_bf16 v[124:127], v[128:131], v[162:165], v[124:127]
	v_mfma_f32_16x16x32_bf16 v[120:123], v[154:157], v[162:165], v[120:123]
	v_mfma_f32_16x16x32_bf16 v[108:111], v[128:131], v[178:181], v[108:111]
	v_mfma_f32_16x16x32_bf16 v[104:107], v[154:157], v[178:181], v[104:107]
	v_mfma_f32_16x16x32_bf16 v[100:103], v[128:131], v[186:189], v[100:103]
	v_mfma_f32_16x16x32_bf16 v[92:95], v[154:157], v[186:189], v[92:95]
	v_mfma_f32_16x16x32_bf16 v[84:87], v[128:131], v[194:197], v[84:87]
	v_mfma_f32_16x16x32_bf16 v[76:79], v[154:157], v[194:197], v[76:79]
	v_mfma_f32_16x16x32_bf16 v[124:127], v[132:135], v[166:169], v[124:127]
	v_mfma_f32_16x16x32_bf16 v[120:123], v[158:161], v[166:169], v[120:123]
	v_mfma_f32_16x16x32_bf16 v[108:111], v[132:135], v[182:185], v[108:111]
	v_mfma_f32_16x16x32_bf16 v[104:107], v[158:161], v[182:185], v[104:107]
	v_mfma_f32_16x16x32_bf16 v[100:103], v[132:135], v[190:193], v[100:103]
	v_mfma_f32_16x16x32_bf16 v[92:95], v[158:161], v[190:193], v[92:95]
	v_mfma_f32_16x16x32_bf16 v[84:87], v[132:135], v[198:201], v[84:87]
	v_mfma_f32_16x16x32_bf16 v[76:79], v[158:161], v[198:201], v[76:79]
	s_barrier
	s_setprio 0
	s_add_i32 s10, 0, 0x1c000
	s_add_i32 s11, s53, s41
	v_add_u32_e32 v177, s10, v171
	s_mov_b32 m0, s11
	ds_read_b128 v[202:205], v177
	ds_read_b128 v[206:209], v177 offset:1024
	ds_read_b128 v[212:215], v177 offset:2048
	ds_read_b128 v[216:219], v177 offset:3072
	global_load_lds_dwordx4 v140, s[98:99]
	s_add_i32 m0, s11, 0x2000
	s_nop 0
	global_load_lds_dwordx4 v136, s[98:99]
	s_waitcnt lgkmcnt(0)
	s_setprio 1
	s_barrier
	v_mfma_f32_16x16x32_bf16 v[116:119], v[202:205], v[162:165], v[116:119]
	v_mfma_f32_16x16x32_bf16 v[112:115], v[212:215], v[162:165], v[112:115]
	v_mfma_f32_16x16x32_bf16 v[96:99], v[202:205], v[178:181], v[96:99]
	v_mfma_f32_16x16x32_bf16 v[88:91], v[212:215], v[178:181], v[88:91]
	v_mfma_f32_16x16x32_bf16 v[80:83], v[202:205], v[186:189], v[80:83]
	v_mfma_f32_16x16x32_bf16 v[72:75], v[212:215], v[186:189], v[72:75]
	v_mfma_f32_16x16x32_bf16 v[68:71], v[202:205], v[194:197], v[68:71]
	v_mfma_f32_16x16x32_bf16 v[64:67], v[212:215], v[194:197], v[64:67]
	v_mfma_f32_16x16x32_bf16 v[116:119], v[206:209], v[166:169], v[116:119]
	v_mfma_f32_16x16x32_bf16 v[112:115], v[216:219], v[166:169], v[112:115]
	v_mfma_f32_16x16x32_bf16 v[96:99], v[206:209], v[182:185], v[96:99]
	v_mfma_f32_16x16x32_bf16 v[88:91], v[216:219], v[182:185], v[88:91]
	v_mfma_f32_16x16x32_bf16 v[80:83], v[206:209], v[190:193], v[80:83]
	v_mfma_f32_16x16x32_bf16 v[72:75], v[216:219], v[190:193], v[72:75]
	v_mfma_f32_16x16x32_bf16 v[68:71], v[206:209], v[198:201], v[68:71]
	v_mfma_f32_16x16x32_bf16 v[64:67], v[216:219], v[198:201], v[64:67]
	s_barrier
	s_setprio 0
	s_mov_b32 m0, s56
	ds_read_b128 v[162:165], v174 offset:49152
	ds_read_b128 v[166:169], v174 offset:50176
	ds_read_b128 v[178:181], v174 offset:51200
	ds_read_b128 v[182:185], v174 offset:52224
	ds_read_b128 v[186:189], v174 offset:53248
	ds_read_b128 v[190:193], v174 offset:54272
	ds_read_b128 v[194:197], v174 offset:55296
	ds_read_b128 v[198:201], v174 offset:56320
	global_load_lds_dwordx4 v142, s[100:101]
	s_mov_b32 m0, s57
	s_nop 0
	global_load_lds_dwordx4 v138, s[100:101]
	s_waitcnt vmcnt(10)
	s_waitcnt lgkmcnt(0)
	s_setprio 1
	s_barrier
	v_mfma_f32_16x16x32_bf16 v[60:63], v[128:131], v[162:165], v[60:63]
	v_mfma_f32_16x16x32_bf16 v[56:59], v[154:157], v[162:165], v[56:59]
	v_mfma_f32_16x16x32_bf16 v[52:55], v[128:131], v[178:181], v[52:55]
	v_mfma_f32_16x16x32_bf16 v[44:47], v[154:157], v[178:181], v[44:47]
	v_mfma_f32_16x16x32_bf16 v[36:39], v[128:131], v[186:189], v[36:39]
	v_mfma_f32_16x16x32_bf16 v[28:31], v[154:157], v[186:189], v[28:31]
	v_mfma_f32_16x16x32_bf16 v[20:23], v[128:131], v[194:197], v[20:23]
	v_mfma_f32_16x16x32_bf16 v[12:15], v[154:157], v[194:197], v[12:15]
	v_mfma_f32_16x16x32_bf16 v[60:63], v[132:135], v[166:169], v[60:63]
	v_mfma_f32_16x16x32_bf16 v[56:59], v[158:161], v[166:169], v[56:59]
	v_mfma_f32_16x16x32_bf16 v[52:55], v[132:135], v[182:185], v[52:55]
	v_mfma_f32_16x16x32_bf16 v[44:47], v[158:161], v[182:185], v[44:47]
	v_mfma_f32_16x16x32_bf16 v[36:39], v[132:135], v[190:193], v[36:39]
	v_mfma_f32_16x16x32_bf16 v[28:31], v[158:161], v[190:193], v[28:31]
	v_mfma_f32_16x16x32_bf16 v[20:23], v[132:135], v[198:201], v[20:23]
	v_mfma_f32_16x16x32_bf16 v[12:15], v[158:161], v[198:201], v[12:15]
	s_barrier
; #define PG8_STAGE(bufoff, gbase, voff) do { _Pragma("unroll") for (int _i = 0; _i < 2; ++_i) \
;     __builtin_amdgcn_global_load_lds((const unsigned*)((const char*)(gbase) + (voff)[_i]), (LAS unsigned*)(lds + (bufoff) + ldsw + _i * 8192), 16, 0, 0); } while (0)
; #define PG8_MMA(ai, bj, At, Bt) do { __builtin_amdgcn_s_setprio(1); _Pragma("unroll") for (int m = 0; m < 4; ++m) _Pragma("unroll") for (int n = 0; n < 2; ++n) _Pragma("unroll") for (int k = 0; k < 2; ++k) \
;     acc[ai][bj][m][n] = __builtin_amdgcn_mfma_f32_16x16x32_bf16(Bt[n][k], At[m][k], acc[ai][bj][m][n], 0, 0, 0); __builtin_amdgcn_s_setprio(0); } while (0)
; #define PG8_WAIT_V(n) asm volatile("s_waitcnt vmcnt(" #n ")" ::: "memory")
; #define PG8_WAIT_L(n) asm volatile("s_waitcnt lgkmcnt(" #n ")" ::: "memory")
; #define PG8_BAR __builtin_amdgcn_s_barrier()
; #define PG8_SCHED __builtin_amdgcn_sched_barrier(0)
;   DI void operator()(const f32x4 (&acc)[2][2][4][2], const Unit& u, int wr, int wc, int fr, int fq) const {
;     const int row0 = u.pm * BM + wr * 64 + fr, col0 = u.pn * BM + wc * 32 + 8 * fq;
;     float rsv[2][4];
; #pragma unroll
;     for (int ai = 0; ai < 2; ++ai)
; #pragma unroll
;       for (int m = 0; m < 4; ++m) rsv[ai][m] = row_rstd(ssq, row0 + ai * HALF + m * 16, fq);
; template <class Epi, class Sched = StaticOrder>
; DI void gemm_phase(LAS unsigned char* lds, const Gemm g, const Sched& S, const Epi& E) {
;     ...
;       PG8_BAR; PG8_WAIT_L(0); PG8_MMA(1, 0, At, B0); PG8_BAR; PG8_SCHED;
;       PG8_STAGE(PG8_SB(1, 1), b3 + hstep, voffB);
;       PG8_WAIT_V(6); PG8_BAR; PG8_MMA(1, 1, At, B1); PG8_BAR;
;     }
	s_setprio 0
	s_add_u32 s8, s8, 0x80080
	s_addc_u32 s9, s9, 0
	s_add_i32 s10, s10, s41
	s_mov_b32 m0, s10
	s_nop 0
	global_load_lds_dwordx4 v140, s[8:9]
	s_add_i32 m0, s10, 0x2000
	s_nop 0
	global_load_lds_dwordx4 v136, s[8:9]
	ds_read_b128 v[128:131], v173
	ds_read_b128 v[132:135], v173 offset:1024
	ds_read_b128 v[154:157], v173 offset:2048
	ds_read_b128 v[158:161], v173 offset:3072
	s_waitcnt vmcnt(6)
	s_setprio 1
	s_barrier
	v_mfma_f32_16x16x32_bf16 v[48:51], v[202:205], v[162:165], v[48:51]
	v_mfma_f32_16x16x32_bf16 v[40:43], v[212:215], v[162:165], v[40:43]
	v_mfma_f32_16x16x32_bf16 v[32:35], v[202:205], v[178:181], v[32:35]
	v_mfma_f32_16x16x32_bf16 v[24:27], v[212:215], v[178:181], v[24:27]
	v_mfma_f32_16x16x32_bf16 v[16:19], v[202:205], v[186:189], v[16:19]
	v_mfma_f32_16x16x32_bf16 v[8:11], v[212:215], v[186:189], v[8:11]
	v_mfma_f32_16x16x32_bf16 v[4:7], v[202:205], v[194:197], v[4:7]
	v_mfma_f32_16x16x32_bf16 v[0:3], v[212:215], v[194:197], v[0:3]
	v_mfma_f32_16x16x32_bf16 v[48:51], v[206:209], v[166:169], v[48:51]
	v_mfma_f32_16x16x32_bf16 v[40:43], v[216:219], v[166:169], v[40:43]
	v_mfma_f32_16x16x32_bf16 v[32:35], v[206:209], v[182:185], v[32:35]
	v_mfma_f32_16x16x32_bf16 v[24:27], v[216:219], v[182:185], v[24:27]
	v_mfma_f32_16x16x32_bf16 v[16:19], v[206:209], v[190:193], v[16:19]
	v_mfma_f32_16x16x32_bf16 v[8:11], v[216:219], v[190:193], v[8:11]
	v_mfma_f32_16x16x32_bf16 v[4:7], v[206:209], v[198:201], v[4:7]
	v_mfma_f32_16x16x32_bf16 v[0:3], v[216:219], v[198:201], v[0:3]
	s_add_i32 s52, s52, 2
	s_add_u32 s6, s6, 0x100
	s_addc_u32 s7, s7, 0
	s_add_u32 s44, s44, 0x100
	s_addc_u32 s45, s45, 0
	s_cmp_gt_u32 s52, 29
	s_barrier
	s_setprio 0
	s_cbranch_scc0 .LBB0_346
	s_waitcnt lgkmcnt(0)
	v_lshl_add_u32 v168, s4, 8, v170
	v_ashrrev_i32_e32 v169, 31, v168
	v_or_b32_e32 v154, 16, v168
	v_lshlrev_b64 v[128:129], 7, v[168:169]
	v_ashrrev_i32_e32 v155, 31, v154
	v_lshl_add_u64 v[128:129], v[144:145], 0, v[128:129]
	v_lshlrev_b64 v[156:157], 7, v[154:155]
	global_load_dwordx4 v[132:135], v[128:129], off
	s_nop 0
	global_load_dwordx4 v[128:131], v[128:129], off offset:16
	v_lshl_add_u64 v[156:157], v[144:145], 0, v[156:157]
	global_load_dwordx4 v[178:181], v[156:157], off
	global_load_dwordx4 v[182:185], v[156:157], off offset:16
	v_or_b32_e32 v160, 32, v168
	v_ashrrev_i32_e32 v161, 31, v160
	v_lshlrev_b64 v[156:157], 7, v[160:161]
	v_lshl_add_u64 v[156:157], v[144:145], 0, v[156:157]
	global_load_dwordx4 v[186:189], v[156:157], off
	global_load_dwordx4 v[190:193], v[156:157], off offset:16
	v_or_b32_e32 v156, 48, v168
	v_ashrrev_i32_e32 v157, 31, v156
	v_lshlrev_b64 v[158:159], 7, v[156:157]
	v_lshl_add_u64 v[158:159], v[144:145], 0, v[158:159]
	global_load_dwordx4 v[194:197], v[158:159], off
	global_load_dwordx4 v[198:201], v[158:159], off offset:16
	v_add_u32_e32 v164, 0x80, v168
	v_ashrrev_i32_e32 v165, 31, v164
	v_lshlrev_b64 v[158:159], 7, v[164:165]
	v_lshl_add_u64 v[158:159], v[144:145], 0, v[158:159]
	global_load_dwordx4 v[202:205], v[158:159], off
	global_load_dwordx4 v[206:209], v[158:159], off offset:16
	v_add_u32_e32 v158, 0x90, v168
	v_ashrrev_i32_e32 v159, 31, v158
	v_lshlrev_b64 v[162:163], 7, v[158:159]
	v_lshl_add_u64 v[162:163], v[144:145], 0, v[162:163]
	global_load_dwordx4 v[212:215], v[162:163], off
	global_load_dwordx4 v[216:219], v[162:163], off offset:16
	v_add_u32_e32 v166, 0xa0, v168
	v_ashrrev_i32_e32 v167, 31, v166
	v_lshlrev_b64 v[162:163], 7, v[166:167]
	v_lshl_add_u64 v[162:163], v[144:145], 0, v[162:163]
	global_load_dwordx4 v[220:223], v[162:163], off
	global_load_dwordx4 v[224:227], v[162:163], off offset:16
	v_add_u32_e32 v162, 0xb0, v168
	v_ashrrev_i32_e32 v163, 31, v162
	v_lshlrev_b64 v[228:229], 7, v[162:163]
	v_lshl_add_u64 v[232:233], v[144:145], 0, v[228:229]
	global_load_dwordx4 v[228:231], v[232:233], off
	s_nop 0
	global_load_dwordx4 v[232:235], v[232:233], off offset:16
	s_waitcnt vmcnt(0)
	v_mov_b32_e32 v236, v132
	v_mov_b32_e32 v237, v128
	v_mov_b32_e32 v128, v133
	v_mov_b32_e32 v132, v134
	v_mov_b32_e32 v133, v130
	v_mov_b32_e32 v130, v135
	v_pk_add_f32 v[130:131], v[132:133], v[130:131]
	v_mov_b32_e32 v132, v178
	v_mov_b32_e32 v133, v182
	v_mov_b32_e32 v182, v179
	v_mov_b32_e32 v134, v180
	v_mov_b32_e32 v135, v184
	v_mov_b32_e32 v184, v181
	v_pk_add_f32 v[128:129], v[236:237], v[128:129]
	v_pk_add_f32 v[132:133], v[132:133], v[182:183]
	v_pk_add_f32 v[134:135], v[134:135], v[184:185]
	v_pk_add_f32 v[128:129], v[128:129], v[130:131]
	v_pk_add_f32 v[130:131], v[132:133], v[134:135]
	v_mov_b32_e32 v133, v128
	v_mov_b32_e32 v132, v130
	v_and_b32_e32 v130, 64, v176
	v_add_u32_e32 v155, 64, v130
	v_xor_b32_e32 v130, 16, v176
	v_cmp_lt_i32_e32 vcc, v130, v155
	v_mov_b32_e32 v128, v131
	v_pk_add_f32 v[128:129], v[132:133], v[128:129]
	v_cndmask_b32_e32 v130, v176, v130, vcc
	v_lshlrev_b32_e32 v157, 2, v130
	ds_bpermute_b32 v131, v157, v129
	ds_bpermute_b32 v130, v157, v128
	v_mov_b32_e32 v178, v186
	v_mov_b32_e32 v179, v190
	v_mov_b32_e32 v190, v187
	v_mov_b32_e32 v186, v194
	s_waitcnt lgkmcnt(0)
	v_pk_add_f32 v[128:129], v[128:129], v[130:131]
	v_xor_b32_e32 v130, 32, v176
	v_cmp_lt_i32_e32 vcc, v130, v155
	v_mov_b32_e32 v187, v198
	v_mov_b32_e32 v198, v195
	v_cndmask_b32_e32 v130, v176, v130, vcc
	v_lshlrev_b32_e32 v155, 2, v130
	ds_bpermute_b32 v131, v155, v129
	ds_bpermute_b32 v130, v155, v128
	v_pk_add_f32 v[182:183], v[186:187], v[198:199]
	v_mov_b32_e32 v180, v188
	v_mov_b32_e32 v181, v192
	v_mov_b32_e32 v192, v189
	s_waitcnt lgkmcnt(0)
; DI unsigned pack2(float lo, float hi) { f32x2 v = {lo, hi}; bf16v2 r = __builtin_convertvector(v, bf16v2); return __builtin_bit_cast(unsigned, r); }
; DI float row_rstd(const float* ssq, int row, int fq) {
;   const f32x4 a = *(const f32x4*)(ssq + (size_t)row * 32 + fq * 8), b = *(const f32x4*)(ssq + (size_t)row * 32 + fq * 8 + 4);
;   float sm = ((a[0] + a[1]) + (a[2] + a[3])) + ((b[0] + b[1]) + (b[2] + b[3]));
;   sm += __shfl_xor(sm, 16); sm += __shfl_xor(sm, 32);
;   return rsqrtf(sm * (1.0f / 2048.f) + 1e-6f);
; }
;   DI void operator()(const f32x4 (&acc)[2][2][4][2], const Unit& u, int wr, int wc, int fr, int fq) const {
;     const int row0 = u.pm * BM + wr * 64 + fr, col0 = u.pn * BM + wc * 32 + 8 * fq;
;     float rsv[2][4];
; #pragma unroll
;     for (int ai = 0; ai < 2; ++ai)
; #pragma unroll
;       for (int m = 0; m < 4; ++m) rsv[ai][m] = row_rstd(ssq, row0 + ai * HALF + m * 16, fq);
; #pragma unroll
;     for (int ai = 0; ai < 2; ++ai)
; #pragma unroll
;       for (int m = 0; m < 4; ++m) {
;         const int row = row0 + ai * HALF + m * 16;
;         const float rs = rsv[ai][m];
;         bf16_t* rowp = O + (size_t)row * ldc + col0;
; #pragma unroll
;         for (int bj = 0; bj < 2; ++bj) {
;           const f32x4 v0 = acc[ai][bj][m][0] * rs, v1 = acc[ai][bj][m][1] * rs;
;           u32x4 w; w.x = pack2(v0[0], v0[1]); w.y = pack2(v0[2], v0[3]); w.z = pack2(v1[0], v1[1]); w.w = pack2(v1[2], v1[3]);
;           *(u32x4*)(rowp + bj * HALF) = w;
	v_pk_add_f32 v[128:129], v[128:129], v[130:131]
	v_mov_b64_e32 v[130:131], s[26:27]
	v_pk_fma_f32 v[128:129], v[128:129], s[24:25], v[130:131] op_sel_hi:[1,0,0]
	v_mov_b32_e32 v188, v196
	v_mul_f32_e32 v159, 0x4b800000, v129
	v_cmp_gt_f32_e32 vcc, s73, v129
	v_mov_b32_e32 v189, v200
	v_mov_b32_e32 v200, v197
	v_cndmask_b32_e32 v129, v129, v159, vcc
	v_rsq_f32_e32 v129, v129
	v_pk_add_f32 v[178:179], v[178:179], v[190:191]
	v_pk_add_f32 v[180:181], v[180:181], v[192:193]
	v_pk_add_f32 v[184:185], v[188:189], v[200:201]
	v_mul_f32_e32 v159, 0x45800000, v129
	v_cndmask_b32_e32 v198, v129, v159, vcc
	v_pk_mul_f32 v[126:127], v[126:127], v[198:199] op_sel_hi:[1,0]
	v_pk_mul_f32 v[124:125], v[124:125], v[198:199] op_sel_hi:[1,0]
	v_pk_mul_f32 v[122:123], v[122:123], v[198:199] op_sel_hi:[1,0]
	v_pk_mul_f32 v[120:121], v[120:121], v[198:199] op_sel_hi:[1,0]
	v_cvt_pk_bf16_f32 v124, v124, v125
	v_cvt_pk_bf16_f32 v125, v126, v127
	v_cvt_pk_bf16_f32 v127, v122, v123
	v_lshl_or_b32 v122, s5, 8, v172
	v_cvt_pk_bf16_f32 v126, v120, v121
	v_ashrrev_i32_e32 v123, 31, v122
	v_mov_b64_e32 v[120:121], s[2:3]
	v_mad_i64_i32 v[168:169], s[4:5], v168, s76, v[120:121]
	v_lshlrev_b64 v[122:123], 1, v[122:123]
	v_lshl_add_u64 v[168:169], v[168:169], 0, v[122:123]
	global_store_dwordx4 v[168:169], v[124:127], off
	v_mov_b32_e32 v194, v202
	v_mov_b32_e32 v195, v206
	v_pk_add_f32 v[124:125], v[178:179], v[180:181]
	v_pk_add_f32 v[126:127], v[182:183], v[184:185]
	v_mov_b32_e32 v179, v124
	v_mov_b32_e32 v178, v126
	v_mov_b32_e32 v124, v127
	v_pk_add_f32 v[124:125], v[178:179], v[124:125]
	ds_bpermute_b32 v127, v157, v125
	ds_bpermute_b32 v126, v157, v124
	v_mov_b32_e32 v206, v203
	v_mov_b32_e32 v196, v204
	v_mov_b32_e32 v197, v208
	v_mov_b32_e32 v208, v205
	v_mov_b32_e32 v202, v212
	v_mov_b32_e32 v203, v216
	v_mov_b32_e32 v216, v213
	v_mov_b32_e32 v204, v214
	v_mov_b32_e32 v205, v218
	v_mov_b32_e32 v218, v215
	v_pk_add_f32 v[186:187], v[194:195], v[206:207]
	v_pk_add_f32 v[188:189], v[196:197], v[208:209]
	v_pk_add_f32 v[190:191], v[202:203], v[216:217]
	v_pk_add_f32 v[192:193], v[204:205], v[218:219]
	v_pk_mul_f32 v[178:179], v[114:115], v[198:199] op_sel_hi:[1,0]
	s_waitcnt lgkmcnt(0)
	v_pk_add_f32 v[114:115], v[124:125], v[126:127]
	v_pk_add_f32 v[126:127], v[186:187], v[188:189]
	v_pk_add_f32 v[180:181], v[190:191], v[192:193]
	v_mov_b32_e32 v183, v126
	v_mov_b32_e32 v182, v180
	v_mov_b32_e32 v126, v181
	v_pk_add_f32 v[126:127], v[182:183], v[126:127]
	ds_bpermute_b32 v125, v155, v115
	ds_bpermute_b32 v124, v155, v114
	ds_bpermute_b32 v181, v157, v127
	ds_bpermute_b32 v180, v157, v126
	v_mul_f32_e32 v129, 0x4b800000, v128
	v_cmp_gt_f32_e32 vcc, s73, v128
	s_waitcnt lgkmcnt(2)
	v_pk_add_f32 v[114:115], v[114:115], v[124:125]
	v_mov_b32_e32 v194, v220
	s_waitcnt lgkmcnt(0)
	v_pk_add_f32 v[124:125], v[126:127], v[180:181]
	ds_bpermute_b32 v127, v155, v125
	ds_bpermute_b32 v126, v155, v124
	v_pk_fma_f32 v[114:115], v[114:115], s[24:25], v[130:131] op_sel_hi:[1,0,0]
	v_cndmask_b32_e32 v159, v128, v129, vcc
	v_mul_f32_e32 v128, 0x4b800000, v115
	v_cmp_gt_f32_e64 s[4:5], s73, v115
	v_cmp_gt_f32_e64 s[6:7], s73, v114
	v_mov_b32_e32 v195, v224
	v_cndmask_b32_e64 v161, v115, v128, s[4:5]
	v_mul_f32_e32 v115, 0x4b800000, v114
	v_mov_b32_e32 v224, v221
	v_mov_b32_e32 v196, v222
	v_mov_b32_e32 v197, v226
	v_mov_b32_e32 v226, v223
	v_cndmask_b32_e64 v163, v114, v115, s[6:7]
	s_waitcnt lgkmcnt(0)
	v_pk_add_f32 v[114:115], v[124:125], v[126:127]
	v_pk_add_f32 v[132:133], v[194:195], v[224:225]
	v_pk_add_f32 v[134:135], v[196:197], v[226:227]
	v_mov_b32_e32 v194, v228
	v_mov_b32_e32 v195, v232
	v_mov_b32_e32 v232, v229
	v_mov_b32_e32 v196, v230
	v_mov_b32_e32 v197, v234
	v_mov_b32_e32 v234, v231
	v_pk_fma_f32 v[114:115], v[114:115], s[24:25], v[130:131] op_sel_hi:[1,0,0]
	v_pk_add_f32 v[194:195], v[194:195], v[232:233]
	v_pk_add_f32 v[196:197], v[196:197], v[234:235]
	v_mul_f32_e32 v124, 0x4b800000, v115
	v_cmp_gt_f32_e64 s[8:9], s73, v115
	v_pk_add_f32 v[126:127], v[194:195], v[196:197]
	v_cmp_gt_f32_e64 s[10:11], s73, v114
	v_cndmask_b32_e64 v165, v115, v124, s[8:9]
	v_pk_add_f32 v[124:125], v[132:133], v[134:135]
	v_mov_b32_e32 v128, v126
	v_mov_b32_e32 v129, v124
	v_mov_b32_e32 v124, v127
	v_pk_add_f32 v[124:125], v[128:129], v[124:125]
	ds_bpermute_b32 v127, v157, v125
	ds_bpermute_b32 v126, v157, v124
	v_rsq_f32_e32 v128, v159
	v_mul_f32_e32 v115, 0x4b800000, v114
	v_cndmask_b32_e64 v129, v114, v115, s[10:11]
	v_pk_mul_f32 v[116:117], v[116:117], v[198:199] op_sel_hi:[1,0]
	s_waitcnt lgkmcnt(0)
	v_pk_add_f32 v[114:115], v[124:125], v[126:127]
	ds_bpermute_b32 v125, v155, v115
	ds_bpermute_b32 v124, v155, v114
	v_mul_f32_e32 v126, 0x45800000, v128
	v_rsq_f32_e32 v127, v161
	v_cndmask_b32_e32 v126, v128, v126, vcc
	v_rsq_f32_e32 v128, v163
	s_waitcnt lgkmcnt(0)
; DI unsigned pack2(float lo, float hi) { f32x2 v = {lo, hi}; bf16v2 r = __builtin_convertvector(v, bf16v2); return __builtin_bit_cast(unsigned, r); }
;   DI void operator()(const f32x4 (&acc)[2][2][4][2], const Unit& u, int wr, int wc, int fr, int fq) const {
;     const int row0 = u.pm * BM + wr * 64 + fr, col0 = u.pn * BM + wc * 32 + 8 * fq;
;     float rsv[2][4];
; #pragma unroll
;     for (int ai = 0; ai < 2; ++ai)
; #pragma unroll
;       for (int m = 0; m < 4; ++m) rsv[ai][m] = row_rstd(ssq, row0 + ai * HALF + m * 16, fq);
; #pragma unroll
;     for (int ai = 0; ai < 2; ++ai)
; #pragma unroll
;       for (int m = 0; m < 4; ++m) {
;         const int row = row0 + ai * HALF + m * 16;
;         const float rs = rsv[ai][m];
;         bf16_t* rowp = O + (size_t)row * ldc + col0;
; #pragma unroll
;         for (int bj = 0; bj < 2; ++bj) {
;           const f32x4 v0 = acc[ai][bj][m][0] * rs, v1 = acc[ai][bj][m][1] * rs;
;           u32x4 w; w.x = pack2(v0[0], v0[1]); w.y = pack2(v0[2], v0[3]); w.z = pack2(v1[0], v1[1]); w.w = pack2(v1[2], v1[3]);
;           *(u32x4*)(rowp + bj * HALF) = w;
;         }
	v_pk_add_f32 v[114:115], v[114:115], v[124:125]
	v_mul_f32_e32 v124, 0x45800000, v127
	v_cndmask_b32_e64 v124, v127, v124, s[4:5]
	v_mul_f32_e32 v127, 0x45800000, v128
	v_pk_fma_f32 v[114:115], v[114:115], s[24:25], v[130:131] op_sel_hi:[1,0,0]
	v_rsq_f32_e32 v125, v165
	v_cndmask_b32_e64 v128, v128, v127, s[6:7]
	v_rsq_f32_e32 v127, v129
	v_mul_f32_e32 v129, 0x4b800000, v115
	v_cmp_gt_f32_e32 vcc, s73, v115
	v_cmp_gt_f32_e64 s[4:5], s73, v114
	v_pk_mul_f32 v[118:119], v[118:119], v[198:199] op_sel_hi:[1,0]
	v_cndmask_b32_e32 v129, v115, v129, vcc
	v_mul_f32_e32 v115, 0x4b800000, v114
	v_cndmask_b32_e64 v131, v114, v115, s[4:5]
	v_cvt_pk_bf16_f32 v114, v116, v117
	v_rsq_f32_e32 v117, v129
	v_cvt_pk_bf16_f32 v115, v118, v119
	v_rsq_f32_e32 v119, v131
	v_mul_f32_e32 v116, 0x45800000, v125
	v_pk_mul_f32 v[112:113], v[112:113], v[198:199] op_sel_hi:[1,0]
	v_cndmask_b32_e64 v118, v125, v116, s[8:9]
	v_mul_f32_e32 v116, 0x45800000, v127
	v_cndmask_b32_e64 v130, v127, v116, s[10:11]
	v_cvt_pk_bf16_f32 v116, v112, v113
	v_mul_f32_e32 v112, 0x45800000, v117
	v_cndmask_b32_e32 v132, v117, v112, vcc
	v_mul_f32_e32 v112, 0x45800000, v119
	v_cvt_pk_bf16_f32 v117, v178, v179
	v_cndmask_b32_e64 v112, v119, v112, s[4:5]
	global_store_dwordx4 v[168:169], v[114:117], off offset:256
	v_pk_mul_f32 v[110:111], v[110:111], v[126:127] op_sel_hi:[1,0]
	v_pk_mul_f32 v[108:109], v[108:109], v[126:127] op_sel_hi:[1,0]
	v_mad_i64_i32 v[114:115], s[4:5], v154, s76, v[120:121]
	v_pk_mul_f32 v[116:117], v[106:107], v[126:127] op_sel_hi:[1,0]
	v_pk_mul_f32 v[106:107], v[104:105], v[126:127] op_sel_hi:[1,0]
	v_lshl_add_u64 v[114:115], v[114:115], 0, v[122:123]
	v_cvt_pk_bf16_f32 v104, v108, v109
	v_cvt_pk_bf16_f32 v105, v110, v111
	v_cvt_pk_bf16_f32 v106, v106, v107
	v_cvt_pk_bf16_f32 v107, v116, v117
	global_store_dwordx4 v[114:115], v[104:107], off
	v_pk_mul_f32 v[98:99], v[98:99], v[126:127] op_sel_hi:[1,0]
	v_pk_mul_f32 v[96:97], v[96:97], v[126:127] op_sel_hi:[1,0]
	v_pk_mul_f32 v[104:105], v[90:91], v[126:127] op_sel_hi:[1,0]
	v_pk_mul_f32 v[90:91], v[88:89], v[126:127] op_sel_hi:[1,0]
	v_cvt_pk_bf16_f32 v88, v96, v97
	v_cvt_pk_bf16_f32 v89, v98, v99
	v_cvt_pk_bf16_f32 v90, v90, v91
	v_cvt_pk_bf16_f32 v91, v104, v105
	global_store_dwordx4 v[114:115], v[88:91], off offset:256
	v_pk_mul_f32 v[94:95], v[94:95], v[124:125] op_sel_hi:[1,0]
	v_pk_mul_f32 v[92:93], v[92:93], v[124:125] op_sel_hi:[1,0]
	v_mad_i64_i32 v[88:89], s[4:5], v160, s76, v[120:121]
	v_lshl_add_u64 v[96:97], v[88:89], 0, v[122:123]
	v_pk_mul_f32 v[90:91], v[102:103], v[124:125] op_sel_hi:[1,0]
	v_pk_mul_f32 v[88:89], v[100:101], v[124:125] op_sel_hi:[1,0]
	v_pk_mul_f32 v[82:83], v[82:83], v[124:125] op_sel_hi:[1,0]
	v_cvt_pk_bf16_f32 v88, v88, v89
	v_cvt_pk_bf16_f32 v89, v90, v91
	v_cvt_pk_bf16_f32 v90, v92, v93
	v_cvt_pk_bf16_f32 v91, v94, v95
	global_store_dwordx4 v[96:97], v[88:91], off
	v_pk_mul_f32 v[80:81], v[80:81], v[124:125] op_sel_hi:[1,0]
	v_pk_mul_f32 v[78:79], v[78:79], v[128:129] op_sel_hi:[1,0]
	v_pk_mul_f32 v[88:89], v[74:75], v[124:125] op_sel_hi:[1,0]
	v_pk_mul_f32 v[74:75], v[72:73], v[124:125] op_sel_hi:[1,0]
	v_cvt_pk_bf16_f32 v72, v80, v81
	v_cvt_pk_bf16_f32 v73, v82, v83
	v_cvt_pk_bf16_f32 v74, v74, v75
	v_cvt_pk_bf16_f32 v75, v88, v89
	global_store_dwordx4 v[96:97], v[72:75], off offset:256
	v_pk_mul_f32 v[76:77], v[76:77], v[128:129] op_sel_hi:[1,0]
	v_pk_mul_f32 v[70:71], v[70:71], v[128:129] op_sel_hi:[1,0]
	v_mad_i64_i32 v[72:73], s[4:5], v156, s76, v[120:121]
	v_lshl_add_u64 v[80:81], v[72:73], 0, v[122:123]
	v_pk_mul_f32 v[74:75], v[86:87], v[128:129] op_sel_hi:[1,0]
	v_pk_mul_f32 v[72:73], v[84:85], v[128:129] op_sel_hi:[1,0]
	v_pk_mul_f32 v[68:69], v[68:69], v[128:129] op_sel_hi:[1,0]
	v_cvt_pk_bf16_f32 v72, v72, v73
	v_cvt_pk_bf16_f32 v73, v74, v75
	v_cvt_pk_bf16_f32 v74, v76, v77
	v_cvt_pk_bf16_f32 v75, v78, v79
	global_store_dwordx4 v[80:81], v[72:75], off
	v_pk_mul_f32 v[62:63], v[62:63], v[118:119] op_sel_hi:[1,0]
	v_pk_mul_f32 v[60:61], v[60:61], v[118:119] op_sel_hi:[1,0]
	v_pk_mul_f32 v[72:73], v[66:67], v[128:129] op_sel_hi:[1,0]
	v_pk_mul_f32 v[66:67], v[64:65], v[128:129] op_sel_hi:[1,0]
; DI unsigned pack2(float lo, float hi) { f32x2 v = {lo, hi}; bf16v2 r = __builtin_convertvector(v, bf16v2); return __builtin_bit_cast(unsigned, r); }
; #define PG8_WAIT_V(n) asm volatile("s_waitcnt vmcnt(" #n ")" ::: "memory")
; #define PG8_BAR __builtin_amdgcn_s_barrier()
;   DI void operator()(const f32x4 (&acc)[2][2][4][2], const Unit& u, int wr, int wc, int fr, int fq) const {
;     ...
;     for (int ai = 0; ai < 2; ++ai)
; #pragma unroll
;       for (int m = 0; m < 4; ++m) {
;         const int row = row0 + ai * HALF + m * 16;
;         const float rs = rsv[ai][m];
;         bf16_t* rowp = O + (size_t)row * ldc + col0;
; #pragma unroll
;         for (int bj = 0; bj < 2; ++bj) {
;           const f32x4 v0 = acc[ai][bj][m][0] * rs, v1 = acc[ai][bj][m][1] * rs;
;           u32x4 w; w.x = pack2(v0[0], v0[1]); w.y = pack2(v0[2], v0[3]); w.z = pack2(v1[0], v1[1]); w.w = pack2(v1[2], v1[3]);
;           *(u32x4*)(rowp + bj * HALF) = w;
;         }
; template <class Epi, class Sched = StaticOrder>
; DI void gemm_phase(LAS unsigned char* lds, const Gemm g, const Sched& S, const Epi& E) {
;     ...
;     E(acc, cur, wr, wc, fr, fq);
;     if (!has_next) break;
; #pragma unroll
;     for (int a = 0; a < 2; ++a)
; #pragma unroll
;       for (int b = 0; b < 2; ++b)
; #pragma unroll
;         for (int m = 0; m < 4; ++m)
; #pragma unroll
;           for (int n = 0; n < 2; ++n) acc[a][b][m][n] = (f32x4){0.f, 0.f, 0.f, 0.f};
;     cur = nxt; cA = nA; cB = nB; ++ui;
;   }
;   PG8_WAIT_V(0);
;   if (wr == 0) PG8_BAR;
;   PG8_BAR;
	v_cvt_pk_bf16_f32 v64, v68, v69
	v_cvt_pk_bf16_f32 v65, v70, v71
	v_cvt_pk_bf16_f32 v66, v66, v67
	v_cvt_pk_bf16_f32 v67, v72, v73
	global_store_dwordx4 v[80:81], v[64:67], off offset:256
	v_pk_mul_f32 v[50:51], v[50:51], v[118:119] op_sel_hi:[1,0]
	v_pk_mul_f32 v[48:49], v[48:49], v[118:119] op_sel_hi:[1,0]
	v_mad_i64_i32 v[64:65], s[4:5], v164, s76, v[120:121]
	v_pk_mul_f32 v[66:67], v[58:59], v[118:119] op_sel_hi:[1,0]
	v_pk_mul_f32 v[58:59], v[56:57], v[118:119] op_sel_hi:[1,0]
	v_lshl_add_u64 v[64:65], v[64:65], 0, v[122:123]
	v_cvt_pk_bf16_f32 v56, v60, v61
	v_cvt_pk_bf16_f32 v57, v62, v63
	v_cvt_pk_bf16_f32 v58, v58, v59
	v_cvt_pk_bf16_f32 v59, v66, v67
	global_store_dwordx4 v[64:65], v[56:59], off
	v_pk_mul_f32 v[46:47], v[46:47], v[130:131] op_sel_hi:[1,0]
	v_pk_mul_f32 v[44:45], v[44:45], v[130:131] op_sel_hi:[1,0]
	v_pk_mul_f32 v[56:57], v[42:43], v[118:119] op_sel_hi:[1,0]
	v_pk_mul_f32 v[42:43], v[40:41], v[118:119] op_sel_hi:[1,0]
	v_cvt_pk_bf16_f32 v40, v48, v49
	v_cvt_pk_bf16_f32 v41, v50, v51
	v_cvt_pk_bf16_f32 v42, v42, v43
	v_cvt_pk_bf16_f32 v43, v56, v57
	global_store_dwordx4 v[64:65], v[40:43], off offset:256
	v_pk_mul_f32 v[34:35], v[34:35], v[130:131] op_sel_hi:[1,0]
	v_pk_mul_f32 v[32:33], v[32:33], v[130:131] op_sel_hi:[1,0]
	v_mad_i64_i32 v[40:41], s[4:5], v158, s76, v[120:121]
	v_lshl_add_u64 v[48:49], v[40:41], 0, v[122:123]
	v_pk_mul_f32 v[42:43], v[54:55], v[130:131] op_sel_hi:[1,0]
	v_pk_mul_f32 v[40:41], v[52:53], v[130:131] op_sel_hi:[1,0]
	v_pk_mul_f32 v[30:31], v[30:31], v[132:133] op_sel_hi:[1,0]
	v_cvt_pk_bf16_f32 v40, v40, v41
	v_cvt_pk_bf16_f32 v41, v42, v43
	v_cvt_pk_bf16_f32 v42, v44, v45
	v_cvt_pk_bf16_f32 v43, v46, v47
	global_store_dwordx4 v[48:49], v[40:43], off
	v_pk_mul_f32 v[28:29], v[28:29], v[132:133] op_sel_hi:[1,0]
	v_pk_mul_f32 v[18:19], v[18:19], v[132:133] op_sel_hi:[1,0]
	v_pk_mul_f32 v[40:41], v[26:27], v[130:131] op_sel_hi:[1,0]
	v_pk_mul_f32 v[26:27], v[24:25], v[130:131] op_sel_hi:[1,0]
	v_cvt_pk_bf16_f32 v24, v32, v33
	v_cvt_pk_bf16_f32 v25, v34, v35
	v_cvt_pk_bf16_f32 v26, v26, v27
	v_cvt_pk_bf16_f32 v27, v40, v41
	global_store_dwordx4 v[48:49], v[24:27], off offset:256
	v_pk_mul_f32 v[16:17], v[16:17], v[132:133] op_sel_hi:[1,0]
	v_pk_mul_f32 v[14:15], v[14:15], v[112:113] op_sel_hi:[1,0]
	v_mad_i64_i32 v[24:25], s[4:5], v166, s76, v[120:121]
	v_lshl_add_u64 v[32:33], v[24:25], 0, v[122:123]
	v_pk_mul_f32 v[26:27], v[38:39], v[132:133] op_sel_hi:[1,0]
	v_pk_mul_f32 v[24:25], v[36:37], v[132:133] op_sel_hi:[1,0]
	v_pk_mul_f32 v[12:13], v[12:13], v[112:113] op_sel_hi:[1,0]
	v_cvt_pk_bf16_f32 v24, v24, v25
	v_cvt_pk_bf16_f32 v25, v26, v27
	v_cvt_pk_bf16_f32 v26, v28, v29
	v_cvt_pk_bf16_f32 v27, v30, v31
	global_store_dwordx4 v[32:33], v[24:27], off
	v_pk_mul_f32 v[6:7], v[6:7], v[112:113] op_sel_hi:[1,0]
	v_pk_mul_f32 v[4:5], v[4:5], v[112:113] op_sel_hi:[1,0]
	v_pk_mul_f32 v[24:25], v[10:11], v[132:133] op_sel_hi:[1,0]
	v_pk_mul_f32 v[10:11], v[8:9], v[132:133] op_sel_hi:[1,0]
	v_cvt_pk_bf16_f32 v8, v16, v17
	v_cvt_pk_bf16_f32 v9, v18, v19
	v_cvt_pk_bf16_f32 v10, v10, v11
	v_cvt_pk_bf16_f32 v11, v24, v25
	global_store_dwordx4 v[32:33], v[8:11], off offset:256
	s_and_b64 vcc, exec, s[0:1]
	s_mov_b64 s[8:9], s[36:37]
	v_mad_i64_i32 v[8:9], s[4:5], v162, s76, v[120:121]
	v_lshl_add_u64 v[16:17], v[8:9], 0, v[122:123]
	v_pk_mul_f32 v[10:11], v[22:23], v[112:113] op_sel_hi:[1,0]
	v_pk_mul_f32 v[8:9], v[20:21], v[112:113] op_sel_hi:[1,0]
	s_mov_b32 s5, s28
	v_cvt_pk_bf16_f32 v8, v8, v9
	v_cvt_pk_bf16_f32 v9, v10, v11
	v_cvt_pk_bf16_f32 v10, v12, v13
	v_cvt_pk_bf16_f32 v11, v14, v15
	global_store_dwordx4 v[16:17], v[8:11], off
	s_mov_b32 s4, s30
	s_mov_b64 s[6:7], s[34:35]
	v_pk_mul_f32 v[8:9], v[2:3], v[112:113] op_sel_hi:[1,0]
	v_pk_mul_f32 v[2:3], v[0:1], v[112:113] op_sel_hi:[1,0]
	v_cvt_pk_bf16_f32 v0, v4, v5
	v_cvt_pk_bf16_f32 v1, v6, v7
	v_cvt_pk_bf16_f32 v2, v2, v3
	v_cvt_pk_bf16_f32 v3, v8, v9
	global_store_dwordx4 v[16:17], v[0:3], off offset:256
	s_cbranch_vccz .LBB0_343
	s_waitcnt vmcnt(0)
	s_cmpk_gt_u32 s27, 0xff
	s_cbranch_scc1 .LBB0_350
	s_barrier

; #define PG8_STAGE(bufoff, gbase, voff) do { _Pragma("unroll") for (int _i = 0; _i < 2; ++_i) \
;     __builtin_amdgcn_global_load_lds((const unsigned*)((const char*)(gbase) + (voff)[_i]), (LAS unsigned*)(lds + (bufoff) + ldsw + _i * 8192), 16, 0, 0); } while (0)
; #define PG8_LDA(dst, b, h) do { _Pragma("unroll") for (int m = 0; m < 4; ++m) _Pragma("unroll") for (int k = 0; k < 2; ++k) dst[m][k] = *(const LAS bf16x8*)(lds + PG8_SA(b, h) + aoff + m * 2048 + k * 1024); } while (0)
; #define PG8_LDB(dst, b, h) do { _Pragma("unroll") for (int n = 0; n < 2; ++n) _Pragma("unroll") for (int k = 0; k < 2; ++k) dst[n][k] = *(const LAS bf16x8*)(lds + PG8_SB(b, h) + boff + n * 2048 + k * 1024); } while (0)
; #define PG8_MMA(ai, bj, At, Bt) do { __builtin_amdgcn_s_setprio(1); _Pragma("unroll") for (int m = 0; m < 4; ++m) _Pragma("unroll") for (int n = 0; n < 2; ++n) _Pragma("unroll") for (int k = 0; k < 2; ++k) \
;     acc[ai][bj][m][n] = __builtin_amdgcn_mfma_f32_16x16x32_bf16(Bt[n][k], At[m][k], acc[ai][bj][m][n], 0, 0, 0); __builtin_amdgcn_s_setprio(0); } while (0)
; #define PG8_WAIT_V(n) asm volatile("s_waitcnt vmcnt(" #n ")" ::: "memory")
; #define PG8_WAIT_L(n) asm volatile("s_waitcnt lgkmcnt(" #n ")" ::: "memory")
; #define PG8_BAR __builtin_amdgcn_s_barrier()
; #define PG8_SCHED __builtin_amdgcn_sched_barrier(0)
; template <class Epi, class Sched = StaticOrder>
; DI void gemm_phase(LAS unsigned char* lds, const Gemm g, const Sched& S, const Epi& E) {
;     ...
;     for (int t = 0; t < nt; t += 2) {
;       const bool last = (t == nt - 2);
;       const char* a1 = cA + (size_t)(t + 1) * kstep;
;       const char* a2 = last ? nA : cA + (size_t)(t + 2) * kstep; const char* b2 = last ? nB : cB + (size_t)(t + 2) * kstep;
;       const char* a3 = a2 + kstep; const char* b3 = b2 + kstep;
;       PG8_LDB(B0, 0, 0); PG8_SCHED; PG8_LDA(At, 0, 0); PG8_STAGE(PG8_SA(1, 1), a1 + hstep, voffA);
;       PG8_WAIT_L(8); PG8_BAR; PG8_WAIT_L(0); PG8_MMA(0, 0, At, B0); PG8_BAR; PG8_SCHED;
;       PG8_LDB(B1, 0, 1); PG8_STAGE(PG8_SB(0, 0), b2, voffB);
;       PG8_BAR; PG8_WAIT_L(0); PG8_MMA(0, 1, At, B1); PG8_BAR;
;       PG8_LDA(At, 0, 1); PG8_STAGE(PG8_SA(0, 0), a2, voffA);
;       PG8_BAR; PG8_WAIT_L(0); PG8_MMA(1, 0, At, B0); PG8_BAR; PG8_SCHED;
;       PG8_STAGE(PG8_SB(0, 1), b2 + hstep, voffB);
;       PG8_WAIT_V(6); PG8_BAR; PG8_MMA(1, 1, At, B1); PG8_BAR;
.LBB0_728:
	s_add_u32 s24, s22, 0xfff80080
	s_addc_u32 s25, s23, -1
	s_cmp_eq_u32 s53, 28
	s_cselect_b32 s27, s17, s25
	s_cselect_b32 s26, s43, s24
	s_cselect_b32 s25, s15, s52
	s_cselect_b32 s24, s44, s45
	s_add_i32 m0, s37, 0xc000
	ds_read_b128 v[144:147], v208
	ds_read_b128 v[148:151], v208 offset:1024
	ds_read_b128 v[152:155], v208 offset:2048
	ds_read_b128 v[156:159], v208 offset:3072
	ds_read_b128 v[160:163], v208 offset:4096
	ds_read_b128 v[164:167], v208 offset:5120
	ds_read_b128 v[168:171], v208 offset:6144
	ds_read_b128 v[172:175], v208 offset:7168
	global_load_lds_dwordx4 v184, s[22:23]
	s_add_i32 m0, s37, 0xe000
	s_nop 0
	global_load_lds_dwordx4 v186, s[22:23]
	s_waitcnt lgkmcnt(0)
	s_setprio 1
	s_barrier
	v_mfma_f32_16x16x32_bf16 v[124:127], v[128:131], v[144:147], v[124:127]
	v_mfma_f32_16x16x32_bf16 v[120:123], v[136:139], v[144:147], v[120:123]
	v_mfma_f32_16x16x32_bf16 v[108:111], v[128:131], v[152:155], v[108:111]
	v_mfma_f32_16x16x32_bf16 v[104:107], v[136:139], v[152:155], v[104:107]
	v_mfma_f32_16x16x32_bf16 v[92:95], v[128:131], v[160:163], v[92:95]
	v_mfma_f32_16x16x32_bf16 v[88:91], v[136:139], v[160:163], v[88:91]
	v_mfma_f32_16x16x32_bf16 v[76:79], v[128:131], v[168:171], v[76:79]
	v_mfma_f32_16x16x32_bf16 v[72:75], v[136:139], v[168:171], v[72:75]
	v_mfma_f32_16x16x32_bf16 v[124:127], v[132:135], v[148:151], v[124:127]
	v_mfma_f32_16x16x32_bf16 v[120:123], v[140:143], v[148:151], v[120:123]
	v_mfma_f32_16x16x32_bf16 v[108:111], v[132:135], v[156:159], v[108:111]
	v_mfma_f32_16x16x32_bf16 v[104:107], v[140:143], v[156:159], v[104:107]
	v_mfma_f32_16x16x32_bf16 v[92:95], v[132:135], v[164:167], v[92:95]
	v_mfma_f32_16x16x32_bf16 v[88:91], v[140:143], v[164:167], v[88:91]
	v_mfma_f32_16x16x32_bf16 v[76:79], v[132:135], v[172:175], v[76:79]
	v_mfma_f32_16x16x32_bf16 v[72:75], v[140:143], v[172:175], v[72:75]
	s_barrier
	s_setprio 0
	s_add_i32 s54, s50, s35
	s_add_u32 s98, s24, 0x80
	s_addc_u32 s99, s25, 0
	s_mov_b32 m0, s54
	ds_read_b128 v[192:195], v209
	ds_read_b128 v[196:199], v209 offset:1024
	ds_read_b128 v[200:203], v209 offset:2048
	ds_read_b128 v[212:215], v209 offset:3072
	global_load_lds_dwordx4 v180, s[24:25]
	s_add_i32 m0, s54, 0x2000
	s_nop 0
	global_load_lds_dwordx4 v176, s[24:25]
	s_waitcnt lgkmcnt(0)
	s_setprio 1
	s_barrier
	v_mfma_f32_16x16x32_bf16 v[116:119], v[192:195], v[144:147], v[116:119]
	v_mfma_f32_16x16x32_bf16 v[112:115], v[200:203], v[144:147], v[112:115]
	v_mfma_f32_16x16x32_bf16 v[100:103], v[192:195], v[152:155], v[100:103]
	v_mfma_f32_16x16x32_bf16 v[96:99], v[200:203], v[152:155], v[96:99]
	v_mfma_f32_16x16x32_bf16 v[84:87], v[192:195], v[160:163], v[84:87]
	v_mfma_f32_16x16x32_bf16 v[80:83], v[200:203], v[160:163], v[80:83]
	v_mfma_f32_16x16x32_bf16 v[68:71], v[192:195], v[168:171], v[68:71]
	v_mfma_f32_16x16x32_bf16 v[64:67], v[200:203], v[168:171], v[64:67]
	v_mfma_f32_16x16x32_bf16 v[116:119], v[196:199], v[148:151], v[116:119]
	v_mfma_f32_16x16x32_bf16 v[112:115], v[212:215], v[148:151], v[112:115]
	v_mfma_f32_16x16x32_bf16 v[100:103], v[196:199], v[156:159], v[100:103]
	v_mfma_f32_16x16x32_bf16 v[96:99], v[212:215], v[156:159], v[96:99]
	v_mfma_f32_16x16x32_bf16 v[84:87], v[196:199], v[164:167], v[84:87]
	v_mfma_f32_16x16x32_bf16 v[80:83], v[212:215], v[164:167], v[80:83]
	v_mfma_f32_16x16x32_bf16 v[68:71], v[196:199], v[172:175], v[68:71]
	v_mfma_f32_16x16x32_bf16 v[64:67], v[212:215], v[172:175], v[64:67]
	s_barrier
	s_setprio 0
	s_mov_b32 m0, s37
	s_add_u32 s100, s26, 0x80
	s_addc_u32 s101, s27, 0
	ds_read_b128 v[144:147], v208 offset:16384
	ds_read_b128 v[148:151], v208 offset:17408
	ds_read_b128 v[152:155], v208 offset:18432
	ds_read_b128 v[156:159], v208 offset:19456
	ds_read_b128 v[160:163], v208 offset:20480
	ds_read_b128 v[164:167], v208 offset:21504
	ds_read_b128 v[168:171], v208 offset:22528
	ds_read_b128 v[172:175], v208 offset:23552
	global_load_lds_dwordx4 v182, s[26:27]
	s_mov_b32 m0, s38
	s_nop 0
	global_load_lds_dwordx4 v178, s[26:27]
	s_waitcnt vmcnt(10)
	s_waitcnt lgkmcnt(0)
	s_setprio 1
	s_barrier
	v_mfma_f32_16x16x32_bf16 v[60:63], v[128:131], v[144:147], v[60:63]
	v_mfma_f32_16x16x32_bf16 v[56:59], v[136:139], v[144:147], v[56:59]
	v_mfma_f32_16x16x32_bf16 v[44:47], v[128:131], v[152:155], v[44:47]
	v_mfma_f32_16x16x32_bf16 v[40:43], v[136:139], v[152:155], v[40:43]
	v_mfma_f32_16x16x32_bf16 v[28:31], v[128:131], v[160:163], v[28:31]
	v_mfma_f32_16x16x32_bf16 v[24:27], v[136:139], v[160:163], v[24:27]
	v_mfma_f32_16x16x32_bf16 v[12:15], v[128:131], v[168:171], v[12:15]
	v_mfma_f32_16x16x32_bf16 v[8:11], v[136:139], v[168:171], v[8:11]
	v_mfma_f32_16x16x32_bf16 v[60:63], v[132:135], v[148:151], v[60:63]
	v_mfma_f32_16x16x32_bf16 v[56:59], v[140:143], v[148:151], v[56:59]
	v_mfma_f32_16x16x32_bf16 v[44:47], v[132:135], v[156:159], v[44:47]
	v_mfma_f32_16x16x32_bf16 v[40:43], v[140:143], v[156:159], v[40:43]
	v_mfma_f32_16x16x32_bf16 v[28:31], v[132:135], v[164:167], v[28:31]
	v_mfma_f32_16x16x32_bf16 v[24:27], v[140:143], v[164:167], v[24:27]
	v_mfma_f32_16x16x32_bf16 v[12:15], v[132:135], v[172:175], v[12:15]
	v_mfma_f32_16x16x32_bf16 v[8:11], v[140:143], v[172:175], v[8:11]
	s_barrier
	s_setprio 0
	s_add_u32 s54, s24, 0x80000
	s_addc_u32 s55, s25, 0
	s_add_i32 s57, s51, s35
	s_mov_b32 m0, s57
	s_nop 0
	global_load_lds_dwordx4 v180, s[54:55]
	s_add_i32 m0, s57, 0x2000
	s_nop 0
	global_load_lds_dwordx4 v176, s[54:55]
	s_add_i32 s54, 0, 0x18000
	v_add_u32_e32 v140, s54, v205
	ds_read_b128 v[128:131], v140
	ds_read_b128 v[132:135], v140 offset:1024
	ds_read_b128 v[136:139], v140 offset:2048
	ds_read_b128 v[140:143], v140 offset:3072
	s_waitcnt vmcnt(6)
	s_setprio 1
	s_barrier
; #define PG8_STAGE(bufoff, gbase, voff) do { _Pragma("unroll") for (int _i = 0; _i < 2; ++_i) \
;     __builtin_amdgcn_global_load_lds((const unsigned*)((const char*)(gbase) + (voff)[_i]), (LAS unsigned*)(lds + (bufoff) + ldsw + _i * 8192), 16, 0, 0); } while (0)
; #define PG8_LDA(dst, b, h) do { _Pragma("unroll") for (int m = 0; m < 4; ++m) _Pragma("unroll") for (int k = 0; k < 2; ++k) dst[m][k] = *(const LAS bf16x8*)(lds + PG8_SA(b, h) + aoff + m * 2048 + k * 1024); } while (0)
; #define PG8_LDB(dst, b, h) do { _Pragma("unroll") for (int n = 0; n < 2; ++n) _Pragma("unroll") for (int k = 0; k < 2; ++k) dst[n][k] = *(const LAS bf16x8*)(lds + PG8_SB(b, h) + boff + n * 2048 + k * 1024); } while (0)
; #define PG8_MMA(ai, bj, At, Bt) do { __builtin_amdgcn_s_setprio(1); _Pragma("unroll") for (int m = 0; m < 4; ++m) _Pragma("unroll") for (int n = 0; n < 2; ++n) _Pragma("unroll") for (int k = 0; k < 2; ++k) \
;     acc[ai][bj][m][n] = __builtin_amdgcn_mfma_f32_16x16x32_bf16(Bt[n][k], At[m][k], acc[ai][bj][m][n], 0, 0, 0); __builtin_amdgcn_s_setprio(0); } while (0)
; #define PG8_WAIT_V(n) asm volatile("s_waitcnt vmcnt(" #n ")" ::: "memory")
; #define PG8_WAIT_L(n) asm volatile("s_waitcnt lgkmcnt(" #n ")" ::: "memory")
; #define PG8_BAR __builtin_amdgcn_s_barrier()
; #define PG8_SCHED __builtin_amdgcn_sched_barrier(0)
; template <class Epi, class Sched = StaticOrder>
; DI void gemm_phase(LAS unsigned char* lds, const Gemm g, const Sched& S, const Epi& E) {
;     ...
;       PG8_WAIT_V(6); PG8_BAR; PG8_MMA(1, 1, At, B1); PG8_BAR;
;       PG8_LDB(B0, 1, 0); PG8_SCHED; PG8_LDA(At, 1, 0); PG8_STAGE(PG8_SA(0, 1), a2 + hstep, voffA);
;       PG8_WAIT_L(8); PG8_BAR; PG8_WAIT_L(0); PG8_MMA(0, 0, At, B0); PG8_BAR; PG8_SCHED;
;       PG8_LDB(B1, 1, 1); PG8_STAGE(PG8_SB(1, 0), b3, voffB);
;       PG8_BAR; PG8_WAIT_L(0); PG8_MMA(0, 1, At, B1); PG8_BAR;
;       PG8_LDA(At, 1, 1); PG8_STAGE(PG8_SA(1, 0), a3, voffA);
;       PG8_BAR; PG8_WAIT_L(0); PG8_MMA(1, 0, At, B0); PG8_BAR; PG8_SCHED;
	v_mfma_f32_16x16x32_bf16 v[52:55], v[192:195], v[144:147], v[52:55]
	v_mfma_f32_16x16x32_bf16 v[48:51], v[200:203], v[144:147], v[48:51]
	v_mfma_f32_16x16x32_bf16 v[36:39], v[192:195], v[152:155], v[36:39]
	v_mfma_f32_16x16x32_bf16 v[32:35], v[200:203], v[152:155], v[32:35]
	v_mfma_f32_16x16x32_bf16 v[20:23], v[192:195], v[160:163], v[20:23]
	v_mfma_f32_16x16x32_bf16 v[16:19], v[200:203], v[160:163], v[16:19]
	v_mfma_f32_16x16x32_bf16 v[4:7], v[192:195], v[168:171], v[4:7]
	v_mfma_f32_16x16x32_bf16 v[0:3], v[200:203], v[168:171], v[0:3]
	v_mfma_f32_16x16x32_bf16 v[52:55], v[196:199], v[148:151], v[52:55]
	v_mfma_f32_16x16x32_bf16 v[48:51], v[212:215], v[148:151], v[48:51]
	v_mfma_f32_16x16x32_bf16 v[36:39], v[196:199], v[156:159], v[36:39]
	v_mfma_f32_16x16x32_bf16 v[32:35], v[212:215], v[156:159], v[32:35]
	v_mfma_f32_16x16x32_bf16 v[20:23], v[196:199], v[164:167], v[20:23]
	v_mfma_f32_16x16x32_bf16 v[16:19], v[212:215], v[164:167], v[16:19]
	v_mfma_f32_16x16x32_bf16 v[4:7], v[196:199], v[172:175], v[4:7]
	v_mfma_f32_16x16x32_bf16 v[0:3], v[212:215], v[172:175], v[0:3]
	s_barrier
	s_setprio 0
	s_add_u32 s26, s26, 0x80000
	s_addc_u32 s27, s27, 0
	s_mov_b32 m0, s39
	ds_read_b128 v[144:147], v208 offset:32768
	ds_read_b128 v[148:151], v208 offset:33792
	ds_read_b128 v[152:155], v208 offset:34816
	ds_read_b128 v[156:159], v208 offset:35840
	ds_read_b128 v[160:163], v208 offset:36864
	ds_read_b128 v[164:167], v208 offset:37888
	ds_read_b128 v[168:171], v208 offset:38912
	ds_read_b128 v[172:175], v208 offset:39936
	global_load_lds_dwordx4 v182, s[26:27]
	s_mov_b32 m0, s40
	s_nop 0
	global_load_lds_dwordx4 v178, s[26:27]
	s_waitcnt lgkmcnt(0)
	s_setprio 1
	s_barrier
	v_mfma_f32_16x16x32_bf16 v[124:127], v[128:131], v[144:147], v[124:127]
	v_mfma_f32_16x16x32_bf16 v[120:123], v[136:139], v[144:147], v[120:123]
	v_mfma_f32_16x16x32_bf16 v[108:111], v[128:131], v[152:155], v[108:111]
	v_mfma_f32_16x16x32_bf16 v[104:107], v[136:139], v[152:155], v[104:107]
	v_mfma_f32_16x16x32_bf16 v[92:95], v[128:131], v[160:163], v[92:95]
	v_mfma_f32_16x16x32_bf16 v[88:91], v[136:139], v[160:163], v[88:91]
	v_mfma_f32_16x16x32_bf16 v[76:79], v[128:131], v[168:171], v[76:79]
	v_mfma_f32_16x16x32_bf16 v[72:75], v[136:139], v[168:171], v[72:75]
	v_mfma_f32_16x16x32_bf16 v[124:127], v[132:135], v[148:151], v[124:127]
	v_mfma_f32_16x16x32_bf16 v[120:123], v[140:143], v[148:151], v[120:123]
	v_mfma_f32_16x16x32_bf16 v[108:111], v[132:135], v[156:159], v[108:111]
	v_mfma_f32_16x16x32_bf16 v[104:107], v[140:143], v[156:159], v[104:107]
	v_mfma_f32_16x16x32_bf16 v[92:95], v[132:135], v[164:167], v[92:95]
	v_mfma_f32_16x16x32_bf16 v[88:91], v[140:143], v[164:167], v[88:91]
	v_mfma_f32_16x16x32_bf16 v[76:79], v[132:135], v[172:175], v[76:79]
	v_mfma_f32_16x16x32_bf16 v[72:75], v[140:143], v[172:175], v[72:75]
	s_barrier
	s_setprio 0
	s_add_i32 s26, 0, 0x1c000
	s_add_i32 s27, s54, s35
	v_add_u32_e32 v212, s26, v205
	s_mov_b32 m0, s27
	ds_read_b128 v[192:195], v212
	ds_read_b128 v[196:199], v212 offset:1024
	ds_read_b128 v[200:203], v212 offset:2048
	ds_read_b128 v[212:215], v212 offset:3072
	global_load_lds_dwordx4 v180, s[98:99]
	s_add_i32 m0, s27, 0x2000
	s_nop 0
	global_load_lds_dwordx4 v176, s[98:99]
	s_waitcnt lgkmcnt(0)
	s_setprio 1
	s_barrier
	v_mfma_f32_16x16x32_bf16 v[116:119], v[192:195], v[144:147], v[116:119]
	v_mfma_f32_16x16x32_bf16 v[112:115], v[200:203], v[144:147], v[112:115]
	v_mfma_f32_16x16x32_bf16 v[100:103], v[192:195], v[152:155], v[100:103]
	v_mfma_f32_16x16x32_bf16 v[96:99], v[200:203], v[152:155], v[96:99]
	v_mfma_f32_16x16x32_bf16 v[84:87], v[192:195], v[160:163], v[84:87]
	v_mfma_f32_16x16x32_bf16 v[80:83], v[200:203], v[160:163], v[80:83]
	v_mfma_f32_16x16x32_bf16 v[68:71], v[192:195], v[168:171], v[68:71]
	v_mfma_f32_16x16x32_bf16 v[64:67], v[200:203], v[168:171], v[64:67]
	v_mfma_f32_16x16x32_bf16 v[116:119], v[196:199], v[148:151], v[116:119]
	v_mfma_f32_16x16x32_bf16 v[112:115], v[212:215], v[148:151], v[112:115]
	v_mfma_f32_16x16x32_bf16 v[100:103], v[196:199], v[156:159], v[100:103]
	v_mfma_f32_16x16x32_bf16 v[96:99], v[212:215], v[156:159], v[96:99]
	v_mfma_f32_16x16x32_bf16 v[84:87], v[196:199], v[164:167], v[84:87]
	v_mfma_f32_16x16x32_bf16 v[80:83], v[212:215], v[164:167], v[80:83]
	v_mfma_f32_16x16x32_bf16 v[68:71], v[196:199], v[172:175], v[68:71]
	v_mfma_f32_16x16x32_bf16 v[64:67], v[212:215], v[172:175], v[64:67]
	s_barrier
	s_setprio 0
	s_mov_b32 m0, s46
	ds_read_b128 v[144:147], v208 offset:49152
	ds_read_b128 v[148:151], v208 offset:50176
	ds_read_b128 v[152:155], v208 offset:51200
	ds_read_b128 v[156:159], v208 offset:52224
	ds_read_b128 v[160:163], v208 offset:53248
	ds_read_b128 v[164:167], v208 offset:54272
	ds_read_b128 v[168:171], v208 offset:55296
	ds_read_b128 v[172:175], v208 offset:56320
	global_load_lds_dwordx4 v182, s[100:101]
	s_mov_b32 m0, s47
	s_nop 0
	global_load_lds_dwordx4 v178, s[100:101]
	s_waitcnt vmcnt(10)
	s_waitcnt lgkmcnt(0)
	s_setprio 1
	s_barrier
	v_mfma_f32_16x16x32_bf16 v[60:63], v[128:131], v[144:147], v[60:63]
	v_mfma_f32_16x16x32_bf16 v[56:59], v[136:139], v[144:147], v[56:59]
	v_mfma_f32_16x16x32_bf16 v[44:47], v[128:131], v[152:155], v[44:47]
	v_mfma_f32_16x16x32_bf16 v[40:43], v[136:139], v[152:155], v[40:43]
	v_mfma_f32_16x16x32_bf16 v[28:31], v[128:131], v[160:163], v[28:31]
	v_mfma_f32_16x16x32_bf16 v[24:27], v[136:139], v[160:163], v[24:27]
	v_mfma_f32_16x16x32_bf16 v[12:15], v[128:131], v[168:171], v[12:15]
	v_mfma_f32_16x16x32_bf16 v[8:11], v[136:139], v[168:171], v[8:11]
	v_mfma_f32_16x16x32_bf16 v[60:63], v[132:135], v[148:151], v[60:63]
	v_mfma_f32_16x16x32_bf16 v[56:59], v[140:143], v[148:151], v[56:59]
	v_mfma_f32_16x16x32_bf16 v[44:47], v[132:135], v[156:159], v[44:47]
	v_mfma_f32_16x16x32_bf16 v[40:43], v[140:143], v[156:159], v[40:43]
	v_mfma_f32_16x16x32_bf16 v[28:31], v[132:135], v[164:167], v[28:31]
	v_mfma_f32_16x16x32_bf16 v[24:27], v[140:143], v[164:167], v[24:27]
	v_mfma_f32_16x16x32_bf16 v[12:15], v[132:135], v[172:175], v[12:15]
	v_mfma_f32_16x16x32_bf16 v[8:11], v[140:143], v[172:175], v[8:11]
	s_barrier
; DI unsigned pack2(float lo, float hi) { f32x2 v = {lo, hi}; bf16v2 r = __builtin_convertvector(v, bf16v2); return __builtin_bit_cast(unsigned, r); }
; #define PG8_STAGE(bufoff, gbase, voff) do { _Pragma("unroll") for (int _i = 0; _i < 2; ++_i) \
;     __builtin_amdgcn_global_load_lds((const unsigned*)((const char*)(gbase) + (voff)[_i]), (LAS unsigned*)(lds + (bufoff) + ldsw + _i * 8192), 16, 0, 0); } while (0)
; #define PG8_WAIT_V(n) asm volatile("s_waitcnt vmcnt(" #n ")" ::: "memory")
; #define PG8_BAR __builtin_amdgcn_s_barrier()
;   DI void operator()(const f32x4 (&acc)[2][2][4][2], const Unit& u, int wr, int wc, int fr, int fq) const {
;     const int row0 = u.pm * BM + wr * 64 + fr, col0 = u.pn * BM + wc * 32 + 8 * fq;
; #pragma unroll
;     for (int ai = 0; ai < 2; ++ai) {
;       f32x4 bv[4][2][2];
; #pragma unroll
;       for (int m = 0; m < 4; ++m)
; #pragma unroll
;         for (int bj = 0; bj < 2; ++bj) {
;           const float* bp = base + (size_t)(row0 + ai * HALF + m * 16) * 2048 + col0 + bj * HALF;
;           bv[m][bj][0] = *(const f32x4*)bp; bv[m][bj][1] = *(const f32x4*)(bp + 4);
;         }
; #pragma unroll
;       for (int m = 0; m < 4; ++m) {
;         const int row = row0 + ai * HALF + m * 16;
;         const size_t off = (size_t)row * 2048 + col0;
;         float ss = 0.f;
; #pragma unroll
;         for (int bj = 0; bj < 2; ++bj) {
;           const f32x4 v0 = acc[ai][bj][m][0] + bv[m][bj][0], v1 = acc[ai][bj][m][1] + bv[m][bj][1];
;           *(f32x4*)(C + off + bj * HALF) = v0; *(f32x4*)(C + off + bj * HALF + 4) = v1;
;           if (xb) {
;             u32x4 w; w.x = pack2(v0[0], v0[1]); w.y = pack2(v0[2], v0[3]); w.z = pack2(v1[0], v1[1]); w.w = pack2(v1[2], v1[3]);
;             *(u32x4*)(xb + off + bj * HALF) = w;
;             ss += v0[0] * v0[0] + v0[1] * v0[1] + v0[2] * v0[2] + v0[3] * v0[3] + v1[0] * v1[0] + v1[1] * v1[1] + v1[2] * v1[2] + v1[3] * v1[3];
;           }
;         }
;         if (xb) {
;           ss += __shfl_xor(ss, 16); ss += __shfl_xor(ss, 32);
;           if (fq == 0) ssq[(size_t)row * 32 + u.pn * 4 + wc] = ss;
; template <class Epi, class Sched = StaticOrder>
; DI void gemm_phase(LAS unsigned char* lds, const Gemm g, const Sched& S, const Epi& E) {
;     ...
;       PG8_STAGE(PG8_SB(1, 1), b3 + hstep, voffB);
;       PG8_WAIT_V(6); PG8_BAR; PG8_MMA(1, 1, At, B1); PG8_BAR;
	s_setprio 0
	s_add_u32 s24, s24, 0x80080
	s_addc_u32 s25, s25, 0
	s_add_i32 s26, s26, s35
	s_mov_b32 m0, s26
	s_nop 0
	global_load_lds_dwordx4 v180, s[24:25]
	s_add_i32 m0, s26, 0x2000
	s_nop 0
	global_load_lds_dwordx4 v176, s[24:25]
	ds_read_b128 v[128:131], v207
	ds_read_b128 v[132:135], v207 offset:1024
	ds_read_b128 v[136:139], v207 offset:2048
	ds_read_b128 v[140:143], v207 offset:3072
	s_waitcnt vmcnt(6)
	s_setprio 1
	s_barrier
	v_mfma_f32_16x16x32_bf16 v[52:55], v[192:195], v[144:147], v[52:55]
	v_mfma_f32_16x16x32_bf16 v[48:51], v[200:203], v[144:147], v[48:51]
	v_mfma_f32_16x16x32_bf16 v[36:39], v[192:195], v[152:155], v[36:39]
	v_mfma_f32_16x16x32_bf16 v[32:35], v[200:203], v[152:155], v[32:35]
	v_mfma_f32_16x16x32_bf16 v[20:23], v[192:195], v[160:163], v[20:23]
	v_mfma_f32_16x16x32_bf16 v[16:19], v[200:203], v[160:163], v[16:19]
	v_mfma_f32_16x16x32_bf16 v[4:7], v[192:195], v[168:171], v[4:7]
	v_mfma_f32_16x16x32_bf16 v[0:3], v[200:203], v[168:171], v[0:3]
	v_mfma_f32_16x16x32_bf16 v[52:55], v[196:199], v[148:151], v[52:55]
	v_mfma_f32_16x16x32_bf16 v[48:51], v[212:215], v[148:151], v[48:51]
	v_mfma_f32_16x16x32_bf16 v[36:39], v[196:199], v[156:159], v[36:39]
	v_mfma_f32_16x16x32_bf16 v[32:35], v[212:215], v[156:159], v[32:35]
	v_mfma_f32_16x16x32_bf16 v[20:23], v[196:199], v[164:167], v[20:23]
	v_mfma_f32_16x16x32_bf16 v[16:19], v[212:215], v[164:167], v[16:19]
	v_mfma_f32_16x16x32_bf16 v[4:7], v[196:199], v[172:175], v[4:7]
	v_mfma_f32_16x16x32_bf16 v[0:3], v[212:215], v[172:175], v[0:3]
	s_add_i32 s53, s53, 2
	s_add_u32 s22, s22, 0x100
	s_addc_u32 s23, s23, 0
	s_add_u32 s45, s45, 0x100
	s_addc_u32 s52, s52, 0
	s_cmp_gt_u32 s53, 29
	s_barrier
	s_setprio 0
	s_cbranch_scc0 .LBB0_728
	s_waitcnt lgkmcnt(0)
	v_lshl_add_u32 v196, s12, 8, v204
	v_lshl_or_b32 v192, s42, 8, v206
	v_ashrrev_i32_e32 v193, 31, v192
	v_ashrrev_i32_e32 v197, 31, v196
	v_lshl_add_u64 v[194:195], v[192:193], 2, s[60:61]
	v_lshlrev_b64 v[128:129], 13, v[196:197]
	v_lshl_add_u64 v[128:129], v[194:195], 0, v[128:129]
	global_load_dwordx4 v[214:217], v[128:129], off
	global_load_dwordx4 v[218:221], v[128:129], off offset:16
	global_load_dwordx4 v[222:225], v[128:129], off offset:512
	global_load_dwordx4 v[226:229], v[128:129], off offset:528
	v_or_b32_e32 v202, 16, v196
	v_or_b32_e32 v200, 32, v196
	v_or_b32_e32 v198, 48, v196
	v_ashrrev_i32_e32 v203, 31, v202
	v_ashrrev_i32_e32 v201, 31, v200
	v_ashrrev_i32_e32 v199, 31, v198
	v_lshlrev_b64 v[128:129], 13, v[202:203]
	v_lshlrev_b64 v[130:131], 13, v[200:201]
	v_lshlrev_b64 v[132:133], 13, v[198:199]
	v_lshl_add_u64 v[128:129], v[194:195], 0, v[128:129]
	v_lshl_add_u64 v[130:131], v[194:195], 0, v[130:131]
	v_lshl_add_u64 v[132:133], v[194:195], 0, v[132:133]
	global_load_dwordx4 v[168:171], v[128:129], off offset:16
	global_load_dwordx4 v[172:175], v[128:129], off
	global_load_dwordx4 v[160:163], v[128:129], off offset:528
	global_load_dwordx4 v[164:167], v[128:129], off offset:512
	global_load_dwordx4 v[152:155], v[130:131], off offset:16
	global_load_dwordx4 v[156:159], v[130:131], off
	global_load_dwordx4 v[144:147], v[130:131], off offset:528
	global_load_dwordx4 v[148:151], v[130:131], off offset:512
	global_load_dwordx4 v[136:139], v[132:133], off offset:16
	global_load_dwordx4 v[140:143], v[132:133], off
	s_nop 0
	global_load_dwordx4 v[128:131], v[132:133], off offset:528
	s_nop 0
	global_load_dwordx4 v[132:135], v[132:133], off offset:512
	v_and_b32_e32 v212, 64, v211
	v_xor_b32_e32 v230, 16, v211
	v_add_u32_e32 v232, 64, v212
	v_xor_b32_e32 v231, 32, v211
	v_cmp_lt_i32_e32 vcc, v230, v232
	v_lshlrev_b64 v[212:213], 11, v[196:197]
	v_readlane_b32 s64, v243, 3
	v_cndmask_b32_e32 v233, v211, v230, vcc
	v_cmp_lt_i32_e32 vcc, v231, v232
	v_readlane_b32 s78, v243, 17
	v_readlane_b32 s79, v243, 18
	v_cndmask_b32_e32 v234, v211, v231, vcc
	v_lshl_add_u64 v[230:231], v[212:213], 0, v[192:193]
	v_lshlrev_b32_e32 v212, 2, v233
	v_lshl_add_u64 v[232:233], v[230:231], 2, s[78:79]
	v_lshl_add_u64 v[230:231], v[230:231], 1, s[2:3]
	s_lshl_b32 s22, s42, 2
	s_ashr_i32 s23, s22, 31
	v_readlane_b32 s65, v243, 4
	v_readlane_b32 s66, v243, 5
	v_readlane_b32 s67, v243, 6
	v_readlane_b32 s68, v243, 7
	v_readlane_b32 s69, v243, 8
	v_readlane_b32 s70, v243, 9
	v_readlane_b32 s71, v243, 10
	v_readlane_b32 s72, v243, 11
	v_readlane_b32 s73, v243, 12
	v_readlane_b32 s74, v243, 13
	v_readlane_b32 s75, v243, 14
	v_readlane_b32 s76, v243, 15
	v_readlane_b32 s77, v243, 16
	s_waitcnt vmcnt(0)
	v_pk_add_f32 v[126:127], v[126:127], v[216:217]
	v_pk_add_f32 v[124:125], v[124:125], v[214:215]
	v_pk_add_f32 v[116:117], v[116:117], v[222:223]
	v_pk_add_f32 v[122:123], v[122:123], v[220:221]
	v_pk_add_f32 v[120:121], v[120:121], v[218:219]
	v_pk_add_f32 v[214:215], v[112:113], v[226:227]
	global_store_dwordx4 v[232:233], v[124:127], off
	global_store_dwordx4 v[232:233], v[120:123], off offset:16
	v_cvt_pk_bf16_f32 v112, v124, v125
	v_mul_f32_e32 v125, v125, v125
	v_mul_f32_e32 v213, v117, v117
	v_pk_add_f32 v[118:119], v[118:119], v[224:225]
	v_fmac_f32_e32 v125, v124, v124
	v_fmac_f32_e32 v213, v116, v116
	v_fmac_f32_e32 v125, v126, v126
	v_fmac_f32_e32 v213, v118, v118
	v_fmac_f32_e32 v125, v127, v127
	v_fmac_f32_e32 v213, v119, v119
	v_fmac_f32_e32 v125, v120, v120
	v_fmac_f32_e32 v213, v214, v214
	v_pk_add_f32 v[216:217], v[114:115], v[228:229]
	v_fmac_f32_e32 v125, v121, v121
	v_fmac_f32_e32 v213, v215, v215
	v_fmac_f32_e32 v125, v122, v122
	v_fmac_f32_e32 v213, v216, v216
	v_fmac_f32_e32 v125, v123, v123
	v_fmac_f32_e32 v213, v217, v217
	v_cvt_pk_bf16_f32 v114, v120, v121
	v_add_f32_e32 v120, v125, v213
	ds_bpermute_b32 v121, v212, v120
	v_cvt_pk_bf16_f32 v113, v126, v127
	v_cvt_pk_bf16_f32 v115, v122, v123
	global_store_dwordx4 v[230:231], v[112:115], off
	global_store_dwordx4 v[232:233], v[116:119], off offset:512
	global_store_dwordx4 v[232:233], v[214:217], off offset:528
	v_cvt_pk_bf16_f32 v122, v116, v117
	s_waitcnt lgkmcnt(0)
	v_add_f32_e32 v112, v120, v121
	v_lshlrev_b32_e32 v120, 2, v234
	ds_bpermute_b32 v113, v120, v112
	v_cvt_pk_bf16_f32 v123, v118, v119
	v_cvt_pk_bf16_f32 v124, v214, v215
	v_cvt_pk_bf16_f32 v125, v216, v217
	global_store_dwordx4 v[230:231], v[122:125], off offset:256
	s_and_saveexec_b64 s[24:25], s[0:1]
	s_cbranch_execz .LBB0_731
	s_waitcnt lgkmcnt(0)
	v_add_f32_e32 v114, v112, v113
	v_lshlrev_b64 v[112:113], 7, v[196:197]
	v_lshl_add_u64 v[112:113], s[8:9], 0, v[112:113]
	v_lshl_add_u64 v[112:113], s[22:23], 2, v[112:113]
	s_lshl_b32 s12, s41, 2
	v_lshl_add_u64 v[112:113], v[112:113], 0, s[12:13]
	global_store_dword v[112:113], v114, off

; #define PG8_STAGE(bufoff, gbase, voff) do { _Pragma("unroll") for (int _i = 0; _i < 2; ++_i) \
;     __builtin_amdgcn_global_load_lds((const unsigned*)((const char*)(gbase) + (voff)[_i]), (LAS unsigned*)(lds + (bufoff) + ldsw + _i * 8192), 16, 0, 0); } while (0)
; #define PG8_LDA(dst, b, h) do { _Pragma("unroll") for (int m = 0; m < 4; ++m) _Pragma("unroll") for (int k = 0; k < 2; ++k) dst[m][k] = *(const LAS bf16x8*)(lds + PG8_SA(b, h) + aoff + m * 2048 + k * 1024); } while (0)
; #define PG8_LDB(dst, b, h) do { _Pragma("unroll") for (int n = 0; n < 2; ++n) _Pragma("unroll") for (int k = 0; k < 2; ++k) dst[n][k] = *(const LAS bf16x8*)(lds + PG8_SB(b, h) + boff + n * 2048 + k * 1024); } while (0)
; #define PG8_MMA(ai, bj, At, Bt) do { __builtin_amdgcn_s_setprio(1); _Pragma("unroll") for (int m = 0; m < 4; ++m) _Pragma("unroll") for (int n = 0; n < 2; ++n) _Pragma("unroll") for (int k = 0; k < 2; ++k) \
;     acc[ai][bj][m][n] = __builtin_amdgcn_mfma_f32_16x16x32_bf16(Bt[n][k], At[m][k], acc[ai][bj][m][n], 0, 0, 0); __builtin_amdgcn_s_setprio(0); } while (0)
; #define PG8_WAIT_V(n) asm volatile("s_waitcnt vmcnt(" #n ")" ::: "memory")
; template <class Epi, class Sched = StaticOrder>
; DI void gemm_phase(LAS unsigned char* lds, const Gemm g, const Sched& S, const Epi& E) {
;     ...
;     for (int t = 0; t < nt; t += 2) {
;       const bool last = (t == nt - 2);
;       const char* a1 = cA + (size_t)(t + 1) * kstep;
;       const char* a2 = last ? nA : cA + (size_t)(t + 2) * kstep; const char* b2 = last ? nB : cB + (size_t)(t + 2) * kstep;
;       const char* a3 = a2 + kstep; const char* b3 = b2 + kstep;
;       PG8_LDB(B0, 0, 0); PG8_SCHED; PG8_LDA(At, 0, 0); PG8_STAGE(PG8_SA(1, 1), a1 + hstep, voffA);
;       PG8_WAIT_L(8); PG8_BAR; PG8_WAIT_L(0); PG8_MMA(0, 0, At, B0); PG8_BAR; PG8_SCHED;
;       PG8_LDB(B1, 0, 1); PG8_STAGE(PG8_SB(0, 0), b2, voffB);
;       PG8_BAR; PG8_WAIT_L(0); PG8_MMA(0, 1, At, B1); PG8_BAR;
;       PG8_LDA(At, 0, 1); PG8_STAGE(PG8_SA(0, 0), a2, voffA);
;       PG8_BAR; PG8_WAIT_L(0); PG8_MMA(1, 0, At, B0); PG8_BAR; PG8_SCHED;
;       PG8_STAGE(PG8_SB(0, 1), b2 + hstep, voffB);
;       PG8_WAIT_V(6); PG8_BAR; PG8_MMA(1, 1, At, B1); PG8_BAR;
;       PG8_LDB(B0, 1, 0); PG8_SCHED; PG8_LDA(At, 1, 0); PG8_STAGE(PG8_SA(0, 1), a2 + hstep, voffA);
;       PG8_WAIT_L(8); PG8_BAR; PG8_WAIT_L(0); PG8_MMA(0, 0, At, B0); PG8_BAR; PG8_SCHED;
.LBB0_811:
	s_add_u32 s46, s14, 0xfff80080
	s_addc_u32 s47, s15, -1
	s_cmp_eq_u32 s52, 28
	s_cselect_b32 s49, s37, s47
	s_cselect_b32 s48, s42, s46
	s_cselect_b32 s47, s35, s45
	s_cselect_b32 s46, s43, s44
	s_add_i32 m0, s62, 0xc000
	ds_read_b128 v[80:83], v202
	ds_read_b128 v[84:87], v202 offset:1024
	ds_read_b128 v[92:95], v202 offset:2048
	ds_read_b128 v[96:99], v202 offset:3072
	ds_read_b128 v[180:183], v202 offset:4096
	ds_read_b128 v[184:187], v202 offset:5120
	ds_read_b128 v[188:191], v202 offset:6144
	ds_read_b128 v[192:195], v202 offset:7168
	global_load_lds_dwordx4 v170, s[14:15]
	s_add_i32 m0, s62, 0xe000
	s_nop 0
	global_load_lds_dwordx4 v172, s[14:15]
	s_waitcnt lgkmcnt(0)
	s_setprio 1
	s_barrier
	v_mfma_f32_16x16x32_bf16 v[156:159], v[64:67], v[80:83], v[156:159]
	v_mfma_f32_16x16x32_bf16 v[144:147], v[72:75], v[80:83], v[144:147]
	v_mfma_f32_16x16x32_bf16 v[140:143], v[64:67], v[92:95], v[140:143]
	v_mfma_f32_16x16x32_bf16 v[132:135], v[72:75], v[92:95], v[132:135]
	v_mfma_f32_16x16x32_bf16 v[124:127], v[64:67], v[180:183], v[124:127]
	v_mfma_f32_16x16x32_bf16 v[116:119], v[72:75], v[180:183], v[116:119]
	v_mfma_f32_16x16x32_bf16 v[112:115], v[64:67], v[188:191], v[112:115]
	v_mfma_f32_16x16x32_bf16 v[108:111], v[72:75], v[188:191], v[108:111]
	v_mfma_f32_16x16x32_bf16 v[156:159], v[68:71], v[84:87], v[156:159]
	v_mfma_f32_16x16x32_bf16 v[144:147], v[76:79], v[84:87], v[144:147]
	v_mfma_f32_16x16x32_bf16 v[140:143], v[68:71], v[96:99], v[140:143]
	v_mfma_f32_16x16x32_bf16 v[132:135], v[76:79], v[96:99], v[132:135]
	v_mfma_f32_16x16x32_bf16 v[124:127], v[68:71], v[184:187], v[124:127]
	v_mfma_f32_16x16x32_bf16 v[116:119], v[76:79], v[184:187], v[116:119]
	v_mfma_f32_16x16x32_bf16 v[112:115], v[68:71], v[192:195], v[112:115]
	v_mfma_f32_16x16x32_bf16 v[108:111], v[76:79], v[192:195], v[108:111]
	s_barrier
	s_setprio 0
	s_add_i32 s53, s72, s60
	s_add_u32 s98, s46, 0x80
	s_addc_u32 s99, s47, 0
	s_mov_b32 m0, s53
	ds_read_b128 v[206:209], v203
	ds_read_b128 v[212:215], v203 offset:1024
	ds_read_b128 v[216:219], v203 offset:2048
	ds_read_b128 v[220:223], v203 offset:3072
	global_load_lds_dwordx4 v164, s[46:47]
	s_add_i32 m0, s53, 0x2000
	s_nop 0
	global_load_lds_dwordx4 v160, s[46:47]
	s_waitcnt lgkmcnt(0)
	s_setprio 1
	s_barrier
	v_mfma_f32_16x16x32_bf16 v[152:155], v[206:209], v[80:83], v[152:155]
	v_mfma_f32_16x16x32_bf16 v[80:83], v[216:219], v[80:83], v[148:151]
	v_mfma_f32_16x16x32_bf16 v[152:155], v[212:215], v[84:87], v[152:155]
	v_mfma_f32_16x16x32_bf16 v[80:83], v[220:223], v[84:87], v[80:83]
	v_mfma_f32_16x16x32_bf16 v[84:87], v[206:209], v[92:95], v[136:139]
	v_mfma_f32_16x16x32_bf16 v[92:95], v[216:219], v[92:95], v[128:131]
	v_mfma_f32_16x16x32_bf16 v[104:107], v[216:219], v[180:183], v[104:107]
	v_mfma_f32_16x16x32_bf16 v[100:103], v[206:209], v[188:191], v[100:103]
	v_mfma_f32_16x16x32_bf16 v[88:91], v[216:219], v[188:191], v[88:91]
	v_mfma_f32_16x16x32_bf16 v[84:87], v[212:215], v[96:99], v[84:87]
	v_mfma_f32_16x16x32_bf16 v[92:95], v[220:223], v[96:99], v[92:95]
	v_mfma_f32_16x16x32_bf16 v[96:99], v[206:209], v[180:183], v[120:123]
	v_mfma_f32_16x16x32_bf16 v[104:107], v[220:223], v[184:187], v[104:107]
	v_mfma_f32_16x16x32_bf16 v[100:103], v[212:215], v[192:195], v[100:103]
	v_mfma_f32_16x16x32_bf16 v[88:91], v[220:223], v[192:195], v[88:91]
	v_mfma_f32_16x16x32_bf16 v[96:99], v[212:215], v[184:187], v[96:99]
	s_barrier
	s_setprio 0
	s_mov_b32 m0, s62
	s_add_u32 s100, s48, 0x80
	s_addc_u32 s101, s49, 0
	ds_read_b128 v[120:123], v202 offset:16384
	ds_read_b128 v[128:131], v202 offset:17408
	ds_read_b128 v[136:139], v202 offset:18432
	ds_read_b128 v[148:151], v202 offset:19456
	ds_read_b128 v[180:183], v202 offset:20480
	ds_read_b128 v[184:187], v202 offset:21504
	ds_read_b128 v[188:191], v202 offset:22528
	ds_read_b128 v[192:195], v202 offset:23552
	global_load_lds_dwordx4 v166, s[48:49]
	s_mov_b32 m0, s63
	s_nop 0
	global_load_lds_dwordx4 v162, s[48:49]
	s_waitcnt vmcnt(10)
	s_waitcnt lgkmcnt(0)
	s_setprio 1
	s_barrier
	v_mfma_f32_16x16x32_bf16 v[60:63], v[64:67], v[120:123], v[60:63]
	v_mfma_f32_16x16x32_bf16 v[48:51], v[72:75], v[120:123], v[48:51]
	v_mfma_f32_16x16x32_bf16 v[44:47], v[64:67], v[136:139], v[44:47]
	v_mfma_f32_16x16x32_bf16 v[36:39], v[72:75], v[136:139], v[36:39]
	v_mfma_f32_16x16x32_bf16 v[28:31], v[64:67], v[180:183], v[28:31]
	v_mfma_f32_16x16x32_bf16 v[20:23], v[72:75], v[180:183], v[20:23]
	v_mfma_f32_16x16x32_bf16 v[16:19], v[64:67], v[188:191], v[16:19]
	v_mfma_f32_16x16x32_bf16 v[12:15], v[72:75], v[188:191], v[12:15]
	v_mfma_f32_16x16x32_bf16 v[60:63], v[68:71], v[128:131], v[60:63]
	v_mfma_f32_16x16x32_bf16 v[48:51], v[76:79], v[128:131], v[48:51]
	v_mfma_f32_16x16x32_bf16 v[44:47], v[68:71], v[148:151], v[44:47]
	v_mfma_f32_16x16x32_bf16 v[36:39], v[76:79], v[148:151], v[36:39]
	v_mfma_f32_16x16x32_bf16 v[28:31], v[68:71], v[184:187], v[28:31]
	v_mfma_f32_16x16x32_bf16 v[20:23], v[76:79], v[184:187], v[20:23]
	v_mfma_f32_16x16x32_bf16 v[16:19], v[68:71], v[192:195], v[16:19]
	v_mfma_f32_16x16x32_bf16 v[12:15], v[76:79], v[192:195], v[12:15]
	s_barrier
	s_setprio 0
	s_add_u32 s54, s46, 0x80000
	s_addc_u32 s55, s47, 0
	s_add_i32 s53, s73, s60
	s_mov_b32 m0, s53
	s_nop 0
	global_load_lds_dwordx4 v164, s[54:55]
	s_add_i32 m0, s53, 0x2000
	s_nop 0
	global_load_lds_dwordx4 v160, s[54:55]
	s_add_i32 s53, 0, 0x18000
	v_add_u32_e32 v76, s53, v198
	ds_read_b128 v[64:67], v76
	ds_read_b128 v[68:71], v76 offset:1024
	ds_read_b128 v[72:75], v76 offset:2048
	ds_read_b128 v[76:79], v76 offset:3072
	s_waitcnt vmcnt(6)
	s_setprio 1
	s_barrier
; #define PG8_STAGE(bufoff, gbase, voff) do { _Pragma("unroll") for (int _i = 0; _i < 2; ++_i) \
;     __builtin_amdgcn_global_load_lds((const unsigned*)((const char*)(gbase) + (voff)[_i]), (LAS unsigned*)(lds + (bufoff) + ldsw + _i * 8192), 16, 0, 0); } while (0)
; #define PG8_LDA(dst, b, h) do { _Pragma("unroll") for (int m = 0; m < 4; ++m) _Pragma("unroll") for (int k = 0; k < 2; ++k) dst[m][k] = *(const LAS bf16x8*)(lds + PG8_SA(b, h) + aoff + m * 2048 + k * 1024); } while (0)
; #define PG8_LDB(dst, b, h) do { _Pragma("unroll") for (int n = 0; n < 2; ++n) _Pragma("unroll") for (int k = 0; k < 2; ++k) dst[n][k] = *(const LAS bf16x8*)(lds + PG8_SB(b, h) + boff + n * 2048 + k * 1024); } while (0)
; #define PG8_MMA(ai, bj, At, Bt) do { __builtin_amdgcn_s_setprio(1); _Pragma("unroll") for (int m = 0; m < 4; ++m) _Pragma("unroll") for (int n = 0; n < 2; ++n) _Pragma("unroll") for (int k = 0; k < 2; ++k) \
;     acc[ai][bj][m][n] = __builtin_amdgcn_mfma_f32_16x16x32_bf16(Bt[n][k], At[m][k], acc[ai][bj][m][n], 0, 0, 0); __builtin_amdgcn_s_setprio(0); } while (0)
; #define PG8_WAIT_V(n) asm volatile("s_waitcnt vmcnt(" #n ")" ::: "memory")
; #define PG8_WAIT_L(n) asm volatile("s_waitcnt lgkmcnt(" #n ")" ::: "memory")
; #define PG8_BAR __builtin_amdgcn_s_barrier()
; #define PG8_SCHED __builtin_amdgcn_sched_barrier(0)
; template <class Epi, class Sched = StaticOrder>
; DI void gemm_phase(LAS unsigned char* lds, const Gemm g, const Sched& S, const Epi& E) {
;     ...
;       PG8_WAIT_V(6); PG8_BAR; PG8_MMA(1, 1, At, B1); PG8_BAR;
;       PG8_LDB(B0, 1, 0); PG8_SCHED; PG8_LDA(At, 1, 0); PG8_STAGE(PG8_SA(0, 1), a2 + hstep, voffA);
;       PG8_WAIT_L(8); PG8_BAR; PG8_WAIT_L(0); PG8_MMA(0, 0, At, B0); PG8_BAR; PG8_SCHED;
;       PG8_LDB(B1, 1, 1); PG8_STAGE(PG8_SB(1, 0), b3, voffB);
;       PG8_BAR; PG8_WAIT_L(0); PG8_MMA(0, 1, At, B1); PG8_BAR;
;       PG8_LDA(At, 1, 1); PG8_STAGE(PG8_SA(1, 0), a3, voffA);
;       PG8_BAR; PG8_WAIT_L(0); PG8_MMA(1, 0, At, B0); PG8_BAR; PG8_SCHED;
	v_mfma_f32_16x16x32_bf16 v[56:59], v[206:209], v[120:123], v[56:59]
	v_mfma_f32_16x16x32_bf16 v[52:55], v[216:219], v[120:123], v[52:55]
	v_mfma_f32_16x16x32_bf16 v[40:43], v[206:209], v[136:139], v[40:43]
	v_mfma_f32_16x16x32_bf16 v[32:35], v[216:219], v[136:139], v[32:35]
	v_mfma_f32_16x16x32_bf16 v[24:27], v[206:209], v[180:183], v[24:27]
	v_mfma_f32_16x16x32_bf16 v[8:11], v[216:219], v[180:183], v[8:11]
	v_mfma_f32_16x16x32_bf16 v[4:7], v[206:209], v[188:191], v[4:7]
	v_mfma_f32_16x16x32_bf16 v[0:3], v[216:219], v[188:191], v[0:3]
	v_mfma_f32_16x16x32_bf16 v[56:59], v[212:215], v[128:131], v[56:59]
	v_mfma_f32_16x16x32_bf16 v[52:55], v[220:223], v[128:131], v[52:55]
	v_mfma_f32_16x16x32_bf16 v[40:43], v[212:215], v[148:151], v[40:43]
	v_mfma_f32_16x16x32_bf16 v[32:35], v[220:223], v[148:151], v[32:35]
	v_mfma_f32_16x16x32_bf16 v[24:27], v[212:215], v[184:187], v[24:27]
	v_mfma_f32_16x16x32_bf16 v[8:11], v[220:223], v[184:187], v[8:11]
	v_mfma_f32_16x16x32_bf16 v[4:7], v[212:215], v[192:195], v[4:7]
	v_mfma_f32_16x16x32_bf16 v[0:3], v[220:223], v[192:195], v[0:3]
	s_barrier
	s_setprio 0
	s_add_u32 s48, s48, 0x80000
	s_addc_u32 s49, s49, 0
	s_mov_b32 m0, s64
	ds_read_b128 v[120:123], v202 offset:32768
	ds_read_b128 v[128:131], v202 offset:33792
	ds_read_b128 v[180:183], v202 offset:34816
	ds_read_b128 v[184:187], v202 offset:35840
	ds_read_b128 v[188:191], v202 offset:36864
	ds_read_b128 v[192:195], v202 offset:37888
	ds_read_b128 v[206:209], v202 offset:38912
	ds_read_b128 v[212:215], v202 offset:39936
	global_load_lds_dwordx4 v166, s[48:49]
	s_mov_b32 m0, s65
	s_nop 0
	global_load_lds_dwordx4 v162, s[48:49]
	s_waitcnt lgkmcnt(0)
	s_setprio 1
	s_barrier
	v_mfma_f32_16x16x32_bf16 v[136:139], v[64:67], v[120:123], v[156:159]
	v_mfma_f32_16x16x32_bf16 v[156:159], v[68:71], v[128:131], v[136:139]
	v_mfma_f32_16x16x32_bf16 v[136:139], v[72:75], v[120:123], v[144:147]
	v_mfma_f32_16x16x32_bf16 v[144:147], v[76:79], v[128:131], v[136:139]
	v_mfma_f32_16x16x32_bf16 v[136:139], v[64:67], v[180:183], v[140:143]
	v_mfma_f32_16x16x32_bf16 v[132:135], v[72:75], v[180:183], v[132:135]
	v_mfma_f32_16x16x32_bf16 v[124:127], v[64:67], v[188:191], v[124:127]
	v_mfma_f32_16x16x32_bf16 v[116:119], v[72:75], v[188:191], v[116:119]
	v_mfma_f32_16x16x32_bf16 v[112:115], v[64:67], v[206:209], v[112:115]
	v_mfma_f32_16x16x32_bf16 v[108:111], v[72:75], v[206:209], v[108:111]
	v_mfma_f32_16x16x32_bf16 v[140:143], v[68:71], v[184:187], v[136:139]
	v_mfma_f32_16x16x32_bf16 v[132:135], v[76:79], v[184:187], v[132:135]
	v_mfma_f32_16x16x32_bf16 v[124:127], v[68:71], v[192:195], v[124:127]
	v_mfma_f32_16x16x32_bf16 v[116:119], v[76:79], v[192:195], v[116:119]
	v_mfma_f32_16x16x32_bf16 v[112:115], v[68:71], v[212:215], v[112:115]
	v_mfma_f32_16x16x32_bf16 v[108:111], v[76:79], v[212:215], v[108:111]
	s_barrier
	s_setprio 0
	s_add_i32 s48, 0, 0x1c000
	v_add_u32_e32 v136, s48, v198
	s_add_i32 s49, s53, s60
	ds_read_b128 v[216:219], v136
	ds_read_b128 v[220:223], v136 offset:1024
	ds_read_b128 v[224:227], v136 offset:2048
	ds_read_b128 v[228:231], v136 offset:3072
	s_mov_b32 m0, s49
	s_nop 0
	global_load_lds_dwordx4 v164, s[98:99]
	s_add_i32 m0, s49, 0x2000
	s_nop 0
	global_load_lds_dwordx4 v160, s[98:99]
	s_waitcnt lgkmcnt(0)
	s_setprio 1
	s_barrier
	v_mfma_f32_16x16x32_bf16 v[80:83], v[224:227], v[120:123], v[80:83]
	v_mfma_f32_16x16x32_bf16 v[136:139], v[216:219], v[120:123], v[152:155]
	v_mfma_f32_16x16x32_bf16 v[148:151], v[228:231], v[128:131], v[80:83]
	v_mfma_f32_16x16x32_bf16 v[80:83], v[216:219], v[180:183], v[84:87]
	v_mfma_f32_16x16x32_bf16 v[152:155], v[220:223], v[128:131], v[136:139]
	v_mfma_f32_16x16x32_bf16 v[136:139], v[220:223], v[184:187], v[80:83]
	v_mfma_f32_16x16x32_bf16 v[80:83], v[224:227], v[180:183], v[92:95]
	v_mfma_f32_16x16x32_bf16 v[128:131], v[228:231], v[184:187], v[80:83]
	v_mfma_f32_16x16x32_bf16 v[80:83], v[216:219], v[188:191], v[96:99]
	v_mfma_f32_16x16x32_bf16 v[120:123], v[220:223], v[192:195], v[80:83]
	v_mfma_f32_16x16x32_bf16 v[80:83], v[224:227], v[188:191], v[104:107]
	v_mfma_f32_16x16x32_bf16 v[104:107], v[228:231], v[192:195], v[80:83]
	v_mfma_f32_16x16x32_bf16 v[80:83], v[216:219], v[206:209], v[100:103]
	v_mfma_f32_16x16x32_bf16 v[100:103], v[220:223], v[212:215], v[80:83]
	v_mfma_f32_16x16x32_bf16 v[80:83], v[224:227], v[206:209], v[88:91]
	v_mfma_f32_16x16x32_bf16 v[88:91], v[228:231], v[212:215], v[80:83]
	s_barrier
	s_setprio 0
	s_mov_b32 m0, s67
	s_nop 2
	ds_read_b128 v[80:83], v202 offset:49152
	ds_read_b128 v[84:87], v202 offset:50176
	ds_read_b128 v[92:95], v202 offset:51200
	ds_read_b128 v[96:99], v202 offset:52224
	ds_read_b128 v[180:183], v202 offset:53248
	ds_read_b128 v[184:187], v202 offset:54272
	ds_read_b128 v[188:191], v202 offset:55296
	ds_read_b128 v[192:195], v202 offset:56320
	global_load_lds_dwordx4 v166, s[100:101]
	s_mov_b32 m0, s68
	s_nop 0
	global_load_lds_dwordx4 v162, s[100:101]
	s_waitcnt vmcnt(10)
	s_waitcnt lgkmcnt(0)
	s_setprio 1
	s_barrier
	v_mfma_f32_16x16x32_bf16 v[60:63], v[64:67], v[80:83], v[60:63]
	v_mfma_f32_16x16x32_bf16 v[48:51], v[72:75], v[80:83], v[48:51]
	v_mfma_f32_16x16x32_bf16 v[44:47], v[64:67], v[92:95], v[44:47]
	v_mfma_f32_16x16x32_bf16 v[36:39], v[72:75], v[92:95], v[36:39]
	v_mfma_f32_16x16x32_bf16 v[28:31], v[64:67], v[180:183], v[28:31]
	v_mfma_f32_16x16x32_bf16 v[20:23], v[72:75], v[180:183], v[20:23]
	v_mfma_f32_16x16x32_bf16 v[16:19], v[64:67], v[188:191], v[16:19]
	v_mfma_f32_16x16x32_bf16 v[12:15], v[72:75], v[188:191], v[12:15]
	v_mfma_f32_16x16x32_bf16 v[60:63], v[68:71], v[84:87], v[60:63]
	v_mfma_f32_16x16x32_bf16 v[48:51], v[76:79], v[84:87], v[48:51]
	v_mfma_f32_16x16x32_bf16 v[44:47], v[68:71], v[96:99], v[44:47]
	v_mfma_f32_16x16x32_bf16 v[36:39], v[76:79], v[96:99], v[36:39]
	v_mfma_f32_16x16x32_bf16 v[28:31], v[68:71], v[184:187], v[28:31]
	v_mfma_f32_16x16x32_bf16 v[20:23], v[76:79], v[184:187], v[20:23]
	v_mfma_f32_16x16x32_bf16 v[16:19], v[68:71], v[192:195], v[16:19]
	v_mfma_f32_16x16x32_bf16 v[12:15], v[76:79], v[192:195], v[12:15]
	s_barrier
; #define PG8_STAGE(bufoff, gbase, voff) do { _Pragma("unroll") for (int _i = 0; _i < 2; ++_i) \
;     __builtin_amdgcn_global_load_lds((const unsigned*)((const char*)(gbase) + (voff)[_i]), (LAS unsigned*)(lds + (bufoff) + ldsw + _i * 8192), 16, 0, 0); } while (0)
; #define PG8_MMA(ai, bj, At, Bt) do { __builtin_amdgcn_s_setprio(1); _Pragma("unroll") for (int m = 0; m < 4; ++m) _Pragma("unroll") for (int n = 0; n < 2; ++n) _Pragma("unroll") for (int k = 0; k < 2; ++k) \
;     acc[ai][bj][m][n] = __builtin_amdgcn_mfma_f32_16x16x32_bf16(Bt[n][k], At[m][k], acc[ai][bj][m][n], 0, 0, 0); __builtin_amdgcn_s_setprio(0); } while (0)
; #define PG8_WAIT_V(n) asm volatile("s_waitcnt vmcnt(" #n ")" ::: "memory")
; #define PG8_BAR __builtin_amdgcn_s_barrier()
;   DI void operator()(const f32x4 (&acc)[2][2][4][2], const Unit& u, int wr, int wc, int fr, int fq) const {
;     const int col = u.pn * 128 + wc * 32 + 8 * fq;
;     float w0[8], w1[8], w2[8], bb[8];
; #pragma unroll
;     for (int e = 0; e < 8; ++e) { w0[e] = cw[col + e]; w1[e] = cw[5632 + col + e]; w2[e] = cw[2 * 5632 + col + e]; bb[e] = cb[col + e]; }
; #pragma unroll
;     for (int ai = 0; ai < 2; ++ai) {
;       const int row0 = u.pm * BM + ai * HALF + wr * 64, span = row0 >> 6;
;       float rsv[4];
; #pragma unroll
;       for (int m = 0; m < 4; ++m) rsv[m] = row_rstd(ssq, row0 + 16 * m + fr, fq);
; template <class Epi, class Sched = StaticOrder>
; DI void gemm_phase(LAS unsigned char* lds, const Gemm g, const Sched& S, const Epi& E) {
;     ...
;       PG8_STAGE(PG8_SB(1, 1), b3 + hstep, voffB);
;       PG8_WAIT_V(6); PG8_BAR; PG8_MMA(1, 1, At, B1); PG8_BAR;
	s_setprio 0
	s_add_u32 s46, s46, 0x80080
	s_addc_u32 s47, s47, 0
	s_add_i32 s48, s48, s60
	s_mov_b32 m0, s48
	s_nop 0
	global_load_lds_dwordx4 v164, s[46:47]
	s_add_i32 m0, s48, 0x2000
	s_nop 0
	global_load_lds_dwordx4 v160, s[46:47]
	ds_read_b128 v[64:67], v201
	ds_read_b128 v[68:71], v201 offset:1024
	ds_read_b128 v[72:75], v201 offset:2048
	ds_read_b128 v[76:79], v201 offset:3072
	s_waitcnt vmcnt(6)
	s_setprio 1
	s_barrier
	v_mfma_f32_16x16x32_bf16 v[56:59], v[216:219], v[80:83], v[56:59]
	v_mfma_f32_16x16x32_bf16 v[52:55], v[224:227], v[80:83], v[52:55]
	v_mfma_f32_16x16x32_bf16 v[40:43], v[216:219], v[92:95], v[40:43]
	v_mfma_f32_16x16x32_bf16 v[32:35], v[224:227], v[92:95], v[32:35]
	v_mfma_f32_16x16x32_bf16 v[24:27], v[216:219], v[180:183], v[24:27]
	v_mfma_f32_16x16x32_bf16 v[8:11], v[224:227], v[180:183], v[8:11]
	v_mfma_f32_16x16x32_bf16 v[4:7], v[216:219], v[188:191], v[4:7]
	v_mfma_f32_16x16x32_bf16 v[0:3], v[224:227], v[188:191], v[0:3]
	v_mfma_f32_16x16x32_bf16 v[56:59], v[220:223], v[84:87], v[56:59]
	v_mfma_f32_16x16x32_bf16 v[52:55], v[228:231], v[84:87], v[52:55]
	v_mfma_f32_16x16x32_bf16 v[40:43], v[220:223], v[96:99], v[40:43]
	v_mfma_f32_16x16x32_bf16 v[32:35], v[228:231], v[96:99], v[32:35]
	v_mfma_f32_16x16x32_bf16 v[24:27], v[220:223], v[184:187], v[24:27]
	v_mfma_f32_16x16x32_bf16 v[8:11], v[228:231], v[184:187], v[8:11]
	v_mfma_f32_16x16x32_bf16 v[4:7], v[220:223], v[192:195], v[4:7]
	v_mfma_f32_16x16x32_bf16 v[0:3], v[228:231], v[192:195], v[0:3]
	s_add_i32 s52, s52, 2
	s_add_u32 s14, s14, 0x100
	s_addc_u32 s15, s15, 0
	s_add_u32 s44, s44, 0x100
	s_addc_u32 s45, s45, 0
	s_cmp_gt_u32 s52, 29
	s_barrier
	s_setprio 0
	s_cbranch_scc0 .LBB0_811
	s_waitcnt lgkmcnt(0)
	s_lshl_b32 s35, s12, 8
	s_add_i32 s35, s35, s66
	v_or_b32_e32 v190, s35, v179
	v_ashrrev_i32_e32 v191, 31, v190
	v_lshlrev_b64 v[64:65], 7, v[190:191]
	v_or_b32_e32 v188, 16, v190
	v_lshl_add_u64 v[64:65], v[168:169], 0, v[64:65]
	v_ashrrev_i32_e32 v189, 31, v188
	global_load_dwordx4 v[192:195], v[64:65], off
	global_load_dwordx4 v[206:209], v[64:65], off offset:16
	v_lshlrev_b64 v[64:65], 7, v[188:189]
	v_lshl_add_u64 v[64:65], v[168:169], 0, v[64:65]
	global_load_dwordx4 v[212:215], v[64:65], off
	global_load_dwordx4 v[216:219], v[64:65], off offset:16
	v_or_b32_e32 v186, 32, v190
	v_ashrrev_i32_e32 v187, 31, v186
	v_lshlrev_b64 v[64:65], 7, v[186:187]
	v_or_b32_e32 v184, 48, v190
	v_lshl_add_u64 v[64:65], v[168:169], 0, v[64:65]
	v_ashrrev_i32_e32 v185, 31, v184
	global_load_dwordx4 v[220:223], v[64:65], off
	global_load_dwordx4 v[224:227], v[64:65], off offset:16
	v_lshlrev_b64 v[64:65], 7, v[184:185]
	v_lshl_add_u64 v[64:65], v[168:169], 0, v[64:65]
	global_load_dwordx4 v[228:231], v[64:65], off
	global_load_dwordx4 v[232:235], v[64:65], off offset:16
	v_lshl_or_b32 v180, s13, 7, v200
	v_and_b32_e32 v65, 64, v204
	v_xor_b32_e32 v64, 16, v204
	v_ashrrev_i32_e32 v181, 31, v180
	v_add_u32_e32 v65, 64, v65
	v_readlane_b32 s44, v243, 3
	v_xor_b32_e32 v66, 32, v204
	v_lshlrev_b64 v[182:183], 2, v[180:181]
	v_cmp_lt_i32_e32 vcc, v64, v65
	v_readlane_b32 s52, v243, 11
	v_readlane_b32 s53, v243, 12
	v_cndmask_b32_e32 v64, v204, v64, vcc
	v_cmp_lt_i32_e32 vcc, v66, v65
	v_lshl_add_u64 v[92:93], s[52:53], 0, v[182:183]
	v_readlane_b32 s54, v243, 13
	v_cndmask_b32_e32 v65, v204, v66, vcc
	v_add_co_u32_e32 v94, vcc, 0x5000, v92
	v_readlane_b32 s55, v243, 14
	s_nop 0
	v_addc_co_u32_e32 v95, vcc, 0, v93, vcc
	v_add_co_u32_e32 v96, vcc, 0xb000, v92
	v_lshl_add_u64 v[72:73], s[54:55], 0, v[182:183]
	v_lshl_add_u64 v[74:75], v[92:93], 0, s[26:27]
	v_lshl_add_u64 v[76:77], v[92:93], 0, s[28:29]
	v_addc_co_u32_e32 v97, vcc, 0, v93, vcc
	v_lshlrev_b32_e32 v187, 2, v64
	v_lshlrev_b32_e32 v185, 2, v65
	global_load_dwordx4 v[64:67], v[92:93], off offset:16
	global_load_dwordx4 v[80:83], v[92:93], off
	global_load_dwordx4 v[68:71], v[72:73], off offset:16
	global_load_dwordx4 v[84:87], v[72:73], off
	s_nop 0
	global_load_dwordx4 v[72:75], v[74:75], off offset:16
	s_nop 0
	global_load_dwordx4 v[76:79], v[76:77], off offset:16
	s_nop 0
	global_load_dwordx4 v[92:95], v[94:95], off offset:2048
	s_nop 0
	global_load_dwordx4 v[96:99], v[96:97], off
	v_mov_b32_e32 v211, 0
	v_mov_b32_e32 v205, 0
	v_readlane_b32 s45, v243, 4
	v_readlane_b32 s46, v243, 5
	v_readlane_b32 s47, v243, 6
	v_readlane_b32 s48, v243, 7
	v_readlane_b32 s49, v243, 8
	v_readlane_b32 s50, v243, 9
	v_readlane_b32 s51, v243, 10
	v_readlane_b32 s56, v243, 15
	v_readlane_b32 s57, v243, 16
	v_readlane_b32 s58, v243, 17
	v_readlane_b32 s59, v243, 18
	s_waitcnt vmcnt(0)
	v_mov_b32_e32 v196, v192
	v_mov_b32_e32 v197, v206
	v_mov_b32_e32 v206, v193
	v_mov_b32_e32 v192, v194
	v_mov_b32_e32 v193, v208
	v_mov_b32_e32 v208, v195
	v_pk_add_f32 v[194:195], v[196:197], v[206:207]
	v_pk_add_f32 v[192:193], v[192:193], v[208:209]
	v_mov_b32_e32 v196, v212
	v_mov_b32_e32 v197, v216
	v_mov_b32_e32 v216, v213
	v_mov_b32_e32 v206, v214
	v_mov_b32_e32 v207, v218
	v_mov_b32_e32 v218, v215
	v_pk_add_f32 v[192:193], v[194:195], v[192:193]
	v_pk_add_f32 v[194:195], v[196:197], v[216:217]
	v_pk_add_f32 v[196:197], v[206:207], v[218:219]
	v_mov_b32_e32 v208, v220
	v_pk_add_f32 v[194:195], v[194:195], v[196:197]
	v_mov_b32_e32 v197, v192
	v_mov_b32_e32 v196, v194
	v_mov_b32_e32 v192, v195
	v_pk_add_f32 v[192:193], v[196:197], v[192:193]
	ds_bpermute_b32 v195, v187, v193
	ds_bpermute_b32 v194, v187, v192
	v_mov_b32_e32 v209, v224
	v_mov_b32_e32 v224, v221
	v_mov_b32_e32 v212, v222
	v_mov_b32_e32 v213, v226
	s_waitcnt lgkmcnt(0)
; DI unsigned pack2(float lo, float hi) { f32x2 v = {lo, hi}; bf16v2 r = __builtin_convertvector(v, bf16v2); return __builtin_bit_cast(unsigned, r); }
; DI float silu_f(float x) { return x * sigmoid_f(x); }
; DI float dpp_ror1(float v) { return __int_as_float(__builtin_amdgcn_update_dpp(0, __float_as_int(v), 0x121, 0xf, 0xf, false)); }
; DI float dpp_ror2(float v) { return __int_as_float(__builtin_amdgcn_update_dpp(0, __float_as_int(v), 0x122, 0xf, 0xf, false)); }
;   DI void operator()(const f32x4 (&acc)[2][2][4][2], const Unit& u, int wr, int wc, int fr, int fq) const {
;     ...
;       for (int m = 0; m < 4; ++m) rsv[m] = row_rstd(ssq, row0 + 16 * m + fr, fq);
;       float p1[8], p2[8];
; #pragma unroll
;       for (int e = 0; e < 8; ++e) { p1[e] = 0.f; p2[e] = 0.f; }
; #pragma unroll
;       for (int m = 0; m < 4; ++m) {
;         float g[8], uu[8], a[8];
;         const float rs = rsv[m];
; #pragma unroll
;         for (int e = 0; e < 4; ++e) { g[e] = acc[ai][0][m][0][e] * rs; g[4 + e] = acc[ai][0][m][1][e] * rs; uu[e] = acc[ai][1][m][0][e] * rs; uu[4 + e] = acc[ai][1][m][1][e] * rs; }
; #pragma unroll
;         for (int e = 0; e < 8; ++e) {
;           const float x1 = dpp_ror1(g[e]), x2 = dpp_ror2(g[e]);
;           const float pr1 = (fr == 0) ? p1[e] : x1, pr2 = (fr < 2) ? p2[e] : x2;
;           a[e] = w2[e] * g[e] + w1[e] * pr1 + w0[e] * pr2 + bb[e];
;           p1[e] = x1; p2[e] = x2;
;         }
;         if (m == 0 && fr < 2) {
;           float* ha = headA + (size_t)(span * 2 + fr) * 5632 + col; float* hu = headU + (size_t)(span * 2 + fr) * 5632 + col;
;           *(f32x4*)ha = (f32x4){a[0], a[1], a[2], a[3]}; *(f32x4*)(ha + 4) = (f32x4){a[4], a[5], a[6], a[7]};
;           *(f32x4*)hu = (f32x4){uu[0], uu[1], uu[2], uu[3]}; *(f32x4*)(hu + 4) = (f32x4){uu[4], uu[5], uu[6], uu[7]};
;         } else {
;           u32x4 w;
;           w.x = pack2(silu_f(a[0]) * uu[0], silu_f(a[1]) * uu[1]);
;           w.y = pack2(silu_f(a[2]) * uu[2], silu_f(a[3]) * uu[3]);
;           w.z = pack2(silu_f(a[4]) * uu[4], silu_f(a[5]) * uu[5]);
;           w.w = pack2(silu_f(a[6]) * uu[6], silu_f(a[7]) * uu[7]);
;           *(u32x4*)(H + (size_t)(row0 + 16 * m + fr) * 5632 + col) = w;
	v_pk_add_f32 v[192:193], v[192:193], v[194:195]
	ds_bpermute_b32 v195, v185, v193
	ds_bpermute_b32 v194, v185, v192
	v_mov_b32_e32 v226, v223
	v_mov_b32_e32 v196, v228
	v_mov_b32_e32 v197, v232
	v_mov_b32_e32 v232, v229
	s_waitcnt lgkmcnt(0)
	v_pk_add_f32 v[192:193], v[192:193], v[194:195]
	v_mov_b32_e32 v206, v230
	v_pk_fma_f32 v[192:193], v[192:193], s[30:31], v[178:179] op_sel_hi:[1,0,0]
	v_mov_b32_e32 v207, v234
	v_mul_f32_e32 v189, 0x4b800000, v193
	v_cmp_gt_f32_e64 s[12:13], s74, v193
	v_mov_b32_e32 v234, v231
	v_pk_add_f32 v[208:209], v[208:209], v[224:225]
	v_cndmask_b32_e64 v189, v193, v189, s[12:13]
	v_rsq_f32_e32 v189, v189
	v_pk_add_f32 v[212:213], v[212:213], v[226:227]
	v_pk_add_f32 v[196:197], v[196:197], v[232:233]
	v_pk_add_f32 v[194:195], v[206:207], v[234:235]
	v_mul_f32_e32 v191, 0x45800000, v189
	v_cndmask_b32_e64 v220, v189, v191, s[12:13]
	v_pk_add_f32 v[208:209], v[208:209], v[212:213]
	v_pk_add_f32 v[194:195], v[196:197], v[194:195]
	v_pk_mul_f32 v[156:157], v[156:157], v[220:221] op_sel_hi:[1,0]
	v_mov_b32_e32 v216, 0
	v_mov_b32_e32 v218, 0
	v_mov_b32_e32 v196, v194
	v_mov_b32_e32 v197, v208
	v_mov_b32_e32 v208, v195
	v_mov_b32_dpp v216, v156 row_ror:1 row_mask:0xf bank_mask:0xf
	v_mov_b32_dpp v218, v157 row_ror:1 row_mask:0xf bank_mask:0xf
	v_pk_add_f32 v[194:195], v[196:197], v[208:209]
	v_cndmask_b32_e64 v207, v218, 0, s[0:1]
	v_cndmask_b32_e64 v206, v216, 0, s[0:1]
	v_pk_mul_f32 v[158:159], v[158:159], v[220:221] op_sel_hi:[1,0]
	v_mov_b32_e32 v212, 0
	v_mov_b32_e32 v214, 0
	ds_bpermute_b32 v197, v187, v195
	ds_bpermute_b32 v196, v187, v194
	v_mov_b32_e32 v215, 0
	v_mov_b32_e32 v217, 0
	v_pk_mul_f32 v[206:207], v[92:93], v[206:207]
	v_mov_b32_dpp v212, v158 row_ror:1 row_mask:0xf bank_mask:0xf
	v_mov_b32_dpp v214, v159 row_ror:1 row_mask:0xf bank_mask:0xf
	v_mov_b32_dpp v215, v156 row_ror:2 row_mask:0xf bank_mask:0xf
	v_mov_b32_dpp v217, v157 row_ror:2 row_mask:0xf bank_mask:0xf
	v_pk_fma_f32 v[156:157], v[96:97], v[156:157], v[206:207]
	v_mov_b32_e32 v213, 0
	v_cndmask_b32_e64 v207, v214, 0, s[0:1]
	v_cndmask_b32_e64 v206, v212, 0, s[0:1]
	v_cndmask_b32_e64 v209, v217, 0, s[4:5]
	v_cndmask_b32_e64 v208, v215, 0, s[4:5]
	v_mov_b32_dpp v211, v158 row_ror:2 row_mask:0xf bank_mask:0xf
	v_mov_b32_dpp v213, v159 row_ror:2 row_mask:0xf bank_mask:0xf
	v_pk_mul_f32 v[206:207], v[94:95], v[206:207]
	v_pk_fma_f32 v[156:157], v[80:81], v[208:209], v[156:157]
	v_cndmask_b32_e64 v209, v213, 0, s[4:5]
	v_cndmask_b32_e64 v208, v211, 0, s[4:5]
	v_pk_fma_f32 v[158:159], v[98:99], v[158:159], v[206:207]
	v_pk_mul_f32 v[144:145], v[144:145], v[220:221] op_sel_hi:[1,0]
	v_pk_fma_f32 v[158:159], v[82:83], v[208:209], v[158:159]
	v_mov_b32_e32 v207, 0
	v_mov_b32_e32 v209, 0
	v_pk_mul_f32 v[146:147], v[146:147], v[220:221] op_sel_hi:[1,0]
	v_mov_b32_e32 v191, 0
	s_waitcnt lgkmcnt(0)
	v_pk_add_f32 v[194:195], v[194:195], v[196:197]
	v_mov_b32_dpp v207, v144 row_ror:1 row_mask:0xf bank_mask:0xf
	v_mov_b32_dpp v209, v145 row_ror:1 row_mask:0xf bank_mask:0xf
	v_mov_b32_dpp v191, v146 row_ror:1 row_mask:0xf bank_mask:0xf
	v_mov_b32_dpp v205, v147 row_ror:1 row_mask:0xf bank_mask:0xf
	ds_bpermute_b32 v197, v185, v195
	ds_bpermute_b32 v196, v185, v194
	v_pk_mul_f32 v[152:153], v[152:153], v[220:221] op_sel_hi:[1,0]
	v_pk_mul_f32 v[148:149], v[148:149], v[220:221] op_sel_hi:[1,0]
	v_pk_mul_f32 v[154:155], v[154:155], v[220:221] op_sel_hi:[1,0]
	v_pk_mul_f32 v[150:151], v[150:151], v[220:221] op_sel_hi:[1,0]
	v_mov_b32_e32 v206, 0
	v_mov_b32_e32 v208, 0
	v_cndmask_b32_e64 v223, v209, 0, s[0:1]
	v_cndmask_b32_e64 v222, v207, 0, s[0:1]
	v_mov_b32_e32 v189, 0
	v_mov_b32_e32 v193, 0
	v_cndmask_b32_e64 v221, v205, 0, s[0:1]
	v_cndmask_b32_e64 v220, v191, 0, s[0:1]
	v_mov_b32_dpp v206, v144 row_ror:2 row_mask:0xf bank_mask:0xf
	v_mov_b32_dpp v208, v145 row_ror:2 row_mask:0xf bank_mask:0xf
	v_pk_mul_f32 v[222:223], v[72:73], v[222:223]
	v_mov_b32_dpp v189, v146 row_ror:2 row_mask:0xf bank_mask:0xf
	v_mov_b32_dpp v193, v147 row_ror:2 row_mask:0xf bank_mask:0xf
	v_pk_mul_f32 v[220:221], v[74:75], v[220:221]
	v_cndmask_b32_e64 v225, v208, 0, s[4:5]
	v_cndmask_b32_e64 v224, v206, 0, s[4:5]
	v_pk_fma_f32 v[144:145], v[76:77], v[144:145], v[222:223]
	v_cndmask_b32_e64 v223, v193, 0, s[4:5]
	v_cndmask_b32_e64 v222, v189, 0, s[4:5]
	v_pk_fma_f32 v[146:147], v[78:79], v[146:147], v[220:221]
	v_pk_fma_f32 v[144:145], v[64:65], v[224:225], v[144:145]
	v_pk_fma_f32 v[146:147], v[66:67], v[222:223], v[146:147]
	v_cmp_gt_f32_e32 vcc, s74, v192
	v_pk_add_f32 v[156:157], v[84:85], v[156:157]
	v_pk_add_f32 v[158:159], v[86:87], v[158:159]
	v_pk_add_f32 v[144:145], v[68:69], v[144:145]
	v_pk_add_f32 v[146:147], v[70:71], v[146:147]
	s_and_saveexec_b64 s[12:13], s[10:11]
	s_xor_b64 s[12:13], exec, s[12:13]
	s_cbranch_execz .LBB0_814
	v_mul_f32_e32 v219, 0xbfb8aa3b, v156
	v_exp_f32_e32 v219, v219
	v_mul_f32_e32 v220, 0xbfb8aa3b, v157
	v_exp_f32_e32 v220, v220
	v_mul_f32_e32 v222, 0xbfb8aa3b, v159
	v_add_f32_e32 v219, 1.0, v219
	v_exp_f32_e32 v223, v222
	v_add_f32_e32 v221, 1.0, v220
	v_rcp_f32_e32 v220, v219
	v_mul_f32_e32 v219, 0xbfb8aa3b, v158
	v_exp_f32_e32 v219, v219
	v_rcp_f32_e32 v221, v221
	v_add_f32_e32 v219, 1.0, v219
	v_rcp_f32_e32 v222, v219
	v_add_f32_e32 v219, 1.0, v223
	v_rcp_f32_e32 v223, v219
	v_pk_mul_f32 v[156:157], v[156:157], v[220:221]
	s_nop 0
	v_pk_mul_f32 v[152:153], v[152:153], v[156:157]
	v_pk_mul_f32 v[156:157], v[158:159], v[222:223]
	v_cvt_pk_bf16_f32 v152, v152, v153
	v_mul_f32_e32 v153, 0xbfb8aa3b, v144
	v_pk_mul_f32 v[154:155], v[154:155], v[156:157]
	v_exp_f32_e32 v156, v153
	v_mul_f32_e32 v153, 0xbfb8aa3b, v145
	v_exp_f32_e32 v157, v153
	v_cvt_pk_bf16_f32 v153, v154, v155
	v_add_f32_e32 v154, 1.0, v156
	v_mul_f32_e32 v156, 0xbfb8aa3b, v146
	v_add_f32_e32 v155, 1.0, v157
	v_mul_f32_e32 v157, 0xbfb8aa3b, v147
	v_exp_f32_e32 v156, v156
	v_exp_f32_e32 v157, v157
	v_rcp_f32_e32 v154, v154
	v_rcp_f32_e32 v155, v155
	v_add_f32_e32 v156, 1.0, v156
	v_add_f32_e32 v157, 1.0, v157
	v_rcp_f32_e32 v156, v156
	v_rcp_f32_e32 v157, v157
	v_pk_mul_f32 v[144:145], v[144:145], v[154:155]
	s_nop 0
	v_pk_mul_f32 v[144:145], v[148:149], v[144:145]
	s_nop 0
	v_cvt_pk_bf16_f32 v154, v144, v145
	v_pk_mul_f32 v[144:145], v[146:147], v[156:157]
	s_nop 0
	v_pk_mul_f32 v[144:145], v[150:151], v[144:145]
	s_nop 0
	v_cvt_pk_bf16_f32 v155, v144, v145
	v_mov_b64_e32 v[144:145], s[16:17]
	v_mad_i64_i32 v[144:145], s[14:15], v190, s75, v[144:145]
	v_lshl_add_u64 v[144:145], v[180:181], 1, v[144:145]
	global_store_dwordx4 v[144:145], v[152:155], off

; #define PG8_STAGE(bufoff, gbase, voff) do { _Pragma("unroll") for (int _i = 0; _i < 2; ++_i) \
;     __builtin_amdgcn_global_load_lds((const unsigned*)((const char*)(gbase) + (voff)[_i]), (LAS unsigned*)(lds + (bufoff) + ldsw + _i * 8192), 16, 0, 0); } while (0)
; #define PG8_LDA(dst, b, h) do { _Pragma("unroll") for (int m = 0; m < 4; ++m) _Pragma("unroll") for (int k = 0; k < 2; ++k) dst[m][k] = *(const LAS bf16x8*)(lds + PG8_SA(b, h) + aoff + m * 2048 + k * 1024); } while (0)
; #define PG8_LDB(dst, b, h) do { _Pragma("unroll") for (int n = 0; n < 2; ++n) _Pragma("unroll") for (int k = 0; k < 2; ++k) dst[n][k] = *(const LAS bf16x8*)(lds + PG8_SB(b, h) + boff + n * 2048 + k * 1024); } while (0)
; #define PG8_MMA(ai, bj, At, Bt) do { __builtin_amdgcn_s_setprio(1); _Pragma("unroll") for (int m = 0; m < 4; ++m) _Pragma("unroll") for (int n = 0; n < 2; ++n) _Pragma("unroll") for (int k = 0; k < 2; ++k) \
;     acc[ai][bj][m][n] = __builtin_amdgcn_mfma_f32_16x16x32_bf16(Bt[n][k], At[m][k], acc[ai][bj][m][n], 0, 0, 0); __builtin_amdgcn_s_setprio(0); } while (0)
; #define PG8_WAIT_V(n) asm volatile("s_waitcnt vmcnt(" #n ")" ::: "memory")
; template <class Epi, class Sched = StaticOrder>
; DI void gemm_phase(LAS unsigned char* lds, const Gemm g, const Sched& S, const Epi& E) {
;     ...
;     for (int t = 0; t < nt; t += 2) {
;       const bool last = (t == nt - 2);
;       const char* a1 = cA + (size_t)(t + 1) * kstep;
;       const char* a2 = last ? nA : cA + (size_t)(t + 2) * kstep; const char* b2 = last ? nB : cB + (size_t)(t + 2) * kstep;
;       const char* a3 = a2 + kstep; const char* b3 = b2 + kstep;
;       PG8_LDB(B0, 0, 0); PG8_SCHED; PG8_LDA(At, 0, 0); PG8_STAGE(PG8_SA(1, 1), a1 + hstep, voffA);
;       PG8_WAIT_L(8); PG8_BAR; PG8_WAIT_L(0); PG8_MMA(0, 0, At, B0); PG8_BAR; PG8_SCHED;
;       PG8_LDB(B1, 0, 1); PG8_STAGE(PG8_SB(0, 0), b2, voffB);
;       PG8_BAR; PG8_WAIT_L(0); PG8_MMA(0, 1, At, B1); PG8_BAR;
;       PG8_LDA(At, 0, 1); PG8_STAGE(PG8_SA(0, 0), a2, voffA);
;       PG8_BAR; PG8_WAIT_L(0); PG8_MMA(1, 0, At, B0); PG8_BAR; PG8_SCHED;
;       PG8_STAGE(PG8_SB(0, 1), b2 + hstep, voffB);
;       PG8_WAIT_V(6); PG8_BAR; PG8_MMA(1, 1, At, B1); PG8_BAR;
;       PG8_LDB(B0, 1, 0); PG8_SCHED; PG8_LDA(At, 1, 0); PG8_STAGE(PG8_SA(0, 1), a2 + hstep, voffA);
;       PG8_WAIT_L(8); PG8_BAR; PG8_WAIT_L(0); PG8_MMA(0, 0, At, B0); PG8_BAR; PG8_SCHED;
.LBB0_961:
	s_add_u32 s20, s18, 0xffea0080
	s_addc_u32 s21, s19, -1
	s_cmpk_eq_i32 s44, 0x54
	s_cselect_b32 s23, s5, s21
	s_cselect_b32 s22, s4, s20
	s_cselect_b32 s21, s7, s43
	s_cselect_b32 s20, s6, s42
	s_add_i32 m0, s31, 0xc000
	ds_read_b128 v[144:147], v215
	ds_read_b128 v[148:151], v215 offset:1024
	ds_read_b128 v[152:155], v215 offset:2048
	ds_read_b128 v[156:159], v215 offset:3072
	ds_read_b128 v[160:163], v215 offset:4096
	ds_read_b128 v[164:167], v215 offset:5120
	ds_read_b128 v[168:171], v215 offset:6144
	ds_read_b128 v[172:175], v215 offset:7168
	global_load_lds_dwordx4 v184, s[18:19]
	s_add_i32 m0, s31, 0xe000
	s_nop 0
	global_load_lds_dwordx4 v186, s[18:19]
	s_waitcnt lgkmcnt(0)
	s_setprio 1
	s_barrier
	v_mfma_f32_16x16x32_bf16 v[124:127], v[128:131], v[144:147], v[124:127]
	v_mfma_f32_16x16x32_bf16 v[120:123], v[136:139], v[144:147], v[120:123]
	v_mfma_f32_16x16x32_bf16 v[108:111], v[128:131], v[152:155], v[108:111]
	v_mfma_f32_16x16x32_bf16 v[104:107], v[136:139], v[152:155], v[104:107]
	v_mfma_f32_16x16x32_bf16 v[92:95], v[128:131], v[160:163], v[92:95]
	v_mfma_f32_16x16x32_bf16 v[88:91], v[136:139], v[160:163], v[88:91]
	v_mfma_f32_16x16x32_bf16 v[76:79], v[128:131], v[168:171], v[76:79]
	v_mfma_f32_16x16x32_bf16 v[72:75], v[136:139], v[168:171], v[72:75]
	v_mfma_f32_16x16x32_bf16 v[124:127], v[132:135], v[148:151], v[124:127]
	v_mfma_f32_16x16x32_bf16 v[120:123], v[140:143], v[148:151], v[120:123]
	v_mfma_f32_16x16x32_bf16 v[108:111], v[132:135], v[156:159], v[108:111]
	v_mfma_f32_16x16x32_bf16 v[104:107], v[140:143], v[156:159], v[104:107]
	v_mfma_f32_16x16x32_bf16 v[92:95], v[132:135], v[164:167], v[92:95]
	v_mfma_f32_16x16x32_bf16 v[88:91], v[140:143], v[164:167], v[88:91]
	v_mfma_f32_16x16x32_bf16 v[76:79], v[132:135], v[172:175], v[76:79]
	v_mfma_f32_16x16x32_bf16 v[72:75], v[140:143], v[172:175], v[72:75]
	s_barrier
	s_setprio 0
	s_add_i32 s45, s46, s30
	s_add_u32 s98, s20, 0x80
	s_addc_u32 s99, s21, 0
	s_mov_b32 m0, s45
	ds_read_b128 v[192:195], v216
	ds_read_b128 v[196:199], v216 offset:1024
	ds_read_b128 v[200:203], v216 offset:2048
	ds_read_b128 v[204:207], v216 offset:3072
	global_load_lds_dwordx4 v178, s[20:21]
	s_add_i32 m0, s45, 0x2000
	s_nop 0
	global_load_lds_dwordx4 v182, s[20:21]
	s_waitcnt lgkmcnt(0)
	s_setprio 1
	s_barrier
	v_mfma_f32_16x16x32_bf16 v[116:119], v[192:195], v[144:147], v[116:119]
	v_mfma_f32_16x16x32_bf16 v[112:115], v[200:203], v[144:147], v[112:115]
	v_mfma_f32_16x16x32_bf16 v[100:103], v[192:195], v[152:155], v[100:103]
	v_mfma_f32_16x16x32_bf16 v[96:99], v[200:203], v[152:155], v[96:99]
	v_mfma_f32_16x16x32_bf16 v[84:87], v[192:195], v[160:163], v[84:87]
	v_mfma_f32_16x16x32_bf16 v[80:83], v[200:203], v[160:163], v[80:83]
	v_mfma_f32_16x16x32_bf16 v[68:71], v[192:195], v[168:171], v[68:71]
	v_mfma_f32_16x16x32_bf16 v[64:67], v[200:203], v[168:171], v[64:67]
	v_mfma_f32_16x16x32_bf16 v[116:119], v[196:199], v[148:151], v[116:119]
	v_mfma_f32_16x16x32_bf16 v[112:115], v[204:207], v[148:151], v[112:115]
	v_mfma_f32_16x16x32_bf16 v[100:103], v[196:199], v[156:159], v[100:103]
	v_mfma_f32_16x16x32_bf16 v[96:99], v[204:207], v[156:159], v[96:99]
	v_mfma_f32_16x16x32_bf16 v[84:87], v[196:199], v[164:167], v[84:87]
	v_mfma_f32_16x16x32_bf16 v[80:83], v[204:207], v[164:167], v[80:83]
	v_mfma_f32_16x16x32_bf16 v[68:71], v[196:199], v[172:175], v[68:71]
	v_mfma_f32_16x16x32_bf16 v[64:67], v[204:207], v[172:175], v[64:67]
	s_barrier
	s_setprio 0
	s_mov_b32 m0, s31
	s_add_u32 s100, s22, 0x80
	s_addc_u32 s101, s23, 0
	ds_read_b128 v[144:147], v215 offset:16384
	ds_read_b128 v[148:151], v215 offset:17408
	ds_read_b128 v[152:155], v215 offset:18432
	ds_read_b128 v[156:159], v215 offset:19456
	ds_read_b128 v[160:163], v215 offset:20480
	ds_read_b128 v[164:167], v215 offset:21504
	ds_read_b128 v[168:171], v215 offset:22528
	ds_read_b128 v[172:175], v215 offset:23552
	global_load_lds_dwordx4 v176, s[22:23]
	s_mov_b32 m0, s33
	s_nop 0
	global_load_lds_dwordx4 v180, s[22:23]
	s_waitcnt vmcnt(10)
	s_waitcnt lgkmcnt(0)
	s_setprio 1
	s_barrier
	v_mfma_f32_16x16x32_bf16 v[60:63], v[128:131], v[144:147], v[60:63]
	v_mfma_f32_16x16x32_bf16 v[56:59], v[136:139], v[144:147], v[56:59]
	v_mfma_f32_16x16x32_bf16 v[44:47], v[128:131], v[152:155], v[44:47]
	v_mfma_f32_16x16x32_bf16 v[40:43], v[136:139], v[152:155], v[40:43]
	v_mfma_f32_16x16x32_bf16 v[28:31], v[128:131], v[160:163], v[28:31]
	v_mfma_f32_16x16x32_bf16 v[24:27], v[136:139], v[160:163], v[24:27]
	v_mfma_f32_16x16x32_bf16 v[12:15], v[128:131], v[168:171], v[12:15]
	v_mfma_f32_16x16x32_bf16 v[8:11], v[136:139], v[168:171], v[8:11]
	v_mfma_f32_16x16x32_bf16 v[60:63], v[132:135], v[148:151], v[60:63]
	v_mfma_f32_16x16x32_bf16 v[56:59], v[140:143], v[148:151], v[56:59]
	v_mfma_f32_16x16x32_bf16 v[44:47], v[132:135], v[156:159], v[44:47]
	v_mfma_f32_16x16x32_bf16 v[40:43], v[140:143], v[156:159], v[40:43]
	v_mfma_f32_16x16x32_bf16 v[28:31], v[132:135], v[164:167], v[28:31]
	v_mfma_f32_16x16x32_bf16 v[24:27], v[140:143], v[164:167], v[24:27]
	v_mfma_f32_16x16x32_bf16 v[12:15], v[132:135], v[172:175], v[12:15]
	v_mfma_f32_16x16x32_bf16 v[8:11], v[140:143], v[172:175], v[8:11]
	s_barrier
	s_setprio 0
	s_add_u32 s52, s20, 0x160000
	s_addc_u32 s53, s21, 0
	s_add_i32 s45, s47, s30
	s_mov_b32 m0, s45
	s_nop 0
	global_load_lds_dwordx4 v178, s[52:53]
	s_add_i32 m0, s45, 0x2000
	s_nop 0
	global_load_lds_dwordx4 v182, s[52:53]
	s_add_i32 s45, 0, 0x18000
	v_add_u32_e32 v140, s45, v212
	ds_read_b128 v[128:131], v140
	ds_read_b128 v[132:135], v140 offset:1024
	ds_read_b128 v[136:139], v140 offset:2048
	ds_read_b128 v[140:143], v140 offset:3072
	s_waitcnt vmcnt(6)
	s_setprio 1
	s_barrier
; #define PG8_STAGE(bufoff, gbase, voff) do { _Pragma("unroll") for (int _i = 0; _i < 2; ++_i) \
;     __builtin_amdgcn_global_load_lds((const unsigned*)((const char*)(gbase) + (voff)[_i]), (LAS unsigned*)(lds + (bufoff) + ldsw + _i * 8192), 16, 0, 0); } while (0)
; #define PG8_LDA(dst, b, h) do { _Pragma("unroll") for (int m = 0; m < 4; ++m) _Pragma("unroll") for (int k = 0; k < 2; ++k) dst[m][k] = *(const LAS bf16x8*)(lds + PG8_SA(b, h) + aoff + m * 2048 + k * 1024); } while (0)
; #define PG8_LDB(dst, b, h) do { _Pragma("unroll") for (int n = 0; n < 2; ++n) _Pragma("unroll") for (int k = 0; k < 2; ++k) dst[n][k] = *(const LAS bf16x8*)(lds + PG8_SB(b, h) + boff + n * 2048 + k * 1024); } while (0)
; #define PG8_MMA(ai, bj, At, Bt) do { __builtin_amdgcn_s_setprio(1); _Pragma("unroll") for (int m = 0; m < 4; ++m) _Pragma("unroll") for (int n = 0; n < 2; ++n) _Pragma("unroll") for (int k = 0; k < 2; ++k) \
;     acc[ai][bj][m][n] = __builtin_amdgcn_mfma_f32_16x16x32_bf16(Bt[n][k], At[m][k], acc[ai][bj][m][n], 0, 0, 0); __builtin_amdgcn_s_setprio(0); } while (0)
; #define PG8_WAIT_V(n) asm volatile("s_waitcnt vmcnt(" #n ")" ::: "memory")
; #define PG8_WAIT_L(n) asm volatile("s_waitcnt lgkmcnt(" #n ")" ::: "memory")
; #define PG8_BAR __builtin_amdgcn_s_barrier()
; #define PG8_SCHED __builtin_amdgcn_sched_barrier(0)
; template <class Epi, class Sched = StaticOrder>
; DI void gemm_phase(LAS unsigned char* lds, const Gemm g, const Sched& S, const Epi& E) {
;     ...
;       PG8_WAIT_V(6); PG8_BAR; PG8_MMA(1, 1, At, B1); PG8_BAR;
;       PG8_LDB(B0, 1, 0); PG8_SCHED; PG8_LDA(At, 1, 0); PG8_STAGE(PG8_SA(0, 1), a2 + hstep, voffA);
;       PG8_WAIT_L(8); PG8_BAR; PG8_WAIT_L(0); PG8_MMA(0, 0, At, B0); PG8_BAR; PG8_SCHED;
;       PG8_LDB(B1, 1, 1); PG8_STAGE(PG8_SB(1, 0), b3, voffB);
;       PG8_BAR; PG8_WAIT_L(0); PG8_MMA(0, 1, At, B1); PG8_BAR;
;       PG8_LDA(At, 1, 1); PG8_STAGE(PG8_SA(1, 0), a3, voffA);
;       PG8_BAR; PG8_WAIT_L(0); PG8_MMA(1, 0, At, B0); PG8_BAR; PG8_SCHED;
	v_mfma_f32_16x16x32_bf16 v[52:55], v[192:195], v[144:147], v[52:55]
	v_mfma_f32_16x16x32_bf16 v[48:51], v[200:203], v[144:147], v[48:51]
	v_mfma_f32_16x16x32_bf16 v[36:39], v[192:195], v[152:155], v[36:39]
	v_mfma_f32_16x16x32_bf16 v[32:35], v[200:203], v[152:155], v[32:35]
	v_mfma_f32_16x16x32_bf16 v[20:23], v[192:195], v[160:163], v[20:23]
	v_mfma_f32_16x16x32_bf16 v[16:19], v[200:203], v[160:163], v[16:19]
	v_mfma_f32_16x16x32_bf16 v[4:7], v[192:195], v[168:171], v[4:7]
	v_mfma_f32_16x16x32_bf16 v[0:3], v[200:203], v[168:171], v[0:3]
	v_mfma_f32_16x16x32_bf16 v[52:55], v[196:199], v[148:151], v[52:55]
	v_mfma_f32_16x16x32_bf16 v[48:51], v[204:207], v[148:151], v[48:51]
	v_mfma_f32_16x16x32_bf16 v[36:39], v[196:199], v[156:159], v[36:39]
	v_mfma_f32_16x16x32_bf16 v[32:35], v[204:207], v[156:159], v[32:35]
	v_mfma_f32_16x16x32_bf16 v[20:23], v[196:199], v[164:167], v[20:23]
	v_mfma_f32_16x16x32_bf16 v[16:19], v[204:207], v[164:167], v[16:19]
	v_mfma_f32_16x16x32_bf16 v[4:7], v[196:199], v[172:175], v[4:7]
	v_mfma_f32_16x16x32_bf16 v[0:3], v[204:207], v[172:175], v[0:3]
	s_barrier
	s_setprio 0
	s_add_u32 s22, s22, 0x160000
	s_addc_u32 s23, s23, 0
	s_mov_b32 m0, s34
	ds_read_b128 v[144:147], v215 offset:32768
	ds_read_b128 v[148:151], v215 offset:33792
	ds_read_b128 v[152:155], v215 offset:34816
	ds_read_b128 v[156:159], v215 offset:35840
	ds_read_b128 v[160:163], v215 offset:36864
	ds_read_b128 v[164:167], v215 offset:37888
	ds_read_b128 v[168:171], v215 offset:38912
	ds_read_b128 v[172:175], v215 offset:39936
	global_load_lds_dwordx4 v176, s[22:23]
	s_mov_b32 m0, s35
	s_nop 0
	global_load_lds_dwordx4 v180, s[22:23]
	s_waitcnt lgkmcnt(0)
	s_setprio 1
	s_barrier
	v_mfma_f32_16x16x32_bf16 v[124:127], v[128:131], v[144:147], v[124:127]
	v_mfma_f32_16x16x32_bf16 v[120:123], v[136:139], v[144:147], v[120:123]
	v_mfma_f32_16x16x32_bf16 v[108:111], v[128:131], v[152:155], v[108:111]
	v_mfma_f32_16x16x32_bf16 v[104:107], v[136:139], v[152:155], v[104:107]
	v_mfma_f32_16x16x32_bf16 v[92:95], v[128:131], v[160:163], v[92:95]
	v_mfma_f32_16x16x32_bf16 v[88:91], v[136:139], v[160:163], v[88:91]
	v_mfma_f32_16x16x32_bf16 v[76:79], v[128:131], v[168:171], v[76:79]
	v_mfma_f32_16x16x32_bf16 v[72:75], v[136:139], v[168:171], v[72:75]
	v_mfma_f32_16x16x32_bf16 v[124:127], v[132:135], v[148:151], v[124:127]
	v_mfma_f32_16x16x32_bf16 v[120:123], v[140:143], v[148:151], v[120:123]
	v_mfma_f32_16x16x32_bf16 v[108:111], v[132:135], v[156:159], v[108:111]
	v_mfma_f32_16x16x32_bf16 v[104:107], v[140:143], v[156:159], v[104:107]
	v_mfma_f32_16x16x32_bf16 v[92:95], v[132:135], v[164:167], v[92:95]
	v_mfma_f32_16x16x32_bf16 v[88:91], v[140:143], v[164:167], v[88:91]
	v_mfma_f32_16x16x32_bf16 v[76:79], v[132:135], v[172:175], v[76:79]
	v_mfma_f32_16x16x32_bf16 v[72:75], v[140:143], v[172:175], v[72:75]
	s_barrier
	s_setprio 0
	s_add_i32 s22, 0, 0x1c000
	s_add_i32 s23, s45, s30
	v_add_u32_e32 v204, s22, v212
	s_mov_b32 m0, s23
	ds_read_b128 v[192:195], v204
	ds_read_b128 v[196:199], v204 offset:1024
	ds_read_b128 v[200:203], v204 offset:2048
	ds_read_b128 v[204:207], v204 offset:3072
	global_load_lds_dwordx4 v178, s[98:99]
	s_add_i32 m0, s23, 0x2000
	s_nop 0
	global_load_lds_dwordx4 v182, s[98:99]
	s_waitcnt lgkmcnt(0)
	s_setprio 1
	s_barrier
	v_mfma_f32_16x16x32_bf16 v[116:119], v[192:195], v[144:147], v[116:119]
	v_mfma_f32_16x16x32_bf16 v[112:115], v[200:203], v[144:147], v[112:115]
	v_mfma_f32_16x16x32_bf16 v[100:103], v[192:195], v[152:155], v[100:103]
	v_mfma_f32_16x16x32_bf16 v[96:99], v[200:203], v[152:155], v[96:99]
	v_mfma_f32_16x16x32_bf16 v[84:87], v[192:195], v[160:163], v[84:87]
	v_mfma_f32_16x16x32_bf16 v[80:83], v[200:203], v[160:163], v[80:83]
	v_mfma_f32_16x16x32_bf16 v[68:71], v[192:195], v[168:171], v[68:71]
	v_mfma_f32_16x16x32_bf16 v[64:67], v[200:203], v[168:171], v[64:67]
	v_mfma_f32_16x16x32_bf16 v[116:119], v[196:199], v[148:151], v[116:119]
	v_mfma_f32_16x16x32_bf16 v[112:115], v[204:207], v[148:151], v[112:115]
	v_mfma_f32_16x16x32_bf16 v[100:103], v[196:199], v[156:159], v[100:103]
	v_mfma_f32_16x16x32_bf16 v[96:99], v[204:207], v[156:159], v[96:99]
	v_mfma_f32_16x16x32_bf16 v[84:87], v[196:199], v[164:167], v[84:87]
	v_mfma_f32_16x16x32_bf16 v[80:83], v[204:207], v[164:167], v[80:83]
	v_mfma_f32_16x16x32_bf16 v[68:71], v[196:199], v[172:175], v[68:71]
	v_mfma_f32_16x16x32_bf16 v[64:67], v[204:207], v[172:175], v[64:67]
	s_barrier
	s_setprio 0
	s_mov_b32 m0, s37
	ds_read_b128 v[144:147], v215 offset:49152
	ds_read_b128 v[148:151], v215 offset:50176
	ds_read_b128 v[152:155], v215 offset:51200
	ds_read_b128 v[156:159], v215 offset:52224
	ds_read_b128 v[160:163], v215 offset:53248
	ds_read_b128 v[164:167], v215 offset:54272
	ds_read_b128 v[168:171], v215 offset:55296
	ds_read_b128 v[172:175], v215 offset:56320
	global_load_lds_dwordx4 v176, s[100:101]
	s_mov_b32 m0, s38
	s_nop 0
	global_load_lds_dwordx4 v180, s[100:101]
	s_waitcnt vmcnt(10)
	s_waitcnt lgkmcnt(0)
	s_setprio 1
	s_barrier
	v_mfma_f32_16x16x32_bf16 v[60:63], v[128:131], v[144:147], v[60:63]
	v_mfma_f32_16x16x32_bf16 v[56:59], v[136:139], v[144:147], v[56:59]
	v_mfma_f32_16x16x32_bf16 v[44:47], v[128:131], v[152:155], v[44:47]
	v_mfma_f32_16x16x32_bf16 v[40:43], v[136:139], v[152:155], v[40:43]
	v_mfma_f32_16x16x32_bf16 v[28:31], v[128:131], v[160:163], v[28:31]
	v_mfma_f32_16x16x32_bf16 v[24:27], v[136:139], v[160:163], v[24:27]
	v_mfma_f32_16x16x32_bf16 v[12:15], v[128:131], v[168:171], v[12:15]
	v_mfma_f32_16x16x32_bf16 v[8:11], v[136:139], v[168:171], v[8:11]
	v_mfma_f32_16x16x32_bf16 v[60:63], v[132:135], v[148:151], v[60:63]
	v_mfma_f32_16x16x32_bf16 v[56:59], v[140:143], v[148:151], v[56:59]
	v_mfma_f32_16x16x32_bf16 v[44:47], v[132:135], v[156:159], v[44:47]
	v_mfma_f32_16x16x32_bf16 v[40:43], v[140:143], v[156:159], v[40:43]
	v_mfma_f32_16x16x32_bf16 v[28:31], v[132:135], v[164:167], v[28:31]
	v_mfma_f32_16x16x32_bf16 v[24:27], v[140:143], v[164:167], v[24:27]
	v_mfma_f32_16x16x32_bf16 v[12:15], v[132:135], v[172:175], v[12:15]
	v_mfma_f32_16x16x32_bf16 v[8:11], v[140:143], v[172:175], v[8:11]
	s_barrier
; DI unsigned pack2(float lo, float hi) { f32x2 v = {lo, hi}; bf16v2 r = __builtin_convertvector(v, bf16v2); return __builtin_bit_cast(unsigned, r); }
; #define PG8_STAGE(bufoff, gbase, voff) do { _Pragma("unroll") for (int _i = 0; _i < 2; ++_i) \
;     __builtin_amdgcn_global_load_lds((const unsigned*)((const char*)(gbase) + (voff)[_i]), (LAS unsigned*)(lds + (bufoff) + ldsw + _i * 8192), 16, 0, 0); } while (0)
; #define PG8_WAIT_V(n) asm volatile("s_waitcnt vmcnt(" #n ")" ::: "memory")
; #define PG8_BAR __builtin_amdgcn_s_barrier()
;   DI void operator()(const f32x4 (&acc)[2][2][4][2], const Unit& u, int wr, int wc, int fr, int fq) const {
;     const int row0 = u.pm * BM + wr * 64 + fr, col0 = u.pn * BM + wc * 32 + 8 * fq;
; #pragma unroll
;     for (int ai = 0; ai < 2; ++ai) {
;       f32x4 bv[4][2][2];
; #pragma unroll
;       for (int m = 0; m < 4; ++m)
; #pragma unroll
;         for (int bj = 0; bj < 2; ++bj) {
;           const float* bp = base + (size_t)(row0 + ai * HALF + m * 16) * 2048 + col0 + bj * HALF;
;           bv[m][bj][0] = *(const f32x4*)bp; bv[m][bj][1] = *(const f32x4*)(bp + 4);
;         }
; #pragma unroll
;       for (int m = 0; m < 4; ++m) {
;         const int row = row0 + ai * HALF + m * 16;
;         const size_t off = (size_t)row * 2048 + col0;
;         float ss = 0.f;
; #pragma unroll
;         for (int bj = 0; bj < 2; ++bj) {
;           const f32x4 v0 = acc[ai][bj][m][0] + bv[m][bj][0], v1 = acc[ai][bj][m][1] + bv[m][bj][1];
;           *(f32x4*)(C + off + bj * HALF) = v0; *(f32x4*)(C + off + bj * HALF + 4) = v1;
;           if (xb) {
;             u32x4 w; w.x = pack2(v0[0], v0[1]); w.y = pack2(v0[2], v0[3]); w.z = pack2(v1[0], v1[1]); w.w = pack2(v1[2], v1[3]);
;             *(u32x4*)(xb + off + bj * HALF) = w;
;             ss += v0[0] * v0[0] + v0[1] * v0[1] + v0[2] * v0[2] + v0[3] * v0[3] + v1[0] * v1[0] + v1[1] * v1[1] + v1[2] * v1[2] + v1[3] * v1[3];
;           }
;         }
;         if (xb) {
;           ss += __shfl_xor(ss, 16); ss += __shfl_xor(ss, 32);
;           if (fq == 0) ssq[(size_t)row * 32 + u.pn * 4 + wc] = ss;
; template <class Epi, class Sched = StaticOrder>
; DI void gemm_phase(LAS unsigned char* lds, const Gemm g, const Sched& S, const Epi& E) {
;     ...
;       PG8_STAGE(PG8_SB(1, 1), b3 + hstep, voffB);
;       PG8_WAIT_V(6); PG8_BAR; PG8_MMA(1, 1, At, B1); PG8_BAR;
	s_setprio 0
	s_add_u32 s20, s20, 0x160080
	s_addc_u32 s21, s21, 0
	s_add_i32 s22, s22, s30
	s_mov_b32 m0, s22
	s_nop 0
	global_load_lds_dwordx4 v178, s[20:21]
	s_add_i32 m0, s22, 0x2000
	s_nop 0
	global_load_lds_dwordx4 v182, s[20:21]
	ds_read_b128 v[128:131], v214
	ds_read_b128 v[132:135], v214 offset:1024
	ds_read_b128 v[136:139], v214 offset:2048
	ds_read_b128 v[140:143], v214 offset:3072
	s_waitcnt vmcnt(6)
	s_setprio 1
	s_barrier
	v_mfma_f32_16x16x32_bf16 v[52:55], v[192:195], v[144:147], v[52:55]
	v_mfma_f32_16x16x32_bf16 v[48:51], v[200:203], v[144:147], v[48:51]
	v_mfma_f32_16x16x32_bf16 v[36:39], v[192:195], v[152:155], v[36:39]
	v_mfma_f32_16x16x32_bf16 v[32:35], v[200:203], v[152:155], v[32:35]
	v_mfma_f32_16x16x32_bf16 v[20:23], v[192:195], v[160:163], v[20:23]
	v_mfma_f32_16x16x32_bf16 v[16:19], v[200:203], v[160:163], v[16:19]
	v_mfma_f32_16x16x32_bf16 v[4:7], v[192:195], v[168:171], v[4:7]
	v_mfma_f32_16x16x32_bf16 v[0:3], v[200:203], v[168:171], v[0:3]
	v_mfma_f32_16x16x32_bf16 v[52:55], v[196:199], v[148:151], v[52:55]
	v_mfma_f32_16x16x32_bf16 v[48:51], v[204:207], v[148:151], v[48:51]
	v_mfma_f32_16x16x32_bf16 v[36:39], v[196:199], v[156:159], v[36:39]
	v_mfma_f32_16x16x32_bf16 v[32:35], v[204:207], v[156:159], v[32:35]
	v_mfma_f32_16x16x32_bf16 v[20:23], v[196:199], v[164:167], v[20:23]
	v_mfma_f32_16x16x32_bf16 v[16:19], v[204:207], v[164:167], v[16:19]
	v_mfma_f32_16x16x32_bf16 v[4:7], v[196:199], v[172:175], v[4:7]
	v_mfma_f32_16x16x32_bf16 v[0:3], v[204:207], v[172:175], v[0:3]
	s_add_i32 s44, s44, 2
	s_add_u32 s18, s18, 0x100
	s_addc_u32 s19, s19, 0
	s_add_u32 s42, s42, 0x100
	s_addc_u32 s43, s43, 0
	s_cmpk_gt_u32 s44, 0x55
	s_barrier
	s_setprio 0
	s_cbranch_scc0 .LBB0_961
	s_waitcnt lgkmcnt(0)
	v_lshl_add_u32 v194, s51, 8, v211
	v_lshl_or_b32 v192, s2, 8, v213
	v_readlane_b32 s52, v243, 3
	v_ashrrev_i32_e32 v193, 31, v192
	v_readlane_b32 s66, v243, 17
	v_readlane_b32 s67, v243, 18
	v_ashrrev_i32_e32 v195, 31, v194
	v_lshlrev_b64 v[128:129], 13, v[194:195]
	v_lshl_add_u64 v[196:197], v[192:193], 2, s[66:67]
	v_lshl_add_u64 v[236:237], v[196:197], 0, v[128:129]
	global_load_dwordx4 v[220:223], v[236:237], off
	global_load_dwordx4 v[224:227], v[236:237], off offset:16
	global_load_dwordx4 v[228:231], v[236:237], off offset:512
	global_load_dwordx4 v[232:235], v[236:237], off offset:528
	v_or_b32_e32 v206, 16, v194
	v_or_b32_e32 v202, 32, v194
	v_or_b32_e32 v198, 48, v194
	v_ashrrev_i32_e32 v207, 31, v206
	v_ashrrev_i32_e32 v203, 31, v202
	v_ashrrev_i32_e32 v199, 31, v198
	v_lshlrev_b64 v[128:129], 13, v[206:207]
	v_lshlrev_b64 v[130:131], 13, v[202:203]
	v_lshlrev_b64 v[132:133], 13, v[198:199]
	v_lshl_add_u64 v[208:209], v[196:197], 0, v[128:129]
	v_lshl_add_u64 v[204:205], v[196:197], 0, v[130:131]
	v_lshl_add_u64 v[200:201], v[196:197], 0, v[132:133]
	global_load_dwordx4 v[168:171], v[208:209], off offset:16
	global_load_dwordx4 v[172:175], v[208:209], off
	global_load_dwordx4 v[160:163], v[208:209], off offset:528
	global_load_dwordx4 v[164:167], v[208:209], off offset:512
	global_load_dwordx4 v[152:155], v[204:205], off offset:16
	global_load_dwordx4 v[156:159], v[204:205], off
	global_load_dwordx4 v[144:147], v[204:205], off offset:528
	global_load_dwordx4 v[148:151], v[204:205], off offset:512
	global_load_dwordx4 v[136:139], v[200:201], off offset:16
	global_load_dwordx4 v[140:143], v[200:201], off
	global_load_dwordx4 v[128:131], v[200:201], off offset:528
	global_load_dwordx4 v[132:135], v[200:201], off offset:512
	v_and_b32_e32 v218, 64, v217
	v_xor_b32_e32 v238, 16, v217
	v_add_u32_e32 v240, 64, v218
	v_xor_b32_e32 v239, 32, v217
	v_cmp_lt_i32_e32 vcc, v238, v240
	v_lshlrev_b64 v[218:219], 11, v[194:195]
	s_lshl_b32 s18, s2, 2
	v_cndmask_b32_e32 v241, v217, v238, vcc
	v_cmp_lt_i32_e32 vcc, v239, v240
	s_ashr_i32 s19, s18, 31
	v_readlane_b32 s53, v243, 4
	v_cndmask_b32_e32 v240, v217, v239, vcc
	v_lshl_add_u64 v[238:239], v[218:219], 0, v[192:193]
	v_lshlrev_b32_e32 v218, 2, v241
	v_lshl_add_u64 v[238:239], v[238:239], 1, s[12:13]
	v_readlane_b32 s54, v243, 5
	v_readlane_b32 s55, v243, 6
	v_readlane_b32 s56, v243, 7
	v_readlane_b32 s57, v243, 8
	v_readlane_b32 s58, v243, 9
	v_readlane_b32 s59, v243, 10
	v_readlane_b32 s60, v243, 11
	v_readlane_b32 s61, v243, 12
	v_readlane_b32 s62, v243, 13
	v_readlane_b32 s63, v243, 14
	v_readlane_b32 s64, v243, 15
	v_readlane_b32 s65, v243, 16
	s_waitcnt vmcnt(0)
	v_pk_add_f32 v[126:127], v[126:127], v[222:223]
	v_pk_add_f32 v[124:125], v[124:125], v[220:221]
	v_pk_add_f32 v[116:117], v[116:117], v[228:229]
	v_pk_add_f32 v[122:123], v[122:123], v[226:227]
	v_pk_add_f32 v[120:121], v[120:121], v[224:225]
	v_pk_add_f32 v[220:221], v[112:113], v[232:233]
	global_store_dwordx4 v[236:237], v[124:127], off
	global_store_dwordx4 v[236:237], v[120:123], off offset:16
	v_cvt_pk_bf16_f32 v112, v124, v125
	v_mul_f32_e32 v125, v125, v125
	v_mul_f32_e32 v219, v117, v117
	v_pk_add_f32 v[118:119], v[118:119], v[230:231]
	v_fmac_f32_e32 v125, v124, v124
	v_fmac_f32_e32 v219, v116, v116
	v_fmac_f32_e32 v125, v126, v126
	v_fmac_f32_e32 v219, v118, v118
	v_fmac_f32_e32 v125, v127, v127
	v_fmac_f32_e32 v219, v119, v119
	v_fmac_f32_e32 v125, v120, v120
	v_fmac_f32_e32 v219, v220, v220
	v_pk_add_f32 v[222:223], v[114:115], v[234:235]
	v_fmac_f32_e32 v125, v121, v121
	v_fmac_f32_e32 v219, v221, v221
	v_fmac_f32_e32 v125, v122, v122
	v_fmac_f32_e32 v219, v222, v222
	v_fmac_f32_e32 v125, v123, v123
	v_fmac_f32_e32 v219, v223, v223
	v_cvt_pk_bf16_f32 v114, v120, v121
	v_add_f32_e32 v121, v125, v219
	v_cvt_pk_bf16_f32 v115, v122, v123
	ds_bpermute_b32 v122, v218, v121
	v_cvt_pk_bf16_f32 v113, v126, v127
	global_store_dwordx4 v[238:239], v[112:115], off
	global_store_dwordx4 v[236:237], v[116:119], off offset:512
	global_store_dwordx4 v[236:237], v[220:223], off offset:528
	v_lshlrev_b32_e32 v126, 2, v240
	v_cvt_pk_bf16_f32 v120, v116, v117
	s_waitcnt lgkmcnt(0)
	v_add_f32_e32 v112, v121, v122
	ds_bpermute_b32 v113, v126, v112
	v_cvt_pk_bf16_f32 v121, v118, v119
	v_cvt_pk_bf16_f32 v122, v220, v221
	v_cvt_pk_bf16_f32 v123, v222, v223
	global_store_dwordx4 v[238:239], v[120:123], off offset:256
	s_and_saveexec_b64 s[20:21], s[0:1]
	s_cbranch_execz .LBB0_964
	s_waitcnt lgkmcnt(0)
	v_add_f32_e32 v114, v112, v113
	v_lshlrev_b64 v[112:113], 7, v[194:195]
	v_lshl_add_u64 v[112:113], s[14:15], 0, v[112:113]
	v_lshl_add_u64 v[112:113], s[18:19], 2, v[112:113]
	s_lshl_b32 s2, s36, 2
	v_lshl_add_u64 v[112:113], v[112:113], 0, s[2:3]
	global_store_dword v[112:113], v114, off

; #define PG8_STAGE(bufoff, gbase, voff) do { _Pragma("unroll") for (int _i = 0; _i < 2; ++_i) \
;     __builtin_amdgcn_global_load_lds((const unsigned*)((const char*)(gbase) + (voff)[_i]), (LAS unsigned*)(lds + (bufoff) + ldsw + _i * 8192), 16, 0, 0); } while (0)
; #define PG8_LDA(dst, b, h) do { _Pragma("unroll") for (int m = 0; m < 4; ++m) _Pragma("unroll") for (int k = 0; k < 2; ++k) dst[m][k] = *(const LAS bf16x8*)(lds + PG8_SA(b, h) + aoff + m * 2048 + k * 1024); } while (0)
; #define PG8_LDB(dst, b, h) do { _Pragma("unroll") for (int n = 0; n < 2; ++n) _Pragma("unroll") for (int k = 0; k < 2; ++k) dst[n][k] = *(const LAS bf16x8*)(lds + PG8_SB(b, h) + boff + n * 2048 + k * 1024); } while (0)
; #define PG8_MMA(ai, bj, At, Bt) do { __builtin_amdgcn_s_setprio(1); _Pragma("unroll") for (int m = 0; m < 4; ++m) _Pragma("unroll") for (int n = 0; n < 2; ++n) _Pragma("unroll") for (int k = 0; k < 2; ++k) \
;     acc[ai][bj][m][n] = __builtin_amdgcn_mfma_f32_16x16x32_bf16(Bt[n][k], At[m][k], acc[ai][bj][m][n], 0, 0, 0); __builtin_amdgcn_s_setprio(0); } while (0)
; #define PG8_WAIT_V(n) asm volatile("s_waitcnt vmcnt(" #n ")" ::: "memory")
; template <class Epi, class Sched = StaticOrder>
; DI void gemm_phase(LAS unsigned char* lds, const Gemm g, const Sched& S, const Epi& E) {
;     ...
;     for (int t = 0; t < nt; t += 2) {
;       const bool last = (t == nt - 2);
;       const char* a1 = cA + (size_t)(t + 1) * kstep;
;       const char* a2 = last ? nA : cA + (size_t)(t + 2) * kstep; const char* b2 = last ? nB : cB + (size_t)(t + 2) * kstep;
;       const char* a3 = a2 + kstep; const char* b3 = b2 + kstep;
;       PG8_LDB(B0, 0, 0); PG8_SCHED; PG8_LDA(At, 0, 0); PG8_STAGE(PG8_SA(1, 1), a1 + hstep, voffA);
;       PG8_WAIT_L(8); PG8_BAR; PG8_WAIT_L(0); PG8_MMA(0, 0, At, B0); PG8_BAR; PG8_SCHED;
;       PG8_LDB(B1, 0, 1); PG8_STAGE(PG8_SB(0, 0), b2, voffB);
;       PG8_BAR; PG8_WAIT_L(0); PG8_MMA(0, 1, At, B1); PG8_BAR;
;       PG8_LDA(At, 0, 1); PG8_STAGE(PG8_SA(0, 0), a2, voffA);
;       PG8_BAR; PG8_WAIT_L(0); PG8_MMA(1, 0, At, B0); PG8_BAR; PG8_SCHED;
;       PG8_STAGE(PG8_SB(0, 1), b2 + hstep, voffB);
;       PG8_WAIT_V(6); PG8_BAR; PG8_MMA(1, 1, At, B1); PG8_BAR;
;       PG8_LDB(B0, 1, 0); PG8_SCHED; PG8_LDA(At, 1, 0); PG8_STAGE(PG8_SA(0, 1), a2 + hstep, voffA);
;       PG8_WAIT_L(8); PG8_BAR; PG8_WAIT_L(0); PG8_MMA(0, 0, At, B0); PG8_BAR; PG8_SCHED;
.LBB0_1052:
	s_add_u32 s12, s10, 0xfff80080
	s_addc_u32 s13, s11, -1
	s_cmp_eq_u32 s52, 28
	s_cselect_b32 s65, s41, s13
	s_cselect_b32 s64, s42, s12
	s_cselect_b32 s13, s43, s49
	s_cselect_b32 s12, s44, s45
	s_add_i32 m0, s61, 0xc000
	ds_read_b128 v[144:147], v204
	ds_read_b128 v[148:151], v204 offset:1024
	ds_read_b128 v[152:155], v204 offset:2048
	ds_read_b128 v[156:159], v204 offset:3072
	ds_read_b128 v[178:181], v204 offset:4096
	ds_read_b128 v[182:185], v204 offset:5120
	ds_read_b128 v[186:189], v204 offset:6144
	ds_read_b128 v[190:193], v204 offset:7168
	global_load_lds_dwordx4 v172, s[10:11]
	s_add_i32 m0, s61, 0xe000
	s_nop 0
	global_load_lds_dwordx4 v174, s[10:11]
	s_waitcnt lgkmcnt(0)
	s_setprio 1
	s_barrier
	v_mfma_f32_16x16x32_bf16 v[124:127], v[128:131], v[144:147], v[124:127]
	v_mfma_f32_16x16x32_bf16 v[120:123], v[136:139], v[144:147], v[120:123]
	v_mfma_f32_16x16x32_bf16 v[116:119], v[128:131], v[152:155], v[116:119]
	v_mfma_f32_16x16x32_bf16 v[104:107], v[136:139], v[152:155], v[104:107]
	v_mfma_f32_16x16x32_bf16 v[92:95], v[128:131], v[178:181], v[92:95]
	v_mfma_f32_16x16x32_bf16 v[88:91], v[136:139], v[178:181], v[88:91]
	v_mfma_f32_16x16x32_bf16 v[84:87], v[128:131], v[186:189], v[84:87]
	v_mfma_f32_16x16x32_bf16 v[72:75], v[136:139], v[186:189], v[72:75]
	v_mfma_f32_16x16x32_bf16 v[124:127], v[132:135], v[148:151], v[124:127]
	v_mfma_f32_16x16x32_bf16 v[120:123], v[140:143], v[148:151], v[120:123]
	v_mfma_f32_16x16x32_bf16 v[116:119], v[132:135], v[156:159], v[116:119]
	v_mfma_f32_16x16x32_bf16 v[104:107], v[140:143], v[156:159], v[104:107]
	v_mfma_f32_16x16x32_bf16 v[92:95], v[132:135], v[182:185], v[92:95]
	v_mfma_f32_16x16x32_bf16 v[88:91], v[140:143], v[182:185], v[88:91]
	v_mfma_f32_16x16x32_bf16 v[84:87], v[132:135], v[190:193], v[84:87]
	v_mfma_f32_16x16x32_bf16 v[72:75], v[140:143], v[190:193], v[72:75]
	s_barrier
	s_setprio 0
	s_add_i32 s53, s80, s70
	s_add_u32 s98, s12, 0x80
	s_addc_u32 s99, s13, 0
	s_mov_b32 m0, s53
	ds_read_b128 v[194:197], v205
	ds_read_b128 v[212:215], v205 offset:1024
	ds_read_b128 v[216:219], v205 offset:2048
	ds_read_b128 v[220:223], v205 offset:3072
	global_load_lds_dwordx4 v162, s[12:13]
	s_add_i32 m0, s53, 0x2000
	s_nop 0
	global_load_lds_dwordx4 v166, s[12:13]
	s_waitcnt lgkmcnt(0)
	s_setprio 1
	s_barrier
	v_mfma_f32_16x16x32_bf16 v[112:115], v[194:197], v[144:147], v[112:115]
	v_mfma_f32_16x16x32_bf16 v[108:111], v[216:219], v[144:147], v[108:111]
	v_mfma_f32_16x16x32_bf16 v[100:103], v[194:197], v[152:155], v[100:103]
	v_mfma_f32_16x16x32_bf16 v[96:99], v[216:219], v[152:155], v[96:99]
	v_mfma_f32_16x16x32_bf16 v[80:83], v[194:197], v[178:181], v[80:83]
	v_mfma_f32_16x16x32_bf16 v[76:79], v[216:219], v[178:181], v[76:79]
	v_mfma_f32_16x16x32_bf16 v[68:71], v[194:197], v[186:189], v[68:71]
	v_mfma_f32_16x16x32_bf16 v[64:67], v[216:219], v[186:189], v[64:67]
	v_mfma_f32_16x16x32_bf16 v[112:115], v[212:215], v[148:151], v[112:115]
	v_mfma_f32_16x16x32_bf16 v[108:111], v[220:223], v[148:151], v[108:111]
	v_mfma_f32_16x16x32_bf16 v[100:103], v[212:215], v[156:159], v[100:103]
	v_mfma_f32_16x16x32_bf16 v[96:99], v[220:223], v[156:159], v[96:99]
	v_mfma_f32_16x16x32_bf16 v[80:83], v[212:215], v[182:185], v[80:83]
	v_mfma_f32_16x16x32_bf16 v[76:79], v[220:223], v[182:185], v[76:79]
	v_mfma_f32_16x16x32_bf16 v[68:71], v[212:215], v[190:193], v[68:71]
	v_mfma_f32_16x16x32_bf16 v[64:67], v[220:223], v[190:193], v[64:67]
	s_barrier
	s_setprio 0
	s_mov_b32 m0, s61
	s_add_u32 s100, s64, 0x80
	s_addc_u32 s101, s65, 0
	ds_read_b128 v[144:147], v204 offset:16384
	ds_read_b128 v[148:151], v204 offset:17408
	ds_read_b128 v[152:155], v204 offset:18432
	ds_read_b128 v[156:159], v204 offset:19456
	ds_read_b128 v[178:181], v204 offset:20480
	ds_read_b128 v[182:185], v204 offset:21504
	ds_read_b128 v[186:189], v204 offset:22528
	ds_read_b128 v[190:193], v204 offset:23552
	global_load_lds_dwordx4 v160, s[64:65]
	s_mov_b32 m0, s63
	s_nop 0
	global_load_lds_dwordx4 v164, s[64:65]
	s_waitcnt vmcnt(10)
	s_waitcnt lgkmcnt(0)
	s_setprio 1
	s_barrier
	v_mfma_f32_16x16x32_bf16 v[60:63], v[128:131], v[144:147], v[60:63]
	v_mfma_f32_16x16x32_bf16 v[56:59], v[136:139], v[144:147], v[56:59]
	v_mfma_f32_16x16x32_bf16 v[48:51], v[128:131], v[152:155], v[48:51]
	v_mfma_f32_16x16x32_bf16 v[40:43], v[136:139], v[152:155], v[40:43]
	v_mfma_f32_16x16x32_bf16 v[28:31], v[128:131], v[178:181], v[28:31]
	v_mfma_f32_16x16x32_bf16 v[24:27], v[136:139], v[178:181], v[24:27]
	v_mfma_f32_16x16x32_bf16 v[12:15], v[128:131], v[186:189], v[12:15]
	v_mfma_f32_16x16x32_bf16 v[8:11], v[136:139], v[186:189], v[8:11]
	v_mfma_f32_16x16x32_bf16 v[60:63], v[132:135], v[148:151], v[60:63]
	v_mfma_f32_16x16x32_bf16 v[56:59], v[140:143], v[148:151], v[56:59]
	v_mfma_f32_16x16x32_bf16 v[48:51], v[132:135], v[156:159], v[48:51]
	v_mfma_f32_16x16x32_bf16 v[40:43], v[140:143], v[156:159], v[40:43]
	v_mfma_f32_16x16x32_bf16 v[28:31], v[132:135], v[182:185], v[28:31]
	v_mfma_f32_16x16x32_bf16 v[24:27], v[140:143], v[182:185], v[24:27]
	v_mfma_f32_16x16x32_bf16 v[12:15], v[132:135], v[190:193], v[12:15]
	v_mfma_f32_16x16x32_bf16 v[8:11], v[140:143], v[190:193], v[8:11]
	s_barrier
	s_setprio 0
	s_add_u32 s54, s12, 0x80000
	s_addc_u32 s55, s13, 0
	s_add_i32 s53, s81, s70
	s_mov_b32 m0, s53
	s_nop 0
	global_load_lds_dwordx4 v162, s[54:55]
	s_add_i32 m0, s53, 0x2000
	s_nop 0
	global_load_lds_dwordx4 v166, s[54:55]
	s_add_i32 s53, 0, 0x18000
	v_add_u32_e32 v140, s53, v199
	ds_read_b128 v[128:131], v140
	ds_read_b128 v[132:135], v140 offset:1024
	ds_read_b128 v[136:139], v140 offset:2048
	ds_read_b128 v[140:143], v140 offset:3072
	s_waitcnt vmcnt(6)
	s_setprio 1
	s_barrier
; #define PG8_STAGE(bufoff, gbase, voff) do { _Pragma("unroll") for (int _i = 0; _i < 2; ++_i) \
;     __builtin_amdgcn_global_load_lds((const unsigned*)((const char*)(gbase) + (voff)[_i]), (LAS unsigned*)(lds + (bufoff) + ldsw + _i * 8192), 16, 0, 0); } while (0)
; #define PG8_LDA(dst, b, h) do { _Pragma("unroll") for (int m = 0; m < 4; ++m) _Pragma("unroll") for (int k = 0; k < 2; ++k) dst[m][k] = *(const LAS bf16x8*)(lds + PG8_SA(b, h) + aoff + m * 2048 + k * 1024); } while (0)
; #define PG8_LDB(dst, b, h) do { _Pragma("unroll") for (int n = 0; n < 2; ++n) _Pragma("unroll") for (int k = 0; k < 2; ++k) dst[n][k] = *(const LAS bf16x8*)(lds + PG8_SB(b, h) + boff + n * 2048 + k * 1024); } while (0)
; #define PG8_MMA(ai, bj, At, Bt) do { __builtin_amdgcn_s_setprio(1); _Pragma("unroll") for (int m = 0; m < 4; ++m) _Pragma("unroll") for (int n = 0; n < 2; ++n) _Pragma("unroll") for (int k = 0; k < 2; ++k) \
;     acc[ai][bj][m][n] = __builtin_amdgcn_mfma_f32_16x16x32_bf16(Bt[n][k], At[m][k], acc[ai][bj][m][n], 0, 0, 0); __builtin_amdgcn_s_setprio(0); } while (0)
; #define PG8_WAIT_V(n) asm volatile("s_waitcnt vmcnt(" #n ")" ::: "memory")
; #define PG8_WAIT_L(n) asm volatile("s_waitcnt lgkmcnt(" #n ")" ::: "memory")
; #define PG8_BAR __builtin_amdgcn_s_barrier()
; #define PG8_SCHED __builtin_amdgcn_sched_barrier(0)
; template <class Epi, class Sched = StaticOrder>
; DI void gemm_phase(LAS unsigned char* lds, const Gemm g, const Sched& S, const Epi& E) {
;     ...
;       PG8_WAIT_V(6); PG8_BAR; PG8_MMA(1, 1, At, B1); PG8_BAR;
;       PG8_LDB(B0, 1, 0); PG8_SCHED; PG8_LDA(At, 1, 0); PG8_STAGE(PG8_SA(0, 1), a2 + hstep, voffA);
;       PG8_WAIT_L(8); PG8_BAR; PG8_WAIT_L(0); PG8_MMA(0, 0, At, B0); PG8_BAR; PG8_SCHED;
;       PG8_LDB(B1, 1, 1); PG8_STAGE(PG8_SB(1, 0), b3, voffB);
;       PG8_BAR; PG8_WAIT_L(0); PG8_MMA(0, 1, At, B1); PG8_BAR;
;       PG8_LDA(At, 1, 1); PG8_STAGE(PG8_SA(1, 0), a3, voffA);
;       PG8_BAR; PG8_WAIT_L(0); PG8_MMA(1, 0, At, B0); PG8_BAR; PG8_SCHED;
	v_mfma_f32_16x16x32_bf16 v[52:55], v[194:197], v[144:147], v[52:55]
	v_mfma_f32_16x16x32_bf16 v[44:47], v[216:219], v[144:147], v[44:47]
	v_mfma_f32_16x16x32_bf16 v[36:39], v[194:197], v[152:155], v[36:39]
	v_mfma_f32_16x16x32_bf16 v[32:35], v[216:219], v[152:155], v[32:35]
	v_mfma_f32_16x16x32_bf16 v[20:23], v[194:197], v[178:181], v[20:23]
	v_mfma_f32_16x16x32_bf16 v[16:19], v[216:219], v[178:181], v[16:19]
	v_mfma_f32_16x16x32_bf16 v[4:7], v[194:197], v[186:189], v[4:7]
	v_mfma_f32_16x16x32_bf16 v[0:3], v[216:219], v[186:189], v[0:3]
	v_mfma_f32_16x16x32_bf16 v[52:55], v[212:215], v[148:151], v[52:55]
	v_mfma_f32_16x16x32_bf16 v[44:47], v[220:223], v[148:151], v[44:47]
	v_mfma_f32_16x16x32_bf16 v[36:39], v[212:215], v[156:159], v[36:39]
	v_mfma_f32_16x16x32_bf16 v[32:35], v[220:223], v[156:159], v[32:35]
	v_mfma_f32_16x16x32_bf16 v[20:23], v[212:215], v[182:185], v[20:23]
	v_mfma_f32_16x16x32_bf16 v[16:19], v[220:223], v[182:185], v[16:19]
	v_mfma_f32_16x16x32_bf16 v[4:7], v[212:215], v[190:193], v[4:7]
	v_mfma_f32_16x16x32_bf16 v[0:3], v[220:223], v[190:193], v[0:3]
	s_barrier
	s_setprio 0
	s_add_u32 s54, s64, 0x80000
	s_addc_u32 s55, s65, 0
	s_mov_b32 m0, s71
	ds_read_b128 v[144:147], v204 offset:32768
	ds_read_b128 v[148:151], v204 offset:33792
	ds_read_b128 v[152:155], v204 offset:34816
	ds_read_b128 v[156:159], v204 offset:35840
	ds_read_b128 v[178:181], v204 offset:36864
	ds_read_b128 v[182:185], v204 offset:37888
	ds_read_b128 v[186:189], v204 offset:38912
	ds_read_b128 v[190:193], v204 offset:39936
	global_load_lds_dwordx4 v160, s[54:55]
	s_mov_b32 m0, s72
	s_nop 0
	global_load_lds_dwordx4 v164, s[54:55]
	s_waitcnt lgkmcnt(0)
	s_setprio 1
	s_barrier
	v_mfma_f32_16x16x32_bf16 v[124:127], v[128:131], v[144:147], v[124:127]
	v_mfma_f32_16x16x32_bf16 v[120:123], v[136:139], v[144:147], v[120:123]
	v_mfma_f32_16x16x32_bf16 v[116:119], v[128:131], v[152:155], v[116:119]
	v_mfma_f32_16x16x32_bf16 v[104:107], v[136:139], v[152:155], v[104:107]
	v_mfma_f32_16x16x32_bf16 v[92:95], v[128:131], v[178:181], v[92:95]
	v_mfma_f32_16x16x32_bf16 v[88:91], v[136:139], v[178:181], v[88:91]
	v_mfma_f32_16x16x32_bf16 v[84:87], v[128:131], v[186:189], v[84:87]
	v_mfma_f32_16x16x32_bf16 v[72:75], v[136:139], v[186:189], v[72:75]
	v_mfma_f32_16x16x32_bf16 v[124:127], v[132:135], v[148:151], v[124:127]
	v_mfma_f32_16x16x32_bf16 v[120:123], v[140:143], v[148:151], v[120:123]
	v_mfma_f32_16x16x32_bf16 v[116:119], v[132:135], v[156:159], v[116:119]
	v_mfma_f32_16x16x32_bf16 v[104:107], v[140:143], v[156:159], v[104:107]
	v_mfma_f32_16x16x32_bf16 v[92:95], v[132:135], v[182:185], v[92:95]
	v_mfma_f32_16x16x32_bf16 v[88:91], v[140:143], v[182:185], v[88:91]
	v_mfma_f32_16x16x32_bf16 v[84:87], v[132:135], v[190:193], v[84:87]
	v_mfma_f32_16x16x32_bf16 v[72:75], v[140:143], v[190:193], v[72:75]
	s_barrier
	s_setprio 0
	s_add_i32 s54, 0, 0x1c000
	s_add_i32 s53, s53, s70
	v_add_u32_e32 v168, s54, v199
	s_mov_b32 m0, s53
	ds_read_b128 v[194:197], v168
	ds_read_b128 v[212:215], v168 offset:1024
	ds_read_b128 v[216:219], v168 offset:2048
	ds_read_b128 v[220:223], v168 offset:3072
	global_load_lds_dwordx4 v162, s[98:99]
	s_add_i32 m0, s53, 0x2000
	s_nop 0
	global_load_lds_dwordx4 v166, s[98:99]
	s_waitcnt lgkmcnt(0)
	s_setprio 1
	s_barrier
	v_mfma_f32_16x16x32_bf16 v[112:115], v[194:197], v[144:147], v[112:115]
	v_mfma_f32_16x16x32_bf16 v[108:111], v[216:219], v[144:147], v[108:111]
	v_mfma_f32_16x16x32_bf16 v[100:103], v[194:197], v[152:155], v[100:103]
	v_mfma_f32_16x16x32_bf16 v[96:99], v[216:219], v[152:155], v[96:99]
	v_mfma_f32_16x16x32_bf16 v[80:83], v[194:197], v[178:181], v[80:83]
	v_mfma_f32_16x16x32_bf16 v[76:79], v[216:219], v[178:181], v[76:79]
	v_mfma_f32_16x16x32_bf16 v[68:71], v[194:197], v[186:189], v[68:71]
	v_mfma_f32_16x16x32_bf16 v[64:67], v[216:219], v[186:189], v[64:67]
	v_mfma_f32_16x16x32_bf16 v[112:115], v[212:215], v[148:151], v[112:115]
	v_mfma_f32_16x16x32_bf16 v[108:111], v[220:223], v[148:151], v[108:111]
	v_mfma_f32_16x16x32_bf16 v[100:103], v[212:215], v[156:159], v[100:103]
	v_mfma_f32_16x16x32_bf16 v[96:99], v[220:223], v[156:159], v[96:99]
	v_mfma_f32_16x16x32_bf16 v[80:83], v[212:215], v[182:185], v[80:83]
	v_mfma_f32_16x16x32_bf16 v[76:79], v[220:223], v[182:185], v[76:79]
	v_mfma_f32_16x16x32_bf16 v[68:71], v[212:215], v[190:193], v[68:71]
	v_mfma_f32_16x16x32_bf16 v[64:67], v[220:223], v[190:193], v[64:67]
	s_barrier
	s_setprio 0
	s_mov_b32 m0, s76
	ds_read_b128 v[144:147], v204 offset:49152
	ds_read_b128 v[148:151], v204 offset:50176
	ds_read_b128 v[152:155], v204 offset:51200
	ds_read_b128 v[156:159], v204 offset:52224
	ds_read_b128 v[178:181], v204 offset:53248
	ds_read_b128 v[182:185], v204 offset:54272
	ds_read_b128 v[186:189], v204 offset:55296
	ds_read_b128 v[190:193], v204 offset:56320
	global_load_lds_dwordx4 v160, s[100:101]
	s_mov_b32 m0, s77
	s_nop 0
	global_load_lds_dwordx4 v164, s[100:101]
	s_waitcnt vmcnt(10)
	s_waitcnt lgkmcnt(0)
	s_setprio 1
	s_barrier
	v_mfma_f32_16x16x32_bf16 v[60:63], v[128:131], v[144:147], v[60:63]
	v_mfma_f32_16x16x32_bf16 v[56:59], v[136:139], v[144:147], v[56:59]
	v_mfma_f32_16x16x32_bf16 v[48:51], v[128:131], v[152:155], v[48:51]
	v_mfma_f32_16x16x32_bf16 v[40:43], v[136:139], v[152:155], v[40:43]
	v_mfma_f32_16x16x32_bf16 v[28:31], v[128:131], v[178:181], v[28:31]
	v_mfma_f32_16x16x32_bf16 v[24:27], v[136:139], v[178:181], v[24:27]
	v_mfma_f32_16x16x32_bf16 v[12:15], v[128:131], v[186:189], v[12:15]
	v_mfma_f32_16x16x32_bf16 v[8:11], v[136:139], v[186:189], v[8:11]
	v_mfma_f32_16x16x32_bf16 v[60:63], v[132:135], v[148:151], v[60:63]
	v_mfma_f32_16x16x32_bf16 v[56:59], v[140:143], v[148:151], v[56:59]
	v_mfma_f32_16x16x32_bf16 v[48:51], v[132:135], v[156:159], v[48:51]
	v_mfma_f32_16x16x32_bf16 v[40:43], v[140:143], v[156:159], v[40:43]
	v_mfma_f32_16x16x32_bf16 v[28:31], v[132:135], v[182:185], v[28:31]
	v_mfma_f32_16x16x32_bf16 v[24:27], v[140:143], v[182:185], v[24:27]
	v_mfma_f32_16x16x32_bf16 v[12:15], v[132:135], v[190:193], v[12:15]
	v_mfma_f32_16x16x32_bf16 v[8:11], v[140:143], v[190:193], v[8:11]
	s_barrier
; #define PG8_STAGE(bufoff, gbase, voff) do { _Pragma("unroll") for (int _i = 0; _i < 2; ++_i) \
;     __builtin_amdgcn_global_load_lds((const unsigned*)((const char*)(gbase) + (voff)[_i]), (LAS unsigned*)(lds + (bufoff) + ldsw + _i * 8192), 16, 0, 0); } while (0)
; #define PG8_MMA(ai, bj, At, Bt) do { __builtin_amdgcn_s_setprio(1); _Pragma("unroll") for (int m = 0; m < 4; ++m) _Pragma("unroll") for (int n = 0; n < 2; ++n) _Pragma("unroll") for (int k = 0; k < 2; ++k) \
;     acc[ai][bj][m][n] = __builtin_amdgcn_mfma_f32_16x16x32_bf16(Bt[n][k], At[m][k], acc[ai][bj][m][n], 0, 0, 0); __builtin_amdgcn_s_setprio(0); } while (0)
; #define PG8_WAIT_V(n) asm volatile("s_waitcnt vmcnt(" #n ")" ::: "memory")
; #define PG8_BAR __builtin_amdgcn_s_barrier()
;   DI void operator()(const f32x4 (&acc)[2][2][4][2], const Unit& u, int wr, int wc, int fr, int fq) const {
;     ...
;     const int col = u.pn * 128 + wc * 32 + 8 * fq;
;     float w0[8], w1[8], w2[8];
; #pragma unroll
;     for (int e = 0; e < 8; ++e) { w0[e] = cw[col + e]; w1[e] = cw[2048 + col + e]; w2[e] = cw[4096 + col + e]; }
; #pragma unroll
;     for (int ai = 0; ai < 2; ++ai) {
;       const int row0 = u.pm * BM + ai * HALF + wr * 64, span = row0 >> 6;
;       float rsv[4];
; #pragma unroll
;       for (int m = 0; m < 4; ++m) rsv[m] = row_rstd(ssq, row0 + 16 * m + fr, fq);
; template <class Epi, class Sched = StaticOrder>
; DI void gemm_phase(LAS unsigned char* lds, const Gemm g, const Sched& S, const Epi& E) {
;     ...
;       PG8_STAGE(PG8_SB(1, 1), b3 + hstep, voffB);
;       PG8_WAIT_V(6); PG8_BAR; PG8_MMA(1, 1, At, B1); PG8_BAR;
	s_setprio 0
	s_add_u32 s12, s12, 0x80080
	s_addc_u32 s13, s13, 0
	s_add_i32 s53, s54, s70
	s_mov_b32 m0, s53
	s_nop 0
	global_load_lds_dwordx4 v162, s[12:13]
	s_add_i32 m0, s53, 0x2000
	s_nop 0
	global_load_lds_dwordx4 v166, s[12:13]
	ds_read_b128 v[128:131], v203
	ds_read_b128 v[132:135], v203 offset:1024
	ds_read_b128 v[136:139], v203 offset:2048
	ds_read_b128 v[140:143], v203 offset:3072
	s_waitcnt vmcnt(6)
	s_setprio 1
	s_barrier
	v_mfma_f32_16x16x32_bf16 v[52:55], v[194:197], v[144:147], v[52:55]
	v_mfma_f32_16x16x32_bf16 v[44:47], v[216:219], v[144:147], v[44:47]
	v_mfma_f32_16x16x32_bf16 v[36:39], v[194:197], v[152:155], v[36:39]
	v_mfma_f32_16x16x32_bf16 v[32:35], v[216:219], v[152:155], v[32:35]
	v_mfma_f32_16x16x32_bf16 v[20:23], v[194:197], v[178:181], v[20:23]
	v_mfma_f32_16x16x32_bf16 v[16:19], v[216:219], v[178:181], v[16:19]
	v_mfma_f32_16x16x32_bf16 v[4:7], v[194:197], v[186:189], v[4:7]
	v_mfma_f32_16x16x32_bf16 v[0:3], v[216:219], v[186:189], v[0:3]
	v_mfma_f32_16x16x32_bf16 v[52:55], v[212:215], v[148:151], v[52:55]
	v_mfma_f32_16x16x32_bf16 v[44:47], v[220:223], v[148:151], v[44:47]
	v_mfma_f32_16x16x32_bf16 v[36:39], v[212:215], v[156:159], v[36:39]
	v_mfma_f32_16x16x32_bf16 v[32:35], v[220:223], v[156:159], v[32:35]
	v_mfma_f32_16x16x32_bf16 v[20:23], v[212:215], v[182:185], v[20:23]
	v_mfma_f32_16x16x32_bf16 v[16:19], v[220:223], v[182:185], v[16:19]
	v_mfma_f32_16x16x32_bf16 v[4:7], v[212:215], v[190:193], v[4:7]
	v_mfma_f32_16x16x32_bf16 v[0:3], v[220:223], v[190:193], v[0:3]
	s_add_i32 s52, s52, 2
	s_add_u32 s10, s10, 0x100
	s_addc_u32 s11, s11, 0
	s_add_u32 s45, s45, 0x100
	s_addc_u32 s49, s49, 0
	s_cmp_gt_u32 s52, 29
	s_barrier
	s_setprio 0
	s_cbranch_scc0 .LBB0_1052
	s_waitcnt lgkmcnt(0)
	s_cmp_lt_i32 s62, 16
	s_mov_b64 s[10:11], -1
	s_cbranch_scc0 .LBB0_1067
	s_lshl_b32 s41, s60, 8
	s_add_i32 s41, s41, s75
	v_or_b32_e32 v186, s41, v177
	v_ashrrev_i32_e32 v187, 31, v186
	v_lshlrev_b64 v[128:129], 7, v[186:187]
	v_or_b32_e32 v180, 16, v186
	v_lshl_add_u64 v[128:129], v[170:171], 0, v[128:129]
	v_ashrrev_i32_e32 v181, 31, v180
	global_load_dwordx4 v[152:155], v[128:129], off
	global_load_dwordx4 v[156:159], v[128:129], off offset:16
	v_lshlrev_b64 v[128:129], 7, v[180:181]
	v_lshl_add_u64 v[128:129], v[170:171], 0, v[128:129]
	global_load_dwordx4 v[188:191], v[128:129], off
	global_load_dwordx4 v[192:195], v[128:129], off offset:16
	v_or_b32_e32 v184, 32, v186
	v_ashrrev_i32_e32 v185, 31, v184
	v_lshlrev_b64 v[128:129], 7, v[184:185]
	v_or_b32_e32 v182, 48, v186
	v_lshl_add_u64 v[128:129], v[170:171], 0, v[128:129]
	v_ashrrev_i32_e32 v183, 31, v182
	global_load_dwordx4 v[212:215], v[128:129], off
	global_load_dwordx4 v[216:219], v[128:129], off offset:16
	v_lshlrev_b64 v[128:129], 7, v[182:183]
	v_lshl_add_u64 v[128:129], v[170:171], 0, v[128:129]
	global_load_dwordx4 v[220:223], v[128:129], off
	global_load_dwordx4 v[224:227], v[128:129], off offset:16
	v_and_b32_e32 v129, 64, v206
	v_lshl_or_b32 v178, s62, 7, v200
	v_xor_b32_e32 v128, 16, v206
	v_add_u32_e32 v129, 64, v129
	v_readlane_b32 s44, v243, 3
	v_xor_b32_e32 v130, 32, v206
	v_ashrrev_i32_e32 v179, 31, v178
	v_readlane_b32 s45, v243, 4
	v_cmp_lt_i32_e32 vcc, v128, v129
	s_movk_i32 s10, 0x2000
	v_lshl_add_u64 v[144:145], v[178:179], 2, s[44:45]
	v_cndmask_b32_e32 v134, v206, v128, vcc
	v_cmp_lt_i32_e32 vcc, v130, v129
	v_lshl_add_u64 v[132:133], v[144:145], 0, s[26:27]
	v_lshl_add_u64 v[136:137], v[144:145], 0, s[28:29]
	v_cndmask_b32_e32 v135, v206, v130, vcc
	v_add_co_u32_e32 v146, vcc, s10, v144
	global_load_dwordx4 v[128:131], v[144:145], off offset:16
	global_load_dwordx4 v[140:143], v[144:145], off
	v_addc_co_u32_e32 v147, vcc, 0, v145, vcc
	v_add_co_u32_e32 v148, vcc, s74, v144
	v_lshlrev_b32_e32 v196, 2, v134
	s_nop 0
	v_addc_co_u32_e32 v149, vcc, 0, v145, vcc
	v_lshlrev_b32_e32 v207, 2, v135
	global_load_dwordx4 v[132:135], v[132:133], off offset:16
	s_nop 0
	global_load_dwordx4 v[136:139], v[136:137], off offset:16
	s_nop 0
	global_load_dwordx4 v[144:147], v[146:147], off
	s_nop 0
	global_load_dwordx4 v[148:151], v[148:149], off
	v_mov_b32_e32 v197, 0
	v_mov_b32_e32 v211, 0
	v_readlane_b32 s46, v243, 5
	v_readlane_b32 s47, v243, 6
	v_readlane_b32 s48, v243, 7
	v_readlane_b32 s49, v243, 8
	v_readlane_b32 s50, v243, 9
	v_readlane_b32 s51, v243, 10
	v_readlane_b32 s52, v243, 11
	v_readlane_b32 s53, v243, 12
	v_readlane_b32 s54, v243, 13
	v_readlane_b32 s55, v243, 14
	v_readlane_b32 s56, v243, 15
	v_readlane_b32 s57, v243, 16
	v_readlane_b32 s58, v243, 17
	v_readlane_b32 s59, v243, 18
	s_waitcnt vmcnt(0)
	v_mov_b32_e32 v208, v152
	v_mov_b32_e32 v209, v156
	v_mov_b32_e32 v156, v153
	v_mov_b32_e32 v152, v154
	v_mov_b32_e32 v153, v158
	v_mov_b32_e32 v158, v155
	v_pk_add_f32 v[154:155], v[208:209], v[156:157]
	v_pk_add_f32 v[152:153], v[152:153], v[158:159]
	v_mov_b32_e32 v156, v188
	v_mov_b32_e32 v157, v192
	v_mov_b32_e32 v192, v189
	v_mov_b32_e32 v158, v190
	v_mov_b32_e32 v159, v194
	v_mov_b32_e32 v194, v191
	v_pk_add_f32 v[152:153], v[154:155], v[152:153]
	v_pk_add_f32 v[154:155], v[156:157], v[192:193]
	v_pk_add_f32 v[156:157], v[158:159], v[194:195]
	v_mov_b32_e32 v188, v212
	v_pk_add_f32 v[154:155], v[154:155], v[156:157]
	v_mov_b32_e32 v157, v152
	v_mov_b32_e32 v156, v154
	v_mov_b32_e32 v152, v155
	v_pk_add_f32 v[152:153], v[156:157], v[152:153]
	ds_bpermute_b32 v155, v196, v153
	ds_bpermute_b32 v154, v196, v152
	v_mov_b32_e32 v189, v216
	v_mov_b32_e32 v216, v213
	v_mov_b32_e32 v190, v214
	v_mov_b32_e32 v191, v218
	s_waitcnt lgkmcnt(0)
; DI unsigned pack2(float lo, float hi) { f32x2 v = {lo, hi}; bf16v2 r = __builtin_convertvector(v, bf16v2); return __builtin_bit_cast(unsigned, r); }
; DI float dpp_ror1(float v) { return __int_as_float(__builtin_amdgcn_update_dpp(0, __float_as_int(v), 0x121, 0xf, 0xf, false)); }
; DI float dpp_ror2(float v) { return __int_as_float(__builtin_amdgcn_update_dpp(0, __float_as_int(v), 0x122, 0xf, 0xf, false)); }
;   DI void operator()(const f32x4 (&acc)[2][2][4][2], const Unit& u, int wr, int wc, int fr, int fq) const {
;     ...
;       for (int m = 0; m < 4; ++m) rsv[m] = row_rstd(ssq, row0 + 16 * m + fr, fq);
;       float p1[8], p2[8];
; #pragma unroll
;       for (int e = 0; e < 8; ++e) { p1[e] = 0.f; p2[e] = 0.f; }
; #pragma unroll
;       for (int m = 0; m < 4; ++m) {
;         float g[8], a[8];
;         const float rs1 = rsv[m], rs2 = rs1 * rs1;
; #pragma unroll
;         for (int e = 0; e < 4; ++e) { g[e] = acc[ai][0][m][0][e] * acc[ai][1][m][0][e] * rs2; g[4 + e] = acc[ai][0][m][1][e] * acc[ai][1][m][1][e] * rs2; }
; #pragma unroll
;         for (int e = 0; e < 8; ++e) {
;           const float x1 = dpp_ror1(g[e]), x2 = dpp_ror2(g[e]);
;           const float pr1 = (fr == 0) ? p1[e] : x1, pr2 = (fr < 2) ? p2[e] : x2;
;           a[e] = w2[e] * g[e] + w1[e] * pr1 + w0[e] * pr2;
;           p1[e] = x1; p2[e] = x2;
;         }
;         if (m == 0 && fr < 2) {
;           float* hc = headC + (size_t)(span * 2 + fr) * 2048 + col;
;           *(f32x4*)hc = (f32x4){a[0], a[1], a[2], a[3]}; *(f32x4*)(hc + 4) = (f32x4){a[4], a[5], a[6], a[7]};
;         } else {
;           u32x4 w; w.x = pack2(a[0] * rs1, a[1] * rs1); w.y = pack2(a[2] * rs1, a[3] * rs1); w.z = pack2(a[4] * rs1, a[5] * rs1); w.w = pack2(a[6] * rs1, a[7] * rs1);
;           *(u32x4*)(C + (size_t)(row0 + 16 * m + fr) * 2048 + col) = w;
	v_pk_add_f32 v[152:153], v[152:153], v[154:155]
	ds_bpermute_b32 v155, v207, v153
	ds_bpermute_b32 v154, v207, v152
	v_mov_b32_e32 v218, v215
	v_mov_b32_e32 v208, v220
	v_mov_b32_e32 v209, v224
	v_mov_b32_e32 v224, v221
	v_mov_b32_e32 v212, v222
	v_mov_b32_e32 v213, v226
	v_mov_b32_e32 v226, v223
	v_pk_add_f32 v[156:157], v[188:189], v[216:217]
	v_pk_add_f32 v[158:159], v[190:191], v[218:219]
	v_pk_add_f32 v[188:189], v[208:209], v[224:225]
	v_pk_add_f32 v[190:191], v[212:213], v[226:227]
	s_waitcnt lgkmcnt(0)
	v_pk_add_f32 v[152:153], v[152:153], v[154:155]
	v_pk_add_f32 v[156:157], v[156:157], v[158:159]
	v_pk_add_f32 v[158:159], v[188:189], v[190:191]
	v_pk_fma_f32 v[188:189], v[152:153], s[30:31], v[176:177] op_sel_hi:[1,0,0]
	v_mov_b32_e32 v153, v156
	v_mul_f32_e32 v152, 0x4b800000, v189
	v_cmp_gt_f32_e64 s[10:11], s84, v189
	v_mov_b32_e32 v156, v159
	v_mov_b32_e32 v194, v123
	v_cndmask_b32_e64 v152, v189, v152, s[10:11]
	v_rsq_f32_e32 v168, v152
	v_mov_b32_e32 v152, v158
	v_pk_add_f32 v[152:153], v[152:153], v[156:157]
	ds_bpermute_b32 v155, v196, v153
	ds_bpermute_b32 v154, v196, v152
	v_mul_f32_e32 v156, 0x45800000, v168
	v_cndmask_b32_e64 v195, v168, v156, s[10:11]
	v_mov_b32_e32 v217, 0
	v_mul_f32_e32 v156, v125, v113
	s_waitcnt lgkmcnt(0)
	v_pk_add_f32 v[190:191], v[152:153], v[154:155]
	v_mov_b32_e32 v152, v111
	v_mov_b32_e32 v153, v195
	v_mul_f32_e32 v154, v124, v112
	v_pk_mul_f32 v[152:153], v[194:195], v[152:153]
	v_mul_f32_e32 v155, v120, v108
	v_mul_f32_e32 v154, v154, v153
	v_pk_mul_f32 v[222:223], v[152:153], v[152:153] op_sel:[0,1] op_sel_hi:[1,0]
	v_mov_b32_e32 v213, 0
	v_mov_b32_dpp v217, v154 row_ror:1 row_mask:0xf bank_mask:0xf
	v_cndmask_b32_e64 v152, v217, 0, s[0:1]
	v_mul_f32_e32 v157, v121, v109
	v_mul_f32_e32 v158, v126, v114
	v_mul_f32_e32 v159, v122, v110
	v_mul_f32_e32 v168, v127, v115
	v_mul_f32_e32 v194, v155, v153
	v_mul_f32_e32 v155, v156, v153
	v_mov_b32_dpp v213, v154 row_ror:2 row_mask:0xf bank_mask:0xf
	v_mov_b32_e32 v221, 0
	v_mul_f32_e32 v152, v144, v152
	v_mul_f32_e32 v208, v157, v153
	v_mul_f32_e32 v156, v158, v153
	v_mul_f32_e32 v159, v159, v153
	v_mul_f32_e32 v157, v168, v153
	v_mov_b32_dpp v221, v155 row_ror:1 row_mask:0xf bank_mask:0xf
	v_cndmask_b32_e64 v153, v213, 0, s[8:9]
	v_fmac_f32_e32 v152, v148, v154
	v_mov_b32_e32 v219, 0
	v_fmac_f32_e32 v152, v140, v153
	v_cndmask_b32_e64 v153, v221, 0, s[0:1]
	v_mov_b32_dpp v219, v155 row_ror:2 row_mask:0xf bank_mask:0xf
	v_mul_f32_e32 v153, v145, v153
	v_mov_b32_e32 v216, 0
	v_cndmask_b32_e64 v154, v219, 0, s[8:9]
	v_fmac_f32_e32 v153, v149, v155
	v_mov_b32_dpp v216, v156 row_ror:1 row_mask:0xf bank_mask:0xf
	v_fmac_f32_e32 v153, v141, v154
	v_mov_b32_e32 v212, 0
	v_cndmask_b32_e64 v154, v216, 0, s[0:1]
	v_mov_b32_e32 v220, 0
	v_mov_b32_dpp v212, v156 row_ror:2 row_mask:0xf bank_mask:0xf
	v_mul_f32_e32 v154, v146, v154
	v_mov_b32_dpp v220, v157 row_ror:1 row_mask:0xf bank_mask:0xf
	v_cndmask_b32_e64 v155, v212, 0, s[8:9]
	v_fmac_f32_e32 v154, v150, v156
	v_mov_b32_e32 v218, 0
	v_fmac_f32_e32 v154, v142, v155
	v_cndmask_b32_e64 v155, v220, 0, s[0:1]
	v_mov_b32_dpp v218, v157 row_ror:2 row_mask:0xf bank_mask:0xf
	v_mul_f32_e32 v155, v147, v155
	v_cndmask_b32_e64 v156, v218, 0, s[8:9]
	v_fmac_f32_e32 v155, v151, v157
	v_mov_b32_dpp v197, v194 row_ror:1 row_mask:0xf bank_mask:0xf
	v_fmac_f32_e32 v155, v143, v156
	v_mov_b32_e32 v189, 0
	v_cndmask_b32_e64 v156, v197, 0, s[0:1]
	v_mov_b32_e32 v214, 0
	v_mov_b32_dpp v189, v194 row_ror:2 row_mask:0xf bank_mask:0xf
	v_mul_f32_e32 v156, v132, v156
	v_mov_b32_dpp v214, v208 row_ror:1 row_mask:0xf bank_mask:0xf
	v_cndmask_b32_e64 v157, v189, 0, s[8:9]
	v_fmac_f32_e32 v156, v136, v194
	v_fmac_f32_e32 v156, v128, v157
	v_cndmask_b32_e64 v157, v214, 0, s[0:1]
	v_mov_b32_e32 v209, 0
	v_mul_f32_e32 v157, v133, v157
	v_fmac_f32_e32 v157, v137, v208
	v_mov_b32_dpp v209, v208 row_ror:2 row_mask:0xf bank_mask:0xf
	v_mov_b32_e32 v208, 0
	v_cndmask_b32_e64 v158, v209, 0, s[8:9]
	v_fmac_f32_e32 v157, v129, v158
	v_mov_b32_dpp v208, v159 row_ror:1 row_mask:0xf bank_mask:0xf
	v_mov_b32_e32 v194, 0
	v_cndmask_b32_e64 v158, v208, 0, s[0:1]
	ds_bpermute_b32 v193, v207, v191
	ds_bpermute_b32 v192, v207, v190
	v_mov_b32_dpp v194, v159 row_ror:2 row_mask:0xf bank_mask:0xf
	v_mov_b32_e32 v215, 0
	v_mul_f32_e32 v158, v134, v158
	v_cndmask_b32_e64 v168, v194, 0, s[8:9]
	v_mov_b32_dpp v215, v222 row_ror:1 row_mask:0xf bank_mask:0xf
	v_fmac_f32_e32 v158, v138, v159
	v_mov_b32_dpp v211, v222 row_ror:2 row_mask:0xf bank_mask:0xf
	v_fmac_f32_e32 v158, v130, v168
	v_cndmask_b32_e64 v168, v215, 0, s[0:1]
	v_mul_f32_e32 v159, v139, v222
	v_cndmask_b32_e64 v223, v211, 0, s[8:9]
	v_fmac_f32_e32 v159, v135, v168
	v_cmp_gt_f32_e32 vcc, s84, v188
	v_fmac_f32_e32 v159, v131, v223
	s_and_saveexec_b64 s[10:11], s[4:5]
	s_xor_b64 s[10:11], exec, s[10:11]
	s_cbranch_execz .LBB0_1056
	v_mul_f32_e32 v152, v195, v152
	v_mul_f32_e32 v153, v195, v153
	v_cvt_pk_bf16_f32 v152, v152, v153
	v_mul_f32_e32 v153, v195, v154
	v_mul_f32_e32 v154, v195, v155
	v_cvt_pk_bf16_f32 v153, v153, v154
	v_mul_f32_e32 v154, v195, v156
	v_mul_f32_e32 v155, v195, v157
	v_cvt_pk_bf16_f32 v154, v154, v155
	v_mul_f32_e32 v155, v195, v158
	v_mul_f32_e32 v156, v195, v159
	v_cvt_pk_bf16_f32 v155, v155, v156
	v_lshlrev_b64 v[156:157], 12, v[186:187]
	v_lshl_add_u64 v[156:157], s[18:19], 0, v[156:157]
	v_lshl_add_u64 v[156:157], v[178:179], 1, v[156:157]
	global_store_dwordx4 v[156:157], v[152:155], off

; #define PG8_STAGE(bufoff, gbase, voff) do { _Pragma("unroll") for (int _i = 0; _i < 2; ++_i) \
;     __builtin_amdgcn_global_load_lds((const unsigned*)((const char*)(gbase) + (voff)[_i]), (LAS unsigned*)(lds + (bufoff) + ldsw + _i * 8192), 16, 0, 0); } while (0)
; #define PG8_LDA(dst, b, h) do { _Pragma("unroll") for (int m = 0; m < 4; ++m) _Pragma("unroll") for (int k = 0; k < 2; ++k) dst[m][k] = *(const LAS bf16x8*)(lds + PG8_SA(b, h) + aoff + m * 2048 + k * 1024); } while (0)
; #define PG8_LDB(dst, b, h) do { _Pragma("unroll") for (int n = 0; n < 2; ++n) _Pragma("unroll") for (int k = 0; k < 2; ++k) dst[n][k] = *(const LAS bf16x8*)(lds + PG8_SB(b, h) + boff + n * 2048 + k * 1024); } while (0)
; #define PG8_MMA(ai, bj, At, Bt) do { __builtin_amdgcn_s_setprio(1); _Pragma("unroll") for (int m = 0; m < 4; ++m) _Pragma("unroll") for (int n = 0; n < 2; ++n) _Pragma("unroll") for (int k = 0; k < 2; ++k) \
;     acc[ai][bj][m][n] = __builtin_amdgcn_mfma_f32_16x16x32_bf16(Bt[n][k], At[m][k], acc[ai][bj][m][n], 0, 0, 0); __builtin_amdgcn_s_setprio(0); } while (0)
; #define PG8_WAIT_V(n) asm volatile("s_waitcnt vmcnt(" #n ")" ::: "memory")
; template <class Epi, class Sched = StaticOrder>
; DI void gemm_phase(LAS unsigned char* lds, const Gemm g, const Sched& S, const Epi& E) {
;     ...
;     for (int t = 0; t < nt; t += 2) {
;       const bool last = (t == nt - 2);
;       const char* a1 = cA + (size_t)(t + 1) * kstep;
;       const char* a2 = last ? nA : cA + (size_t)(t + 2) * kstep; const char* b2 = last ? nB : cB + (size_t)(t + 2) * kstep;
;       const char* a3 = a2 + kstep; const char* b3 = b2 + kstep;
;       PG8_LDB(B0, 0, 0); PG8_SCHED; PG8_LDA(At, 0, 0); PG8_STAGE(PG8_SA(1, 1), a1 + hstep, voffA);
;       PG8_WAIT_L(8); PG8_BAR; PG8_WAIT_L(0); PG8_MMA(0, 0, At, B0); PG8_BAR; PG8_SCHED;
;       PG8_LDB(B1, 0, 1); PG8_STAGE(PG8_SB(0, 0), b2, voffB);
;       PG8_BAR; PG8_WAIT_L(0); PG8_MMA(0, 1, At, B1); PG8_BAR;
;       PG8_LDA(At, 0, 1); PG8_STAGE(PG8_SA(0, 0), a2, voffA);
;       PG8_BAR; PG8_WAIT_L(0); PG8_MMA(1, 0, At, B0); PG8_BAR; PG8_SCHED;
;       PG8_STAGE(PG8_SB(0, 1), b2 + hstep, voffB);
;       PG8_WAIT_V(6); PG8_BAR; PG8_MMA(1, 1, At, B1); PG8_BAR;
;       PG8_LDB(B0, 1, 0); PG8_SCHED; PG8_LDA(At, 1, 0); PG8_STAGE(PG8_SA(0, 1), a2 + hstep, voffA);
;       PG8_WAIT_L(8); PG8_BAR; PG8_WAIT_L(0); PG8_MMA(0, 0, At, B0); PG8_BAR; PG8_SCHED;
.LBB0_1194:
	s_add_u32 s24, s22, 0xfff80080
	s_addc_u32 s25, s23, -1
	s_cmp_eq_u32 s54, 28
	s_cselect_b32 s27, s17, s25
	s_cselect_b32 s26, s43, s24
	s_cselect_b32 s25, s15, s53
	s_cselect_b32 s24, s51, s52
	s_add_i32 m0, s37, 0xc000
	ds_read_b128 v[144:147], v215
	ds_read_b128 v[148:151], v215 offset:1024
	ds_read_b128 v[152:155], v215 offset:2048
	ds_read_b128 v[156:159], v215 offset:3072
	ds_read_b128 v[160:163], v215 offset:4096
	ds_read_b128 v[164:167], v215 offset:5120
	ds_read_b128 v[168:171], v215 offset:6144
	ds_read_b128 v[172:175], v215 offset:7168
	global_load_lds_dwordx4 v184, s[22:23]
	s_add_i32 m0, s37, 0xe000
	s_nop 0
	global_load_lds_dwordx4 v186, s[22:23]
	s_waitcnt lgkmcnt(0)
	s_setprio 1
	s_barrier
	v_mfma_f32_16x16x32_bf16 v[124:127], v[128:131], v[144:147], v[124:127]
	v_mfma_f32_16x16x32_bf16 v[120:123], v[136:139], v[144:147], v[120:123]
	v_mfma_f32_16x16x32_bf16 v[108:111], v[128:131], v[152:155], v[108:111]
	v_mfma_f32_16x16x32_bf16 v[104:107], v[136:139], v[152:155], v[104:107]
	v_mfma_f32_16x16x32_bf16 v[92:95], v[128:131], v[160:163], v[92:95]
	v_mfma_f32_16x16x32_bf16 v[88:91], v[136:139], v[160:163], v[88:91]
	v_mfma_f32_16x16x32_bf16 v[76:79], v[128:131], v[168:171], v[76:79]
	v_mfma_f32_16x16x32_bf16 v[72:75], v[136:139], v[168:171], v[72:75]
	v_mfma_f32_16x16x32_bf16 v[124:127], v[132:135], v[148:151], v[124:127]
	v_mfma_f32_16x16x32_bf16 v[120:123], v[140:143], v[148:151], v[120:123]
	v_mfma_f32_16x16x32_bf16 v[108:111], v[132:135], v[156:159], v[108:111]
	v_mfma_f32_16x16x32_bf16 v[104:107], v[140:143], v[156:159], v[104:107]
	v_mfma_f32_16x16x32_bf16 v[92:95], v[132:135], v[164:167], v[92:95]
	v_mfma_f32_16x16x32_bf16 v[88:91], v[140:143], v[164:167], v[88:91]
	v_mfma_f32_16x16x32_bf16 v[76:79], v[132:135], v[172:175], v[76:79]
	v_mfma_f32_16x16x32_bf16 v[72:75], v[140:143], v[172:175], v[72:75]
	s_barrier
	s_setprio 0
	s_add_i32 s55, s48, s35
	s_add_u32 s98, s24, 0x80
	s_addc_u32 s99, s25, 0
	s_mov_b32 m0, s55
	ds_read_b128 v[192:195], v216
	ds_read_b128 v[196:199], v216 offset:1024
	ds_read_b128 v[200:203], v216 offset:2048
	ds_read_b128 v[204:207], v216 offset:3072
	global_load_lds_dwordx4 v180, s[24:25]
	s_add_i32 m0, s55, 0x2000
	s_nop 0
	global_load_lds_dwordx4 v176, s[24:25]
	s_waitcnt lgkmcnt(0)
	s_setprio 1
	s_barrier
	v_mfma_f32_16x16x32_bf16 v[116:119], v[192:195], v[144:147], v[116:119]
	v_mfma_f32_16x16x32_bf16 v[112:115], v[200:203], v[144:147], v[112:115]
	v_mfma_f32_16x16x32_bf16 v[100:103], v[192:195], v[152:155], v[100:103]
	v_mfma_f32_16x16x32_bf16 v[96:99], v[200:203], v[152:155], v[96:99]
	v_mfma_f32_16x16x32_bf16 v[84:87], v[192:195], v[160:163], v[84:87]
	v_mfma_f32_16x16x32_bf16 v[80:83], v[200:203], v[160:163], v[80:83]
	v_mfma_f32_16x16x32_bf16 v[68:71], v[192:195], v[168:171], v[68:71]
	v_mfma_f32_16x16x32_bf16 v[64:67], v[200:203], v[168:171], v[64:67]
	v_mfma_f32_16x16x32_bf16 v[116:119], v[196:199], v[148:151], v[116:119]
	v_mfma_f32_16x16x32_bf16 v[112:115], v[204:207], v[148:151], v[112:115]
	v_mfma_f32_16x16x32_bf16 v[100:103], v[196:199], v[156:159], v[100:103]
	v_mfma_f32_16x16x32_bf16 v[96:99], v[204:207], v[156:159], v[96:99]
	v_mfma_f32_16x16x32_bf16 v[84:87], v[196:199], v[164:167], v[84:87]
	v_mfma_f32_16x16x32_bf16 v[80:83], v[204:207], v[164:167], v[80:83]
	v_mfma_f32_16x16x32_bf16 v[68:71], v[196:199], v[172:175], v[68:71]
	v_mfma_f32_16x16x32_bf16 v[64:67], v[204:207], v[172:175], v[64:67]
	s_barrier
	s_setprio 0
	s_mov_b32 m0, s37
	s_add_u32 s100, s26, 0x80
	s_addc_u32 s101, s27, 0
	ds_read_b128 v[144:147], v215 offset:16384
	ds_read_b128 v[148:151], v215 offset:17408
	ds_read_b128 v[152:155], v215 offset:18432
	ds_read_b128 v[156:159], v215 offset:19456
	ds_read_b128 v[160:163], v215 offset:20480
	ds_read_b128 v[164:167], v215 offset:21504
	ds_read_b128 v[168:171], v215 offset:22528
	ds_read_b128 v[172:175], v215 offset:23552
	global_load_lds_dwordx4 v182, s[26:27]
	s_mov_b32 m0, s38
	s_nop 0
	global_load_lds_dwordx4 v178, s[26:27]
	s_waitcnt vmcnt(10)
	s_waitcnt lgkmcnt(0)
	s_setprio 1
	s_barrier
	v_mfma_f32_16x16x32_bf16 v[60:63], v[128:131], v[144:147], v[60:63]
	v_mfma_f32_16x16x32_bf16 v[56:59], v[136:139], v[144:147], v[56:59]
	v_mfma_f32_16x16x32_bf16 v[44:47], v[128:131], v[152:155], v[44:47]
	v_mfma_f32_16x16x32_bf16 v[40:43], v[136:139], v[152:155], v[40:43]
	v_mfma_f32_16x16x32_bf16 v[28:31], v[128:131], v[160:163], v[28:31]
	v_mfma_f32_16x16x32_bf16 v[24:27], v[136:139], v[160:163], v[24:27]
	v_mfma_f32_16x16x32_bf16 v[12:15], v[128:131], v[168:171], v[12:15]
	v_mfma_f32_16x16x32_bf16 v[8:11], v[136:139], v[168:171], v[8:11]
	v_mfma_f32_16x16x32_bf16 v[60:63], v[132:135], v[148:151], v[60:63]
	v_mfma_f32_16x16x32_bf16 v[56:59], v[140:143], v[148:151], v[56:59]
	v_mfma_f32_16x16x32_bf16 v[44:47], v[132:135], v[156:159], v[44:47]
	v_mfma_f32_16x16x32_bf16 v[40:43], v[140:143], v[156:159], v[40:43]
	v_mfma_f32_16x16x32_bf16 v[28:31], v[132:135], v[164:167], v[28:31]
	v_mfma_f32_16x16x32_bf16 v[24:27], v[140:143], v[164:167], v[24:27]
	v_mfma_f32_16x16x32_bf16 v[12:15], v[132:135], v[172:175], v[12:15]
	v_mfma_f32_16x16x32_bf16 v[8:11], v[140:143], v[172:175], v[8:11]
	s_barrier
	s_setprio 0
	s_add_u32 s56, s24, 0x80000
	s_addc_u32 s57, s25, 0
	s_add_i32 s55, s49, s35
	s_mov_b32 m0, s55
	s_nop 0
	global_load_lds_dwordx4 v180, s[56:57]
	s_add_i32 m0, s55, 0x2000
	s_nop 0
	global_load_lds_dwordx4 v176, s[56:57]
	s_add_i32 s55, 0, 0x18000
	v_add_u32_e32 v140, s55, v212
	ds_read_b128 v[128:131], v140
	ds_read_b128 v[132:135], v140 offset:1024
	ds_read_b128 v[136:139], v140 offset:2048
	ds_read_b128 v[140:143], v140 offset:3072
	s_waitcnt vmcnt(6)
	s_setprio 1
	s_barrier
; #define PG8_STAGE(bufoff, gbase, voff) do { _Pragma("unroll") for (int _i = 0; _i < 2; ++_i) \
;     __builtin_amdgcn_global_load_lds((const unsigned*)((const char*)(gbase) + (voff)[_i]), (LAS unsigned*)(lds + (bufoff) + ldsw + _i * 8192), 16, 0, 0); } while (0)
; #define PG8_LDA(dst, b, h) do { _Pragma("unroll") for (int m = 0; m < 4; ++m) _Pragma("unroll") for (int k = 0; k < 2; ++k) dst[m][k] = *(const LAS bf16x8*)(lds + PG8_SA(b, h) + aoff + m * 2048 + k * 1024); } while (0)
; #define PG8_LDB(dst, b, h) do { _Pragma("unroll") for (int n = 0; n < 2; ++n) _Pragma("unroll") for (int k = 0; k < 2; ++k) dst[n][k] = *(const LAS bf16x8*)(lds + PG8_SB(b, h) + boff + n * 2048 + k * 1024); } while (0)
; #define PG8_MMA(ai, bj, At, Bt) do { __builtin_amdgcn_s_setprio(1); _Pragma("unroll") for (int m = 0; m < 4; ++m) _Pragma("unroll") for (int n = 0; n < 2; ++n) _Pragma("unroll") for (int k = 0; k < 2; ++k) \
;     acc[ai][bj][m][n] = __builtin_amdgcn_mfma_f32_16x16x32_bf16(Bt[n][k], At[m][k], acc[ai][bj][m][n], 0, 0, 0); __builtin_amdgcn_s_setprio(0); } while (0)
; #define PG8_WAIT_V(n) asm volatile("s_waitcnt vmcnt(" #n ")" ::: "memory")
; #define PG8_WAIT_L(n) asm volatile("s_waitcnt lgkmcnt(" #n ")" ::: "memory")
; #define PG8_BAR __builtin_amdgcn_s_barrier()
; #define PG8_SCHED __builtin_amdgcn_sched_barrier(0)
; template <class Epi, class Sched = StaticOrder>
; DI void gemm_phase(LAS unsigned char* lds, const Gemm g, const Sched& S, const Epi& E) {
;     ...
;       PG8_WAIT_V(6); PG8_BAR; PG8_MMA(1, 1, At, B1); PG8_BAR;
;       PG8_LDB(B0, 1, 0); PG8_SCHED; PG8_LDA(At, 1, 0); PG8_STAGE(PG8_SA(0, 1), a2 + hstep, voffA);
;       PG8_WAIT_L(8); PG8_BAR; PG8_WAIT_L(0); PG8_MMA(0, 0, At, B0); PG8_BAR; PG8_SCHED;
;       PG8_LDB(B1, 1, 1); PG8_STAGE(PG8_SB(1, 0), b3, voffB);
;       PG8_BAR; PG8_WAIT_L(0); PG8_MMA(0, 1, At, B1); PG8_BAR;
;       PG8_LDA(At, 1, 1); PG8_STAGE(PG8_SA(1, 0), a3, voffA);
;       PG8_BAR; PG8_WAIT_L(0); PG8_MMA(1, 0, At, B0); PG8_BAR; PG8_SCHED;
	v_mfma_f32_16x16x32_bf16 v[52:55], v[192:195], v[144:147], v[52:55]
	v_mfma_f32_16x16x32_bf16 v[48:51], v[200:203], v[144:147], v[48:51]
	v_mfma_f32_16x16x32_bf16 v[36:39], v[192:195], v[152:155], v[36:39]
	v_mfma_f32_16x16x32_bf16 v[32:35], v[200:203], v[152:155], v[32:35]
	v_mfma_f32_16x16x32_bf16 v[20:23], v[192:195], v[160:163], v[20:23]
	v_mfma_f32_16x16x32_bf16 v[16:19], v[200:203], v[160:163], v[16:19]
	v_mfma_f32_16x16x32_bf16 v[4:7], v[192:195], v[168:171], v[4:7]
	v_mfma_f32_16x16x32_bf16 v[0:3], v[200:203], v[168:171], v[0:3]
	v_mfma_f32_16x16x32_bf16 v[52:55], v[196:199], v[148:151], v[52:55]
	v_mfma_f32_16x16x32_bf16 v[48:51], v[204:207], v[148:151], v[48:51]
	v_mfma_f32_16x16x32_bf16 v[36:39], v[196:199], v[156:159], v[36:39]
	v_mfma_f32_16x16x32_bf16 v[32:35], v[204:207], v[156:159], v[32:35]
	v_mfma_f32_16x16x32_bf16 v[20:23], v[196:199], v[164:167], v[20:23]
	v_mfma_f32_16x16x32_bf16 v[16:19], v[204:207], v[164:167], v[16:19]
	v_mfma_f32_16x16x32_bf16 v[4:7], v[196:199], v[172:175], v[4:7]
	v_mfma_f32_16x16x32_bf16 v[0:3], v[204:207], v[172:175], v[0:3]
	s_barrier
	s_setprio 0
	s_add_u32 s26, s26, 0x80000
	s_addc_u32 s27, s27, 0
	s_mov_b32 m0, s39
	ds_read_b128 v[144:147], v215 offset:32768
	ds_read_b128 v[148:151], v215 offset:33792
	ds_read_b128 v[152:155], v215 offset:34816
	ds_read_b128 v[156:159], v215 offset:35840
	ds_read_b128 v[160:163], v215 offset:36864
	ds_read_b128 v[164:167], v215 offset:37888
	ds_read_b128 v[168:171], v215 offset:38912
	ds_read_b128 v[172:175], v215 offset:39936
	global_load_lds_dwordx4 v182, s[26:27]
	s_mov_b32 m0, s40
	s_nop 0
	global_load_lds_dwordx4 v178, s[26:27]
	s_waitcnt lgkmcnt(0)
	s_setprio 1
	s_barrier
	v_mfma_f32_16x16x32_bf16 v[124:127], v[128:131], v[144:147], v[124:127]
	v_mfma_f32_16x16x32_bf16 v[120:123], v[136:139], v[144:147], v[120:123]
	v_mfma_f32_16x16x32_bf16 v[108:111], v[128:131], v[152:155], v[108:111]
	v_mfma_f32_16x16x32_bf16 v[104:107], v[136:139], v[152:155], v[104:107]
	v_mfma_f32_16x16x32_bf16 v[92:95], v[128:131], v[160:163], v[92:95]
	v_mfma_f32_16x16x32_bf16 v[88:91], v[136:139], v[160:163], v[88:91]
	v_mfma_f32_16x16x32_bf16 v[76:79], v[128:131], v[168:171], v[76:79]
	v_mfma_f32_16x16x32_bf16 v[72:75], v[136:139], v[168:171], v[72:75]
	v_mfma_f32_16x16x32_bf16 v[124:127], v[132:135], v[148:151], v[124:127]
	v_mfma_f32_16x16x32_bf16 v[120:123], v[140:143], v[148:151], v[120:123]
	v_mfma_f32_16x16x32_bf16 v[108:111], v[132:135], v[156:159], v[108:111]
	v_mfma_f32_16x16x32_bf16 v[104:107], v[140:143], v[156:159], v[104:107]
	v_mfma_f32_16x16x32_bf16 v[92:95], v[132:135], v[164:167], v[92:95]
	v_mfma_f32_16x16x32_bf16 v[88:91], v[140:143], v[164:167], v[88:91]
	v_mfma_f32_16x16x32_bf16 v[76:79], v[132:135], v[172:175], v[76:79]
	v_mfma_f32_16x16x32_bf16 v[72:75], v[140:143], v[172:175], v[72:75]
	s_barrier
	s_setprio 0
	s_add_i32 s26, 0, 0x1c000
	s_add_i32 s27, s55, s35
	v_add_u32_e32 v204, s26, v212
	s_mov_b32 m0, s27
	ds_read_b128 v[192:195], v204
	ds_read_b128 v[196:199], v204 offset:1024
	ds_read_b128 v[200:203], v204 offset:2048
	ds_read_b128 v[204:207], v204 offset:3072
	global_load_lds_dwordx4 v180, s[98:99]
	s_add_i32 m0, s27, 0x2000
	s_nop 0
	global_load_lds_dwordx4 v176, s[98:99]
	s_waitcnt lgkmcnt(0)
	s_setprio 1
	s_barrier
	v_mfma_f32_16x16x32_bf16 v[116:119], v[192:195], v[144:147], v[116:119]
	v_mfma_f32_16x16x32_bf16 v[112:115], v[200:203], v[144:147], v[112:115]
	v_mfma_f32_16x16x32_bf16 v[100:103], v[192:195], v[152:155], v[100:103]
	v_mfma_f32_16x16x32_bf16 v[96:99], v[200:203], v[152:155], v[96:99]
	v_mfma_f32_16x16x32_bf16 v[84:87], v[192:195], v[160:163], v[84:87]
	v_mfma_f32_16x16x32_bf16 v[80:83], v[200:203], v[160:163], v[80:83]
	v_mfma_f32_16x16x32_bf16 v[68:71], v[192:195], v[168:171], v[68:71]
	v_mfma_f32_16x16x32_bf16 v[64:67], v[200:203], v[168:171], v[64:67]
	v_mfma_f32_16x16x32_bf16 v[116:119], v[196:199], v[148:151], v[116:119]
	v_mfma_f32_16x16x32_bf16 v[112:115], v[204:207], v[148:151], v[112:115]
	v_mfma_f32_16x16x32_bf16 v[100:103], v[196:199], v[156:159], v[100:103]
	v_mfma_f32_16x16x32_bf16 v[96:99], v[204:207], v[156:159], v[96:99]
	v_mfma_f32_16x16x32_bf16 v[84:87], v[196:199], v[164:167], v[84:87]
	v_mfma_f32_16x16x32_bf16 v[80:83], v[204:207], v[164:167], v[80:83]
	v_mfma_f32_16x16x32_bf16 v[68:71], v[196:199], v[172:175], v[68:71]
	v_mfma_f32_16x16x32_bf16 v[64:67], v[204:207], v[172:175], v[64:67]
	s_barrier
	s_setprio 0
	s_mov_b32 m0, s44
	ds_read_b128 v[144:147], v215 offset:49152
	ds_read_b128 v[148:151], v215 offset:50176
	ds_read_b128 v[152:155], v215 offset:51200
	ds_read_b128 v[156:159], v215 offset:52224
	ds_read_b128 v[160:163], v215 offset:53248
	ds_read_b128 v[164:167], v215 offset:54272
	ds_read_b128 v[168:171], v215 offset:55296
	ds_read_b128 v[172:175], v215 offset:56320
	global_load_lds_dwordx4 v182, s[100:101]
	s_mov_b32 m0, s45
	s_nop 0
	global_load_lds_dwordx4 v178, s[100:101]
	s_waitcnt vmcnt(10)
	s_waitcnt lgkmcnt(0)
	s_setprio 1
	s_barrier
	v_mfma_f32_16x16x32_bf16 v[60:63], v[128:131], v[144:147], v[60:63]
	v_mfma_f32_16x16x32_bf16 v[56:59], v[136:139], v[144:147], v[56:59]
	v_mfma_f32_16x16x32_bf16 v[44:47], v[128:131], v[152:155], v[44:47]
	v_mfma_f32_16x16x32_bf16 v[40:43], v[136:139], v[152:155], v[40:43]
	v_mfma_f32_16x16x32_bf16 v[28:31], v[128:131], v[160:163], v[28:31]
	v_mfma_f32_16x16x32_bf16 v[24:27], v[136:139], v[160:163], v[24:27]
	v_mfma_f32_16x16x32_bf16 v[12:15], v[128:131], v[168:171], v[12:15]
	v_mfma_f32_16x16x32_bf16 v[8:11], v[136:139], v[168:171], v[8:11]
	v_mfma_f32_16x16x32_bf16 v[60:63], v[132:135], v[148:151], v[60:63]
	v_mfma_f32_16x16x32_bf16 v[56:59], v[140:143], v[148:151], v[56:59]
	v_mfma_f32_16x16x32_bf16 v[44:47], v[132:135], v[156:159], v[44:47]
	v_mfma_f32_16x16x32_bf16 v[40:43], v[140:143], v[156:159], v[40:43]
	v_mfma_f32_16x16x32_bf16 v[28:31], v[132:135], v[164:167], v[28:31]
	v_mfma_f32_16x16x32_bf16 v[24:27], v[140:143], v[164:167], v[24:27]
	v_mfma_f32_16x16x32_bf16 v[12:15], v[132:135], v[172:175], v[12:15]
	v_mfma_f32_16x16x32_bf16 v[8:11], v[140:143], v[172:175], v[8:11]
	s_barrier
; DI unsigned pack2(float lo, float hi) { f32x2 v = {lo, hi}; bf16v2 r = __builtin_convertvector(v, bf16v2); return __builtin_bit_cast(unsigned, r); }
; #define PG8_STAGE(bufoff, gbase, voff) do { _Pragma("unroll") for (int _i = 0; _i < 2; ++_i) \
;     __builtin_amdgcn_global_load_lds((const unsigned*)((const char*)(gbase) + (voff)[_i]), (LAS unsigned*)(lds + (bufoff) + ldsw + _i * 8192), 16, 0, 0); } while (0)
; #define PG8_WAIT_V(n) asm volatile("s_waitcnt vmcnt(" #n ")" ::: "memory")
; #define PG8_BAR __builtin_amdgcn_s_barrier()
;   DI void operator()(const f32x4 (&acc)[2][2][4][2], const Unit& u, int wr, int wc, int fr, int fq) const {
;     const int row0 = u.pm * BM + wr * 64 + fr, col0 = u.pn * BM + wc * 32 + 8 * fq;
; #pragma unroll
;     for (int ai = 0; ai < 2; ++ai) {
;       f32x4 bv[4][2][2];
; #pragma unroll
;       for (int m = 0; m < 4; ++m)
; #pragma unroll
;         for (int bj = 0; bj < 2; ++bj) {
;           const float* bp = base + (size_t)(row0 + ai * HALF + m * 16) * 2048 + col0 + bj * HALF;
;           bv[m][bj][0] = *(const f32x4*)bp; bv[m][bj][1] = *(const f32x4*)(bp + 4);
;         }
; #pragma unroll
;       for (int m = 0; m < 4; ++m) {
;         const int row = row0 + ai * HALF + m * 16;
;         const size_t off = (size_t)row * 2048 + col0;
;         float ss = 0.f;
; #pragma unroll
;         for (int bj = 0; bj < 2; ++bj) {
;           const f32x4 v0 = acc[ai][bj][m][0] + bv[m][bj][0], v1 = acc[ai][bj][m][1] + bv[m][bj][1];
;           *(f32x4*)(C + off + bj * HALF) = v0; *(f32x4*)(C + off + bj * HALF + 4) = v1;
;           if (xb) {
;             u32x4 w; w.x = pack2(v0[0], v0[1]); w.y = pack2(v0[2], v0[3]); w.z = pack2(v1[0], v1[1]); w.w = pack2(v1[2], v1[3]);
;             *(u32x4*)(xb + off + bj * HALF) = w;
;             ss += v0[0] * v0[0] + v0[1] * v0[1] + v0[2] * v0[2] + v0[3] * v0[3] + v1[0] * v1[0] + v1[1] * v1[1] + v1[2] * v1[2] + v1[3] * v1[3];
;           }
;         }
;         if (xb) {
;           ss += __shfl_xor(ss, 16); ss += __shfl_xor(ss, 32);
;           if (fq == 0) ssq[(size_t)row * 32 + u.pn * 4 + wc] = ss;
; template <class Epi, class Sched = StaticOrder>
; DI void gemm_phase(LAS unsigned char* lds, const Gemm g, const Sched& S, const Epi& E) {
;     ...
;       PG8_STAGE(PG8_SB(1, 1), b3 + hstep, voffB);
;       PG8_WAIT_V(6); PG8_BAR; PG8_MMA(1, 1, At, B1); PG8_BAR;
	s_setprio 0
	s_add_u32 s24, s24, 0x80080
	s_addc_u32 s25, s25, 0
	s_add_i32 s26, s26, s35
	s_mov_b32 m0, s26
	s_nop 0
	global_load_lds_dwordx4 v180, s[24:25]
	s_add_i32 m0, s26, 0x2000
	s_nop 0
	global_load_lds_dwordx4 v176, s[24:25]
	ds_read_b128 v[128:131], v214
	ds_read_b128 v[132:135], v214 offset:1024
	ds_read_b128 v[136:139], v214 offset:2048
	ds_read_b128 v[140:143], v214 offset:3072
	s_waitcnt vmcnt(6)
	s_setprio 1
	s_barrier
	v_mfma_f32_16x16x32_bf16 v[52:55], v[192:195], v[144:147], v[52:55]
	v_mfma_f32_16x16x32_bf16 v[48:51], v[200:203], v[144:147], v[48:51]
	v_mfma_f32_16x16x32_bf16 v[36:39], v[192:195], v[152:155], v[36:39]
	v_mfma_f32_16x16x32_bf16 v[32:35], v[200:203], v[152:155], v[32:35]
	v_mfma_f32_16x16x32_bf16 v[20:23], v[192:195], v[160:163], v[20:23]
	v_mfma_f32_16x16x32_bf16 v[16:19], v[200:203], v[160:163], v[16:19]
	v_mfma_f32_16x16x32_bf16 v[4:7], v[192:195], v[168:171], v[4:7]
	v_mfma_f32_16x16x32_bf16 v[0:3], v[200:203], v[168:171], v[0:3]
	v_mfma_f32_16x16x32_bf16 v[52:55], v[196:199], v[148:151], v[52:55]
	v_mfma_f32_16x16x32_bf16 v[48:51], v[204:207], v[148:151], v[48:51]
	v_mfma_f32_16x16x32_bf16 v[36:39], v[196:199], v[156:159], v[36:39]
	v_mfma_f32_16x16x32_bf16 v[32:35], v[204:207], v[156:159], v[32:35]
	v_mfma_f32_16x16x32_bf16 v[20:23], v[196:199], v[164:167], v[20:23]
	v_mfma_f32_16x16x32_bf16 v[16:19], v[204:207], v[164:167], v[16:19]
	v_mfma_f32_16x16x32_bf16 v[4:7], v[196:199], v[172:175], v[4:7]
	v_mfma_f32_16x16x32_bf16 v[0:3], v[204:207], v[172:175], v[0:3]
	s_add_i32 s54, s54, 2
	s_add_u32 s22, s22, 0x100
	s_addc_u32 s23, s23, 0
	s_add_u32 s52, s52, 0x100
	s_addc_u32 s53, s53, 0
	s_cmp_gt_u32 s54, 29
	s_barrier
	s_setprio 0
	s_cbranch_scc0 .LBB0_1194
	s_waitcnt lgkmcnt(0)
	v_lshl_add_u32 v194, s12, 8, v211
	v_lshl_or_b32 v192, s42, 8, v213
	v_readlane_b32 s52, v243, 3
	v_ashrrev_i32_e32 v193, 31, v192
	v_readlane_b32 s66, v243, 17
	v_readlane_b32 s67, v243, 18
	v_ashrrev_i32_e32 v195, 31, v194
	v_lshlrev_b64 v[128:129], 13, v[194:195]
	v_lshl_add_u64 v[196:197], v[192:193], 2, s[66:67]
	v_lshl_add_u64 v[236:237], v[196:197], 0, v[128:129]
	global_load_dwordx4 v[220:223], v[236:237], off
	global_load_dwordx4 v[224:227], v[236:237], off offset:16
	global_load_dwordx4 v[228:231], v[236:237], off offset:512
	global_load_dwordx4 v[232:235], v[236:237], off offset:528
	v_or_b32_e32 v206, 16, v194
	v_or_b32_e32 v202, 32, v194
	v_or_b32_e32 v198, 48, v194
	v_ashrrev_i32_e32 v207, 31, v206
	v_ashrrev_i32_e32 v203, 31, v202
	v_ashrrev_i32_e32 v199, 31, v198
	v_lshlrev_b64 v[128:129], 13, v[206:207]
	v_lshlrev_b64 v[130:131], 13, v[202:203]
	v_lshlrev_b64 v[132:133], 13, v[198:199]
	v_lshl_add_u64 v[208:209], v[196:197], 0, v[128:129]
	v_lshl_add_u64 v[204:205], v[196:197], 0, v[130:131]
	v_lshl_add_u64 v[200:201], v[196:197], 0, v[132:133]
	global_load_dwordx4 v[168:171], v[208:209], off offset:16
	global_load_dwordx4 v[172:175], v[208:209], off
	global_load_dwordx4 v[160:163], v[208:209], off offset:528
	global_load_dwordx4 v[164:167], v[208:209], off offset:512
	global_load_dwordx4 v[152:155], v[204:205], off offset:16
	global_load_dwordx4 v[156:159], v[204:205], off
	global_load_dwordx4 v[144:147], v[204:205], off offset:528
	global_load_dwordx4 v[148:151], v[204:205], off offset:512
	global_load_dwordx4 v[136:139], v[200:201], off offset:16
	global_load_dwordx4 v[140:143], v[200:201], off
	global_load_dwordx4 v[128:131], v[200:201], off offset:528
	global_load_dwordx4 v[132:135], v[200:201], off offset:512
	v_and_b32_e32 v218, 64, v217
	v_xor_b32_e32 v238, 16, v217
	v_add_u32_e32 v240, 64, v218
	v_xor_b32_e32 v239, 32, v217
	v_cmp_lt_i32_e32 vcc, v238, v240
	v_lshlrev_b64 v[218:219], 11, v[194:195]
	s_lshl_b32 s22, s42, 2
	v_cndmask_b32_e32 v241, v217, v238, vcc
	v_cmp_lt_i32_e32 vcc, v239, v240
	s_ashr_i32 s23, s22, 31
	v_readlane_b32 s53, v243, 4
	v_cndmask_b32_e32 v240, v217, v239, vcc
	v_lshl_add_u64 v[238:239], v[218:219], 0, v[192:193]
	v_lshlrev_b32_e32 v218, 2, v241
	v_lshl_add_u64 v[238:239], v[238:239], 1, s[2:3]
	v_readlane_b32 s54, v243, 5
	v_readlane_b32 s55, v243, 6
	v_readlane_b32 s56, v243, 7
	v_readlane_b32 s57, v243, 8
	v_readlane_b32 s58, v243, 9
	v_readlane_b32 s59, v243, 10
	v_readlane_b32 s60, v243, 11
	v_readlane_b32 s61, v243, 12
	v_readlane_b32 s62, v243, 13
	v_readlane_b32 s63, v243, 14
	v_readlane_b32 s64, v243, 15
	v_readlane_b32 s65, v243, 16
	s_waitcnt vmcnt(0)
	v_pk_add_f32 v[126:127], v[126:127], v[222:223]
	v_pk_add_f32 v[124:125], v[124:125], v[220:221]
	v_pk_add_f32 v[116:117], v[116:117], v[228:229]
	v_pk_add_f32 v[122:123], v[122:123], v[226:227]
	v_pk_add_f32 v[120:121], v[120:121], v[224:225]
	v_pk_add_f32 v[220:221], v[112:113], v[232:233]
	global_store_dwordx4 v[236:237], v[124:127], off
	global_store_dwordx4 v[236:237], v[120:123], off offset:16
	v_cvt_pk_bf16_f32 v112, v124, v125
	v_mul_f32_e32 v125, v125, v125
	v_mul_f32_e32 v219, v117, v117
	v_pk_add_f32 v[118:119], v[118:119], v[230:231]
	v_fmac_f32_e32 v125, v124, v124
	v_fmac_f32_e32 v219, v116, v116
	v_fmac_f32_e32 v125, v126, v126
	v_fmac_f32_e32 v219, v118, v118
	v_fmac_f32_e32 v125, v127, v127
	v_fmac_f32_e32 v219, v119, v119
	v_fmac_f32_e32 v125, v120, v120
	v_fmac_f32_e32 v219, v220, v220
	v_pk_add_f32 v[222:223], v[114:115], v[234:235]
	v_fmac_f32_e32 v125, v121, v121
	v_fmac_f32_e32 v219, v221, v221
	v_fmac_f32_e32 v125, v122, v122
	v_fmac_f32_e32 v219, v222, v222
	v_fmac_f32_e32 v125, v123, v123
	v_fmac_f32_e32 v219, v223, v223
	v_cvt_pk_bf16_f32 v114, v120, v121
	v_add_f32_e32 v121, v125, v219
	v_cvt_pk_bf16_f32 v115, v122, v123
	ds_bpermute_b32 v122, v218, v121
	v_cvt_pk_bf16_f32 v113, v126, v127
	global_store_dwordx4 v[238:239], v[112:115], off
	global_store_dwordx4 v[236:237], v[116:119], off offset:512
	global_store_dwordx4 v[236:237], v[220:223], off offset:528
	v_lshlrev_b32_e32 v126, 2, v240
	v_cvt_pk_bf16_f32 v120, v116, v117
	s_waitcnt lgkmcnt(0)
	v_add_f32_e32 v112, v121, v122
	ds_bpermute_b32 v113, v126, v112
	v_cvt_pk_bf16_f32 v121, v118, v119
	v_cvt_pk_bf16_f32 v122, v220, v221
	v_cvt_pk_bf16_f32 v123, v222, v223
	global_store_dwordx4 v[238:239], v[120:123], off offset:256
	s_and_saveexec_b64 s[24:25], s[0:1]
	s_cbranch_execz .LBB0_1197
	s_waitcnt lgkmcnt(0)
	v_add_f32_e32 v114, v112, v113
	v_lshlrev_b64 v[112:113], 7, v[194:195]
	v_lshl_add_u64 v[112:113], s[8:9], 0, v[112:113]
	v_lshl_add_u64 v[112:113], s[22:23], 2, v[112:113]
	s_lshl_b32 s12, s41, 2
	v_lshl_add_u64 v[112:113], v[112:113], 0, s[12:13]
	global_store_dword v[112:113], v114, off

; #define PG8_STAGE(bufoff, gbase, voff) do { _Pragma("unroll") for (int _i = 0; _i < 2; ++_i) \
;     __builtin_amdgcn_global_load_lds((const unsigned*)((const char*)(gbase) + (voff)[_i]), (LAS unsigned*)(lds + (bufoff) + ldsw + _i * 8192), 16, 0, 0); } while (0)
; #define PG8_LDA(dst, b, h) do { _Pragma("unroll") for (int m = 0; m < 4; ++m) _Pragma("unroll") for (int k = 0; k < 2; ++k) dst[m][k] = *(const LAS bf16x8*)(lds + PG8_SA(b, h) + aoff + m * 2048 + k * 1024); } while (0)
; #define PG8_LDB(dst, b, h) do { _Pragma("unroll") for (int n = 0; n < 2; ++n) _Pragma("unroll") for (int k = 0; k < 2; ++k) dst[n][k] = *(const LAS bf16x8*)(lds + PG8_SB(b, h) + boff + n * 2048 + k * 1024); } while (0)
; #define PG8_MMA(ai, bj, At, Bt) do { __builtin_amdgcn_s_setprio(1); _Pragma("unroll") for (int m = 0; m < 4; ++m) _Pragma("unroll") for (int n = 0; n < 2; ++n) _Pragma("unroll") for (int k = 0; k < 2; ++k) \
;     acc[ai][bj][m][n] = __builtin_amdgcn_mfma_f32_16x16x32_bf16(Bt[n][k], At[m][k], acc[ai][bj][m][n], 0, 0, 0); __builtin_amdgcn_s_setprio(0); } while (0)
; #define PG8_WAIT_V(n) asm volatile("s_waitcnt vmcnt(" #n ")" ::: "memory")
; template <class Epi, class Sched = StaticOrder>
; DI void gemm_phase(LAS unsigned char* lds, const Gemm g, const Sched& S, const Epi& E) {
;     ...
;     for (int t = 0; t < nt; t += 2) {
;       const bool last = (t == nt - 2);
;       const char* a1 = cA + (size_t)(t + 1) * kstep;
;       const char* a2 = last ? nA : cA + (size_t)(t + 2) * kstep; const char* b2 = last ? nB : cB + (size_t)(t + 2) * kstep;
;       const char* a3 = a2 + kstep; const char* b3 = b2 + kstep;
;       PG8_LDB(B0, 0, 0); PG8_SCHED; PG8_LDA(At, 0, 0); PG8_STAGE(PG8_SA(1, 1), a1 + hstep, voffA);
;       PG8_WAIT_L(8); PG8_BAR; PG8_WAIT_L(0); PG8_MMA(0, 0, At, B0); PG8_BAR; PG8_SCHED;
;       PG8_LDB(B1, 0, 1); PG8_STAGE(PG8_SB(0, 0), b2, voffB);
;       PG8_BAR; PG8_WAIT_L(0); PG8_MMA(0, 1, At, B1); PG8_BAR;
;       PG8_LDA(At, 0, 1); PG8_STAGE(PG8_SA(0, 0), a2, voffA);
;       PG8_BAR; PG8_WAIT_L(0); PG8_MMA(1, 0, At, B0); PG8_BAR; PG8_SCHED;
;       PG8_STAGE(PG8_SB(0, 1), b2 + hstep, voffB);
;       PG8_WAIT_V(6); PG8_BAR; PG8_MMA(1, 1, At, B1); PG8_BAR;
;       PG8_LDB(B0, 1, 0); PG8_SCHED; PG8_LDA(At, 1, 0); PG8_STAGE(PG8_SA(0, 1), a2 + hstep, voffA);
;       PG8_WAIT_L(8); PG8_BAR; PG8_WAIT_L(0); PG8_MMA(0, 0, At, B0); PG8_BAR; PG8_SCHED;
.LBB0_1277:
	s_add_u32 s48, s14, 0xfff80080
	s_addc_u32 s49, s15, -1
	s_cmp_eq_u32 s58, 28
	s_cselect_b32 s51, s41, s49
	s_cselect_b32 s50, s42, s48
	s_cselect_b32 s49, s39, s53
	s_cselect_b32 s48, s43, s52
	s_add_i32 m0, s64, 0xc000
	ds_read_b128 v[80:83], v202
	ds_read_b128 v[84:87], v202 offset:1024
	ds_read_b128 v[88:91], v202 offset:2048
	ds_read_b128 v[92:95], v202 offset:3072
	ds_read_b128 v[180:183], v202 offset:4096
	ds_read_b128 v[184:187], v202 offset:5120
	ds_read_b128 v[188:191], v202 offset:6144
	ds_read_b128 v[192:195], v202 offset:7168
	global_load_lds_dwordx4 v170, s[14:15]
	s_add_i32 m0, s64, 0xe000
	s_nop 0
	global_load_lds_dwordx4 v172, s[14:15]
	s_waitcnt lgkmcnt(0)
	s_setprio 1
	s_barrier
	v_mfma_f32_16x16x32_bf16 v[156:159], v[64:67], v[80:83], v[156:159]
	v_mfma_f32_16x16x32_bf16 v[144:147], v[72:75], v[80:83], v[144:147]
	v_mfma_f32_16x16x32_bf16 v[140:143], v[64:67], v[88:91], v[140:143]
	v_mfma_f32_16x16x32_bf16 v[132:135], v[72:75], v[88:91], v[132:135]
	v_mfma_f32_16x16x32_bf16 v[124:127], v[64:67], v[180:183], v[124:127]
	v_mfma_f32_16x16x32_bf16 v[116:119], v[72:75], v[180:183], v[116:119]
	v_mfma_f32_16x16x32_bf16 v[112:115], v[64:67], v[188:191], v[112:115]
	v_mfma_f32_16x16x32_bf16 v[108:111], v[72:75], v[188:191], v[108:111]
	v_mfma_f32_16x16x32_bf16 v[156:159], v[68:71], v[84:87], v[156:159]
	v_mfma_f32_16x16x32_bf16 v[144:147], v[76:79], v[84:87], v[144:147]
	v_mfma_f32_16x16x32_bf16 v[140:143], v[68:71], v[92:95], v[140:143]
	v_mfma_f32_16x16x32_bf16 v[132:135], v[76:79], v[92:95], v[132:135]
	v_mfma_f32_16x16x32_bf16 v[124:127], v[68:71], v[184:187], v[124:127]
	v_mfma_f32_16x16x32_bf16 v[116:119], v[76:79], v[184:187], v[116:119]
	v_mfma_f32_16x16x32_bf16 v[112:115], v[68:71], v[192:195], v[112:115]
	v_mfma_f32_16x16x32_bf16 v[108:111], v[76:79], v[192:195], v[108:111]
	s_barrier
	s_setprio 0
	s_add_i32 s59, s72, s62
	s_add_u32 s98, s48, 0x80
	s_addc_u32 s99, s49, 0
	s_mov_b32 m0, s59
	ds_read_b128 v[206:209], v203
	ds_read_b128 v[212:215], v203 offset:1024
	ds_read_b128 v[216:219], v203 offset:2048
	ds_read_b128 v[220:223], v203 offset:3072
	global_load_lds_dwordx4 v164, s[48:49]
	s_add_i32 m0, s59, 0x2000
	s_nop 0
	global_load_lds_dwordx4 v160, s[48:49]
	s_waitcnt lgkmcnt(0)
	s_setprio 1
	s_barrier
	v_mfma_f32_16x16x32_bf16 v[152:155], v[206:209], v[80:83], v[152:155]
	v_mfma_f32_16x16x32_bf16 v[80:83], v[216:219], v[80:83], v[148:151]
	v_mfma_f32_16x16x32_bf16 v[152:155], v[212:215], v[84:87], v[152:155]
	v_mfma_f32_16x16x32_bf16 v[80:83], v[220:223], v[84:87], v[80:83]
	v_mfma_f32_16x16x32_bf16 v[84:87], v[206:209], v[88:91], v[136:139]
	v_mfma_f32_16x16x32_bf16 v[88:91], v[216:219], v[88:91], v[128:131]
	v_mfma_f32_16x16x32_bf16 v[104:107], v[216:219], v[180:183], v[104:107]
	v_mfma_f32_16x16x32_bf16 v[100:103], v[206:209], v[188:191], v[100:103]
	v_mfma_f32_16x16x32_bf16 v[96:99], v[216:219], v[188:191], v[96:99]
	v_mfma_f32_16x16x32_bf16 v[84:87], v[212:215], v[92:95], v[84:87]
	v_mfma_f32_16x16x32_bf16 v[88:91], v[220:223], v[92:95], v[88:91]
	v_mfma_f32_16x16x32_bf16 v[92:95], v[206:209], v[180:183], v[120:123]
	v_mfma_f32_16x16x32_bf16 v[104:107], v[220:223], v[184:187], v[104:107]
	v_mfma_f32_16x16x32_bf16 v[100:103], v[212:215], v[192:195], v[100:103]
	v_mfma_f32_16x16x32_bf16 v[96:99], v[220:223], v[192:195], v[96:99]
	v_mfma_f32_16x16x32_bf16 v[92:95], v[212:215], v[184:187], v[92:95]
	s_barrier
	s_setprio 0
	s_mov_b32 m0, s64
	s_add_u32 s100, s50, 0x80
	s_addc_u32 s101, s51, 0
	ds_read_b128 v[120:123], v202 offset:16384
	ds_read_b128 v[128:131], v202 offset:17408
	ds_read_b128 v[136:139], v202 offset:18432
	ds_read_b128 v[148:151], v202 offset:19456
	ds_read_b128 v[180:183], v202 offset:20480
	ds_read_b128 v[184:187], v202 offset:21504
	ds_read_b128 v[188:191], v202 offset:22528
	ds_read_b128 v[192:195], v202 offset:23552
	global_load_lds_dwordx4 v166, s[50:51]
	s_mov_b32 m0, s65
	s_nop 0
	global_load_lds_dwordx4 v162, s[50:51]
	s_waitcnt vmcnt(10)
	s_waitcnt lgkmcnt(0)
	s_setprio 1
	s_barrier
	v_mfma_f32_16x16x32_bf16 v[60:63], v[64:67], v[120:123], v[60:63]
	v_mfma_f32_16x16x32_bf16 v[48:51], v[72:75], v[120:123], v[48:51]
	v_mfma_f32_16x16x32_bf16 v[44:47], v[64:67], v[136:139], v[44:47]
	v_mfma_f32_16x16x32_bf16 v[36:39], v[72:75], v[136:139], v[36:39]
	v_mfma_f32_16x16x32_bf16 v[28:31], v[64:67], v[180:183], v[28:31]
	v_mfma_f32_16x16x32_bf16 v[20:23], v[72:75], v[180:183], v[20:23]
	v_mfma_f32_16x16x32_bf16 v[16:19], v[64:67], v[188:191], v[16:19]
	v_mfma_f32_16x16x32_bf16 v[12:15], v[72:75], v[188:191], v[12:15]
	v_mfma_f32_16x16x32_bf16 v[60:63], v[68:71], v[128:131], v[60:63]
	v_mfma_f32_16x16x32_bf16 v[48:51], v[76:79], v[128:131], v[48:51]
	v_mfma_f32_16x16x32_bf16 v[44:47], v[68:71], v[148:151], v[44:47]
	v_mfma_f32_16x16x32_bf16 v[36:39], v[76:79], v[148:151], v[36:39]
	v_mfma_f32_16x16x32_bf16 v[28:31], v[68:71], v[184:187], v[28:31]
	v_mfma_f32_16x16x32_bf16 v[20:23], v[76:79], v[184:187], v[20:23]
	v_mfma_f32_16x16x32_bf16 v[16:19], v[68:71], v[192:195], v[16:19]
	v_mfma_f32_16x16x32_bf16 v[12:15], v[76:79], v[192:195], v[12:15]
	s_barrier
	s_setprio 0
	s_add_u32 s78, s48, 0x80000
	s_addc_u32 s79, s49, 0
	s_add_i32 s59, s73, s62
	s_mov_b32 m0, s59
	s_nop 0
	global_load_lds_dwordx4 v164, s[78:79]
	s_add_i32 m0, s59, 0x2000
	s_nop 0
	global_load_lds_dwordx4 v160, s[78:79]
	s_add_i32 s59, 0, 0x18000
	v_add_u32_e32 v76, s59, v198
	ds_read_b128 v[64:67], v76
	ds_read_b128 v[68:71], v76 offset:1024
	ds_read_b128 v[72:75], v76 offset:2048
	ds_read_b128 v[76:79], v76 offset:3072
	s_waitcnt vmcnt(6)
	s_setprio 1
	s_barrier
; #define PG8_STAGE(bufoff, gbase, voff) do { _Pragma("unroll") for (int _i = 0; _i < 2; ++_i) \
;     __builtin_amdgcn_global_load_lds((const unsigned*)((const char*)(gbase) + (voff)[_i]), (LAS unsigned*)(lds + (bufoff) + ldsw + _i * 8192), 16, 0, 0); } while (0)
; #define PG8_LDA(dst, b, h) do { _Pragma("unroll") for (int m = 0; m < 4; ++m) _Pragma("unroll") for (int k = 0; k < 2; ++k) dst[m][k] = *(const LAS bf16x8*)(lds + PG8_SA(b, h) + aoff + m * 2048 + k * 1024); } while (0)
; #define PG8_LDB(dst, b, h) do { _Pragma("unroll") for (int n = 0; n < 2; ++n) _Pragma("unroll") for (int k = 0; k < 2; ++k) dst[n][k] = *(const LAS bf16x8*)(lds + PG8_SB(b, h) + boff + n * 2048 + k * 1024); } while (0)
; #define PG8_MMA(ai, bj, At, Bt) do { __builtin_amdgcn_s_setprio(1); _Pragma("unroll") for (int m = 0; m < 4; ++m) _Pragma("unroll") for (int n = 0; n < 2; ++n) _Pragma("unroll") for (int k = 0; k < 2; ++k) \
;     acc[ai][bj][m][n] = __builtin_amdgcn_mfma_f32_16x16x32_bf16(Bt[n][k], At[m][k], acc[ai][bj][m][n], 0, 0, 0); __builtin_amdgcn_s_setprio(0); } while (0)
; #define PG8_WAIT_V(n) asm volatile("s_waitcnt vmcnt(" #n ")" ::: "memory")
; #define PG8_WAIT_L(n) asm volatile("s_waitcnt lgkmcnt(" #n ")" ::: "memory")
; #define PG8_BAR __builtin_amdgcn_s_barrier()
; #define PG8_SCHED __builtin_amdgcn_sched_barrier(0)
; template <class Epi, class Sched = StaticOrder>
; DI void gemm_phase(LAS unsigned char* lds, const Gemm g, const Sched& S, const Epi& E) {
;     ...
;       PG8_WAIT_V(6); PG8_BAR; PG8_MMA(1, 1, At, B1); PG8_BAR;
;       PG8_LDB(B0, 1, 0); PG8_SCHED; PG8_LDA(At, 1, 0); PG8_STAGE(PG8_SA(0, 1), a2 + hstep, voffA);
;       PG8_WAIT_L(8); PG8_BAR; PG8_WAIT_L(0); PG8_MMA(0, 0, At, B0); PG8_BAR; PG8_SCHED;
;       PG8_LDB(B1, 1, 1); PG8_STAGE(PG8_SB(1, 0), b3, voffB);
;       PG8_BAR; PG8_WAIT_L(0); PG8_MMA(0, 1, At, B1); PG8_BAR;
;       PG8_LDA(At, 1, 1); PG8_STAGE(PG8_SA(1, 0), a3, voffA);
;       PG8_BAR; PG8_WAIT_L(0); PG8_MMA(1, 0, At, B0); PG8_BAR; PG8_SCHED;
	v_mfma_f32_16x16x32_bf16 v[56:59], v[206:209], v[120:123], v[56:59]
	v_mfma_f32_16x16x32_bf16 v[52:55], v[216:219], v[120:123], v[52:55]
	v_mfma_f32_16x16x32_bf16 v[40:43], v[206:209], v[136:139], v[40:43]
	v_mfma_f32_16x16x32_bf16 v[32:35], v[216:219], v[136:139], v[32:35]
	v_mfma_f32_16x16x32_bf16 v[24:27], v[206:209], v[180:183], v[24:27]
	v_mfma_f32_16x16x32_bf16 v[8:11], v[216:219], v[180:183], v[8:11]
	v_mfma_f32_16x16x32_bf16 v[4:7], v[206:209], v[188:191], v[4:7]
	v_mfma_f32_16x16x32_bf16 v[0:3], v[216:219], v[188:191], v[0:3]
	v_mfma_f32_16x16x32_bf16 v[56:59], v[212:215], v[128:131], v[56:59]
	v_mfma_f32_16x16x32_bf16 v[52:55], v[220:223], v[128:131], v[52:55]
	v_mfma_f32_16x16x32_bf16 v[40:43], v[212:215], v[148:151], v[40:43]
	v_mfma_f32_16x16x32_bf16 v[32:35], v[220:223], v[148:151], v[32:35]
	v_mfma_f32_16x16x32_bf16 v[24:27], v[212:215], v[184:187], v[24:27]
	v_mfma_f32_16x16x32_bf16 v[8:11], v[220:223], v[184:187], v[8:11]
	v_mfma_f32_16x16x32_bf16 v[4:7], v[212:215], v[192:195], v[4:7]
	v_mfma_f32_16x16x32_bf16 v[0:3], v[220:223], v[192:195], v[0:3]
	s_barrier
	s_setprio 0
	s_add_u32 s50, s50, 0x80000
	s_addc_u32 s51, s51, 0
	s_mov_b32 m0, s66
	ds_read_b128 v[120:123], v202 offset:32768
	ds_read_b128 v[128:131], v202 offset:33792
	ds_read_b128 v[180:183], v202 offset:34816
	ds_read_b128 v[184:187], v202 offset:35840
	ds_read_b128 v[188:191], v202 offset:36864
	ds_read_b128 v[192:195], v202 offset:37888
	ds_read_b128 v[206:209], v202 offset:38912
	ds_read_b128 v[212:215], v202 offset:39936
	global_load_lds_dwordx4 v166, s[50:51]
	s_mov_b32 m0, s67
	s_nop 0
	global_load_lds_dwordx4 v162, s[50:51]
	s_waitcnt lgkmcnt(0)
	s_setprio 1
	s_barrier
	v_mfma_f32_16x16x32_bf16 v[136:139], v[64:67], v[120:123], v[156:159]
	v_mfma_f32_16x16x32_bf16 v[156:159], v[68:71], v[128:131], v[136:139]
	v_mfma_f32_16x16x32_bf16 v[136:139], v[72:75], v[120:123], v[144:147]
	v_mfma_f32_16x16x32_bf16 v[144:147], v[76:79], v[128:131], v[136:139]
	v_mfma_f32_16x16x32_bf16 v[136:139], v[64:67], v[180:183], v[140:143]
	v_mfma_f32_16x16x32_bf16 v[132:135], v[72:75], v[180:183], v[132:135]
	v_mfma_f32_16x16x32_bf16 v[124:127], v[64:67], v[188:191], v[124:127]
	v_mfma_f32_16x16x32_bf16 v[116:119], v[72:75], v[188:191], v[116:119]
	v_mfma_f32_16x16x32_bf16 v[112:115], v[64:67], v[206:209], v[112:115]
	v_mfma_f32_16x16x32_bf16 v[108:111], v[72:75], v[206:209], v[108:111]
	v_mfma_f32_16x16x32_bf16 v[140:143], v[68:71], v[184:187], v[136:139]
	v_mfma_f32_16x16x32_bf16 v[132:135], v[76:79], v[184:187], v[132:135]
	v_mfma_f32_16x16x32_bf16 v[124:127], v[68:71], v[192:195], v[124:127]
	v_mfma_f32_16x16x32_bf16 v[116:119], v[76:79], v[192:195], v[116:119]
	v_mfma_f32_16x16x32_bf16 v[112:115], v[68:71], v[212:215], v[112:115]
	v_mfma_f32_16x16x32_bf16 v[108:111], v[76:79], v[212:215], v[108:111]
	s_barrier
	s_setprio 0
	s_add_i32 s50, 0, 0x1c000
	v_add_u32_e32 v136, s50, v198
	s_add_i32 s51, s59, s62
	ds_read_b128 v[216:219], v136
	ds_read_b128 v[220:223], v136 offset:1024
	ds_read_b128 v[224:227], v136 offset:2048
	ds_read_b128 v[228:231], v136 offset:3072
	s_mov_b32 m0, s51
	s_nop 0
	global_load_lds_dwordx4 v164, s[98:99]
	s_add_i32 m0, s51, 0x2000
	s_nop 0
	global_load_lds_dwordx4 v160, s[98:99]
	s_waitcnt lgkmcnt(0)
	s_setprio 1
	s_barrier
	v_mfma_f32_16x16x32_bf16 v[80:83], v[224:227], v[120:123], v[80:83]
	v_mfma_f32_16x16x32_bf16 v[136:139], v[216:219], v[120:123], v[152:155]
	v_mfma_f32_16x16x32_bf16 v[148:151], v[228:231], v[128:131], v[80:83]
	v_mfma_f32_16x16x32_bf16 v[80:83], v[216:219], v[180:183], v[84:87]
	v_mfma_f32_16x16x32_bf16 v[152:155], v[220:223], v[128:131], v[136:139]
	v_mfma_f32_16x16x32_bf16 v[136:139], v[220:223], v[184:187], v[80:83]
	v_mfma_f32_16x16x32_bf16 v[80:83], v[224:227], v[180:183], v[88:91]
	v_mfma_f32_16x16x32_bf16 v[128:131], v[228:231], v[184:187], v[80:83]
	v_mfma_f32_16x16x32_bf16 v[80:83], v[216:219], v[188:191], v[92:95]
	v_mfma_f32_16x16x32_bf16 v[120:123], v[220:223], v[192:195], v[80:83]
	v_mfma_f32_16x16x32_bf16 v[80:83], v[224:227], v[188:191], v[104:107]
	v_mfma_f32_16x16x32_bf16 v[104:107], v[228:231], v[192:195], v[80:83]
	v_mfma_f32_16x16x32_bf16 v[80:83], v[216:219], v[206:209], v[100:103]
	v_mfma_f32_16x16x32_bf16 v[100:103], v[220:223], v[212:215], v[80:83]
	v_mfma_f32_16x16x32_bf16 v[80:83], v[224:227], v[206:209], v[96:99]
	v_mfma_f32_16x16x32_bf16 v[96:99], v[228:231], v[212:215], v[80:83]
	s_barrier
	s_setprio 0
	s_mov_b32 m0, s55
	s_nop 2
	ds_read_b128 v[80:83], v202 offset:49152
	ds_read_b128 v[84:87], v202 offset:50176
	ds_read_b128 v[88:91], v202 offset:51200
	ds_read_b128 v[92:95], v202 offset:52224
	ds_read_b128 v[180:183], v202 offset:53248
	ds_read_b128 v[184:187], v202 offset:54272
	ds_read_b128 v[188:191], v202 offset:55296
	ds_read_b128 v[192:195], v202 offset:56320
	global_load_lds_dwordx4 v166, s[100:101]
	s_mov_b32 m0, s68
	s_nop 0
	global_load_lds_dwordx4 v162, s[100:101]
	s_waitcnt vmcnt(10)
	s_waitcnt lgkmcnt(0)
	s_setprio 1
	s_barrier
	v_mfma_f32_16x16x32_bf16 v[60:63], v[64:67], v[80:83], v[60:63]
	v_mfma_f32_16x16x32_bf16 v[48:51], v[72:75], v[80:83], v[48:51]
	v_mfma_f32_16x16x32_bf16 v[44:47], v[64:67], v[88:91], v[44:47]
	v_mfma_f32_16x16x32_bf16 v[36:39], v[72:75], v[88:91], v[36:39]
	v_mfma_f32_16x16x32_bf16 v[28:31], v[64:67], v[180:183], v[28:31]
	v_mfma_f32_16x16x32_bf16 v[20:23], v[72:75], v[180:183], v[20:23]
	v_mfma_f32_16x16x32_bf16 v[16:19], v[64:67], v[188:191], v[16:19]
	v_mfma_f32_16x16x32_bf16 v[12:15], v[72:75], v[188:191], v[12:15]
	v_mfma_f32_16x16x32_bf16 v[60:63], v[68:71], v[84:87], v[60:63]
	v_mfma_f32_16x16x32_bf16 v[48:51], v[76:79], v[84:87], v[48:51]
	v_mfma_f32_16x16x32_bf16 v[44:47], v[68:71], v[92:95], v[44:47]
	v_mfma_f32_16x16x32_bf16 v[36:39], v[76:79], v[92:95], v[36:39]
	v_mfma_f32_16x16x32_bf16 v[28:31], v[68:71], v[184:187], v[28:31]
	v_mfma_f32_16x16x32_bf16 v[20:23], v[76:79], v[184:187], v[20:23]
	v_mfma_f32_16x16x32_bf16 v[16:19], v[68:71], v[192:195], v[16:19]
	v_mfma_f32_16x16x32_bf16 v[12:15], v[76:79], v[192:195], v[12:15]
	s_barrier
; #define PG8_STAGE(bufoff, gbase, voff) do { _Pragma("unroll") for (int _i = 0; _i < 2; ++_i) \
;     __builtin_amdgcn_global_load_lds((const unsigned*)((const char*)(gbase) + (voff)[_i]), (LAS unsigned*)(lds + (bufoff) + ldsw + _i * 8192), 16, 0, 0); } while (0)
; #define PG8_MMA(ai, bj, At, Bt) do { __builtin_amdgcn_s_setprio(1); _Pragma("unroll") for (int m = 0; m < 4; ++m) _Pragma("unroll") for (int n = 0; n < 2; ++n) _Pragma("unroll") for (int k = 0; k < 2; ++k) \
;     acc[ai][bj][m][n] = __builtin_amdgcn_mfma_f32_16x16x32_bf16(Bt[n][k], At[m][k], acc[ai][bj][m][n], 0, 0, 0); __builtin_amdgcn_s_setprio(0); } while (0)
; #define PG8_WAIT_V(n) asm volatile("s_waitcnt vmcnt(" #n ")" ::: "memory")
; #define PG8_BAR __builtin_amdgcn_s_barrier()
;   DI void operator()(const f32x4 (&acc)[2][2][4][2], const Unit& u, int wr, int wc, int fr, int fq) const {
;     const int col = u.pn * 128 + wc * 32 + 8 * fq;
;     float w0[8], w1[8], w2[8], bb[8];
; #pragma unroll
;     for (int e = 0; e < 8; ++e) { w0[e] = cw[col + e]; w1[e] = cw[5632 + col + e]; w2[e] = cw[2 * 5632 + col + e]; bb[e] = cb[col + e]; }
; #pragma unroll
;     for (int ai = 0; ai < 2; ++ai) {
;       const int row0 = u.pm * BM + ai * HALF + wr * 64, span = row0 >> 6;
;       float rsv[4];
; #pragma unroll
;       for (int m = 0; m < 4; ++m) rsv[m] = row_rstd(ssq, row0 + 16 * m + fr, fq);
; template <class Epi, class Sched = StaticOrder>
; DI void gemm_phase(LAS unsigned char* lds, const Gemm g, const Sched& S, const Epi& E) {
;     ...
;       PG8_STAGE(PG8_SB(1, 1), b3 + hstep, voffB);
;       PG8_WAIT_V(6); PG8_BAR; PG8_MMA(1, 1, At, B1); PG8_BAR;
	s_setprio 0
	s_add_u32 s48, s48, 0x80080
	s_addc_u32 s49, s49, 0
	s_add_i32 s50, s50, s62
	s_mov_b32 m0, s50
	s_nop 0
	global_load_lds_dwordx4 v164, s[48:49]
	s_add_i32 m0, s50, 0x2000
	s_nop 0
	global_load_lds_dwordx4 v160, s[48:49]
	ds_read_b128 v[64:67], v201
	ds_read_b128 v[68:71], v201 offset:1024
	ds_read_b128 v[72:75], v201 offset:2048
	ds_read_b128 v[76:79], v201 offset:3072
	s_waitcnt vmcnt(6)
	s_setprio 1
	s_barrier
	v_mfma_f32_16x16x32_bf16 v[56:59], v[216:219], v[80:83], v[56:59]
	v_mfma_f32_16x16x32_bf16 v[52:55], v[224:227], v[80:83], v[52:55]
	v_mfma_f32_16x16x32_bf16 v[40:43], v[216:219], v[88:91], v[40:43]
	v_mfma_f32_16x16x32_bf16 v[32:35], v[224:227], v[88:91], v[32:35]
	v_mfma_f32_16x16x32_bf16 v[24:27], v[216:219], v[180:183], v[24:27]
	v_mfma_f32_16x16x32_bf16 v[8:11], v[224:227], v[180:183], v[8:11]
	v_mfma_f32_16x16x32_bf16 v[4:7], v[216:219], v[188:191], v[4:7]
	v_mfma_f32_16x16x32_bf16 v[0:3], v[224:227], v[188:191], v[0:3]
	v_mfma_f32_16x16x32_bf16 v[56:59], v[220:223], v[84:87], v[56:59]
	v_mfma_f32_16x16x32_bf16 v[52:55], v[228:231], v[84:87], v[52:55]
	v_mfma_f32_16x16x32_bf16 v[40:43], v[220:223], v[92:95], v[40:43]
	v_mfma_f32_16x16x32_bf16 v[32:35], v[228:231], v[92:95], v[32:35]
	v_mfma_f32_16x16x32_bf16 v[24:27], v[220:223], v[184:187], v[24:27]
	v_mfma_f32_16x16x32_bf16 v[8:11], v[228:231], v[184:187], v[8:11]
	v_mfma_f32_16x16x32_bf16 v[4:7], v[220:223], v[192:195], v[4:7]
	v_mfma_f32_16x16x32_bf16 v[0:3], v[228:231], v[192:195], v[0:3]
	s_add_i32 s58, s58, 2
	s_add_u32 s14, s14, 0x100
	s_addc_u32 s15, s15, 0
	s_add_u32 s52, s52, 0x100
	s_addc_u32 s53, s53, 0
	s_cmp_gt_u32 s58, 29
	s_barrier
	s_setprio 0
	s_cbranch_scc0 .LBB0_1277
	s_waitcnt lgkmcnt(0)
	s_lshl_b32 s39, s12, 8
	s_add_i32 s39, s39, s54
	v_or_b32_e32 v190, s39, v179
	v_ashrrev_i32_e32 v191, 31, v190
	v_lshlrev_b64 v[64:65], 7, v[190:191]
	v_or_b32_e32 v188, 16, v190
	v_lshl_add_u64 v[64:65], v[168:169], 0, v[64:65]
	v_ashrrev_i32_e32 v189, 31, v188
	global_load_dwordx4 v[192:195], v[64:65], off
	global_load_dwordx4 v[206:209], v[64:65], off offset:16
	v_lshlrev_b64 v[64:65], 7, v[188:189]
	v_lshl_add_u64 v[64:65], v[168:169], 0, v[64:65]
	global_load_dwordx4 v[212:215], v[64:65], off
	global_load_dwordx4 v[216:219], v[64:65], off offset:16
	v_or_b32_e32 v186, 32, v190
	v_ashrrev_i32_e32 v187, 31, v186
	v_lshlrev_b64 v[64:65], 7, v[186:187]
	v_or_b32_e32 v184, 48, v190
	v_lshl_add_u64 v[64:65], v[168:169], 0, v[64:65]
	v_ashrrev_i32_e32 v185, 31, v184
	global_load_dwordx4 v[220:223], v[64:65], off
	global_load_dwordx4 v[224:227], v[64:65], off offset:16
	v_lshlrev_b64 v[64:65], 7, v[184:185]
	v_lshl_add_u64 v[64:65], v[168:169], 0, v[64:65]
	global_load_dwordx4 v[228:231], v[64:65], off
	global_load_dwordx4 v[232:235], v[64:65], off offset:16
	v_lshl_or_b32 v180, s13, 7, v200
	v_and_b32_e32 v65, 64, v204
	v_xor_b32_e32 v64, 16, v204
	v_ashrrev_i32_e32 v181, 31, v180
	v_add_u32_e32 v65, 64, v65
	v_xor_b32_e32 v66, 32, v204
	v_lshlrev_b64 v[182:183], 2, v[180:181]
	v_cmp_lt_i32_e32 vcc, v64, v65
	v_lshl_add_u64 v[88:89], s[16:17], 0, v[182:183]
	v_lshl_add_u64 v[72:73], s[18:19], 0, v[182:183]
	v_cndmask_b32_e32 v64, v204, v64, vcc
	v_cmp_lt_i32_e32 vcc, v66, v65
	v_lshl_add_u64 v[74:75], v[88:89], 0, s[30:31]
	v_lshl_add_u64 v[76:77], v[88:89], 0, s[34:35]
	v_cndmask_b32_e32 v65, v204, v66, vcc
	v_add_co_u32_e32 v90, vcc, 0x5000, v88
	v_lshlrev_b32_e32 v187, 2, v64
	s_nop 0
	v_addc_co_u32_e32 v91, vcc, 0, v89, vcc
	v_add_co_u32_e32 v92, vcc, 0xb000, v88
	v_lshlrev_b32_e32 v185, 2, v65
	s_nop 0
	v_addc_co_u32_e32 v93, vcc, 0, v89, vcc
	global_load_dwordx4 v[64:67], v[88:89], off offset:16
	global_load_dwordx4 v[80:83], v[88:89], off
	global_load_dwordx4 v[68:71], v[72:73], off offset:16
	global_load_dwordx4 v[84:87], v[72:73], off
	s_nop 0
	global_load_dwordx4 v[72:75], v[74:75], off offset:16
	s_nop 0
	global_load_dwordx4 v[76:79], v[76:77], off offset:16
	s_nop 0
	global_load_dwordx4 v[88:91], v[90:91], off offset:2048
	s_nop 0
	global_load_dwordx4 v[92:95], v[92:93], off
	v_mov_b32_e32 v211, 0
	v_mov_b32_e32 v205, 0
	s_waitcnt vmcnt(0)
	v_mov_b32_e32 v196, v192
	v_mov_b32_e32 v197, v206
	v_mov_b32_e32 v206, v193
	v_mov_b32_e32 v192, v194
	v_mov_b32_e32 v193, v208
	v_mov_b32_e32 v208, v195
	v_pk_add_f32 v[194:195], v[196:197], v[206:207]
	v_pk_add_f32 v[192:193], v[192:193], v[208:209]
	v_mov_b32_e32 v196, v212
	v_mov_b32_e32 v197, v216
	v_mov_b32_e32 v216, v213
	v_mov_b32_e32 v206, v214
	v_mov_b32_e32 v207, v218
	v_mov_b32_e32 v218, v215
	v_pk_add_f32 v[192:193], v[194:195], v[192:193]
	v_pk_add_f32 v[194:195], v[196:197], v[216:217]
	v_pk_add_f32 v[196:197], v[206:207], v[218:219]
	v_mov_b32_e32 v208, v220
	v_pk_add_f32 v[194:195], v[194:195], v[196:197]
	v_mov_b32_e32 v197, v192
	v_mov_b32_e32 v196, v194
	v_mov_b32_e32 v192, v195
	v_pk_add_f32 v[192:193], v[196:197], v[192:193]
	ds_bpermute_b32 v195, v187, v193
	ds_bpermute_b32 v194, v187, v192
	v_mov_b32_e32 v209, v224
	v_mov_b32_e32 v224, v221
	v_mov_b32_e32 v212, v222
	v_mov_b32_e32 v213, v226
	s_waitcnt lgkmcnt(0)
	v_pk_add_f32 v[192:193], v[192:193], v[194:195]
	ds_bpermute_b32 v195, v185, v193
	ds_bpermute_b32 v194, v185, v192
	v_mov_b32_e32 v226, v223
	v_mov_b32_e32 v196, v228
	v_mov_b32_e32 v197, v232
	v_mov_b32_e32 v232, v229
	s_waitcnt lgkmcnt(0)
; DI unsigned pack2(float lo, float hi) { f32x2 v = {lo, hi}; bf16v2 r = __builtin_convertvector(v, bf16v2); return __builtin_bit_cast(unsigned, r); }
; DI float silu_f(float x) { return x * sigmoid_f(x); }
; DI float dpp_ror1(float v) { return __int_as_float(__builtin_amdgcn_update_dpp(0, __float_as_int(v), 0x121, 0xf, 0xf, false)); }
; DI float dpp_ror2(float v) { return __int_as_float(__builtin_amdgcn_update_dpp(0, __float_as_int(v), 0x122, 0xf, 0xf, false)); }
;   DI void operator()(const f32x4 (&acc)[2][2][4][2], const Unit& u, int wr, int wc, int fr, int fq) const {
;     ...
;       for (int m = 0; m < 4; ++m) rsv[m] = row_rstd(ssq, row0 + 16 * m + fr, fq);
;       float p1[8], p2[8];
; #pragma unroll
;       for (int e = 0; e < 8; ++e) { p1[e] = 0.f; p2[e] = 0.f; }
; #pragma unroll
;       for (int m = 0; m < 4; ++m) {
;         float g[8], uu[8], a[8];
;         const float rs = rsv[m];
; #pragma unroll
;         for (int e = 0; e < 4; ++e) { g[e] = acc[ai][0][m][0][e] * rs; g[4 + e] = acc[ai][0][m][1][e] * rs; uu[e] = acc[ai][1][m][0][e] * rs; uu[4 + e] = acc[ai][1][m][1][e] * rs; }
; #pragma unroll
;         for (int e = 0; e < 8; ++e) {
;           const float x1 = dpp_ror1(g[e]), x2 = dpp_ror2(g[e]);
;           const float pr1 = (fr == 0) ? p1[e] : x1, pr2 = (fr < 2) ? p2[e] : x2;
;           a[e] = w2[e] * g[e] + w1[e] * pr1 + w0[e] * pr2 + bb[e];
;           p1[e] = x1; p2[e] = x2;
;         }
;         if (m == 0 && fr < 2) {
;           float* ha = headA + (size_t)(span * 2 + fr) * 5632 + col; float* hu = headU + (size_t)(span * 2 + fr) * 5632 + col;
;           *(f32x4*)ha = (f32x4){a[0], a[1], a[2], a[3]}; *(f32x4*)(ha + 4) = (f32x4){a[4], a[5], a[6], a[7]};
;           *(f32x4*)hu = (f32x4){uu[0], uu[1], uu[2], uu[3]}; *(f32x4*)(hu + 4) = (f32x4){uu[4], uu[5], uu[6], uu[7]};
;         } else {
;           u32x4 w;
;           w.x = pack2(silu_f(a[0]) * uu[0], silu_f(a[1]) * uu[1]);
;           w.y = pack2(silu_f(a[2]) * uu[2], silu_f(a[3]) * uu[3]);
;           w.z = pack2(silu_f(a[4]) * uu[4], silu_f(a[5]) * uu[5]);
;           w.w = pack2(silu_f(a[6]) * uu[6], silu_f(a[7]) * uu[7]);
;           *(u32x4*)(H + (size_t)(row0 + 16 * m + fr) * 5632 + col) = w;
	v_pk_add_f32 v[192:193], v[192:193], v[194:195]
	v_mov_b32_e32 v206, v230
	v_pk_fma_f32 v[192:193], v[192:193], s[36:37], v[178:179] op_sel_hi:[1,0,0]
	v_mov_b32_e32 v207, v234
	v_mul_f32_e32 v189, 0x4b800000, v193
	v_cmp_gt_f32_e64 s[12:13], s74, v193
	v_mov_b32_e32 v234, v231
	v_pk_add_f32 v[208:209], v[208:209], v[224:225]
	v_cndmask_b32_e64 v189, v193, v189, s[12:13]
	v_rsq_f32_e32 v189, v189
	v_pk_add_f32 v[212:213], v[212:213], v[226:227]
	v_pk_add_f32 v[196:197], v[196:197], v[232:233]
	v_pk_add_f32 v[194:195], v[206:207], v[234:235]
	v_mul_f32_e32 v191, 0x45800000, v189
	v_cndmask_b32_e64 v220, v189, v191, s[12:13]
	v_pk_add_f32 v[208:209], v[208:209], v[212:213]
	v_pk_add_f32 v[194:195], v[196:197], v[194:195]
	v_pk_mul_f32 v[156:157], v[156:157], v[220:221] op_sel_hi:[1,0]
	v_mov_b32_e32 v216, 0
	v_mov_b32_e32 v218, 0
	v_mov_b32_e32 v196, v194
	v_mov_b32_e32 v197, v208
	v_mov_b32_e32 v208, v195
	v_mov_b32_dpp v216, v156 row_ror:1 row_mask:0xf bank_mask:0xf
	v_mov_b32_dpp v218, v157 row_ror:1 row_mask:0xf bank_mask:0xf
	v_pk_add_f32 v[194:195], v[196:197], v[208:209]
	v_cndmask_b32_e64 v207, v218, 0, s[0:1]
	v_cndmask_b32_e64 v206, v216, 0, s[0:1]
	v_pk_mul_f32 v[158:159], v[158:159], v[220:221] op_sel_hi:[1,0]
	v_mov_b32_e32 v212, 0
	v_mov_b32_e32 v214, 0
	ds_bpermute_b32 v197, v187, v195
	ds_bpermute_b32 v196, v187, v194
	v_mov_b32_e32 v215, 0
	v_mov_b32_e32 v217, 0
	v_pk_mul_f32 v[206:207], v[88:89], v[206:207]
	v_mov_b32_dpp v212, v158 row_ror:1 row_mask:0xf bank_mask:0xf
	v_mov_b32_dpp v214, v159 row_ror:1 row_mask:0xf bank_mask:0xf
	v_mov_b32_dpp v215, v156 row_ror:2 row_mask:0xf bank_mask:0xf
	v_mov_b32_dpp v217, v157 row_ror:2 row_mask:0xf bank_mask:0xf
	v_pk_fma_f32 v[156:157], v[92:93], v[156:157], v[206:207]
	v_mov_b32_e32 v213, 0
	v_cndmask_b32_e64 v207, v214, 0, s[0:1]
	v_cndmask_b32_e64 v206, v212, 0, s[0:1]
	v_cndmask_b32_e64 v209, v217, 0, s[4:5]
	v_cndmask_b32_e64 v208, v215, 0, s[4:5]
	v_mov_b32_dpp v211, v158 row_ror:2 row_mask:0xf bank_mask:0xf
	v_mov_b32_dpp v213, v159 row_ror:2 row_mask:0xf bank_mask:0xf
	v_pk_mul_f32 v[206:207], v[90:91], v[206:207]
	v_pk_fma_f32 v[156:157], v[80:81], v[208:209], v[156:157]
	v_cndmask_b32_e64 v209, v213, 0, s[4:5]
	v_cndmask_b32_e64 v208, v211, 0, s[4:5]
	v_pk_fma_f32 v[158:159], v[94:95], v[158:159], v[206:207]
	v_pk_mul_f32 v[144:145], v[144:145], v[220:221] op_sel_hi:[1,0]
	v_pk_fma_f32 v[158:159], v[82:83], v[208:209], v[158:159]
	v_mov_b32_e32 v207, 0
	v_mov_b32_e32 v209, 0
	v_pk_mul_f32 v[146:147], v[146:147], v[220:221] op_sel_hi:[1,0]
	v_mov_b32_e32 v191, 0
	s_waitcnt lgkmcnt(0)
	v_pk_add_f32 v[194:195], v[194:195], v[196:197]
	v_mov_b32_dpp v207, v144 row_ror:1 row_mask:0xf bank_mask:0xf
	v_mov_b32_dpp v209, v145 row_ror:1 row_mask:0xf bank_mask:0xf
	v_mov_b32_dpp v191, v146 row_ror:1 row_mask:0xf bank_mask:0xf
	v_mov_b32_dpp v205, v147 row_ror:1 row_mask:0xf bank_mask:0xf
	ds_bpermute_b32 v197, v185, v195
	ds_bpermute_b32 v196, v185, v194
	v_pk_mul_f32 v[152:153], v[152:153], v[220:221] op_sel_hi:[1,0]
	v_pk_mul_f32 v[148:149], v[148:149], v[220:221] op_sel_hi:[1,0]
	v_pk_mul_f32 v[154:155], v[154:155], v[220:221] op_sel_hi:[1,0]
	v_pk_mul_f32 v[150:151], v[150:151], v[220:221] op_sel_hi:[1,0]
	v_mov_b32_e32 v206, 0
	v_mov_b32_e32 v208, 0
	v_cndmask_b32_e64 v223, v209, 0, s[0:1]
	v_cndmask_b32_e64 v222, v207, 0, s[0:1]
	v_mov_b32_e32 v189, 0
	v_mov_b32_e32 v193, 0
	v_cndmask_b32_e64 v221, v205, 0, s[0:1]
	v_cndmask_b32_e64 v220, v191, 0, s[0:1]
	v_mov_b32_dpp v206, v144 row_ror:2 row_mask:0xf bank_mask:0xf
	v_mov_b32_dpp v208, v145 row_ror:2 row_mask:0xf bank_mask:0xf
	v_pk_mul_f32 v[222:223], v[72:73], v[222:223]
	v_mov_b32_dpp v189, v146 row_ror:2 row_mask:0xf bank_mask:0xf
	v_mov_b32_dpp v193, v147 row_ror:2 row_mask:0xf bank_mask:0xf
	v_pk_mul_f32 v[220:221], v[74:75], v[220:221]
	v_cndmask_b32_e64 v225, v208, 0, s[4:5]
	v_cndmask_b32_e64 v224, v206, 0, s[4:5]
	v_pk_fma_f32 v[144:145], v[76:77], v[144:145], v[222:223]
	v_cndmask_b32_e64 v223, v193, 0, s[4:5]
	v_cndmask_b32_e64 v222, v189, 0, s[4:5]
	v_pk_fma_f32 v[146:147], v[78:79], v[146:147], v[220:221]
	v_pk_fma_f32 v[144:145], v[64:65], v[224:225], v[144:145]
	v_pk_fma_f32 v[146:147], v[66:67], v[222:223], v[146:147]
	v_cmp_gt_f32_e32 vcc, s74, v192
	v_pk_add_f32 v[156:157], v[84:85], v[156:157]
	v_pk_add_f32 v[158:159], v[86:87], v[158:159]
	v_pk_add_f32 v[144:145], v[68:69], v[144:145]
	v_pk_add_f32 v[146:147], v[70:71], v[146:147]
	s_and_saveexec_b64 s[12:13], s[10:11]
	s_xor_b64 s[12:13], exec, s[12:13]
	s_cbranch_execz .LBB0_1280
	v_mul_f32_e32 v219, 0xbfb8aa3b, v156
	v_exp_f32_e32 v219, v219
	v_mul_f32_e32 v220, 0xbfb8aa3b, v157
	v_exp_f32_e32 v220, v220
	v_mul_f32_e32 v222, 0xbfb8aa3b, v159
	v_add_f32_e32 v219, 1.0, v219
	v_exp_f32_e32 v223, v222
	v_add_f32_e32 v221, 1.0, v220
	v_rcp_f32_e32 v220, v219
	v_mul_f32_e32 v219, 0xbfb8aa3b, v158
	v_exp_f32_e32 v219, v219
	v_rcp_f32_e32 v221, v221
	v_add_f32_e32 v219, 1.0, v219
	v_rcp_f32_e32 v222, v219
	v_add_f32_e32 v219, 1.0, v223
	v_rcp_f32_e32 v223, v219
	v_pk_mul_f32 v[156:157], v[156:157], v[220:221]
	s_nop 0
	v_pk_mul_f32 v[152:153], v[152:153], v[156:157]
	v_pk_mul_f32 v[156:157], v[158:159], v[222:223]
	v_cvt_pk_bf16_f32 v152, v152, v153
	v_mul_f32_e32 v153, 0xbfb8aa3b, v144
	v_pk_mul_f32 v[154:155], v[154:155], v[156:157]
	v_exp_f32_e32 v156, v153
	v_mul_f32_e32 v153, 0xbfb8aa3b, v145
	v_exp_f32_e32 v157, v153
	v_cvt_pk_bf16_f32 v153, v154, v155
	v_add_f32_e32 v154, 1.0, v156
	v_mul_f32_e32 v156, 0xbfb8aa3b, v146
	v_add_f32_e32 v155, 1.0, v157
	v_mul_f32_e32 v157, 0xbfb8aa3b, v147
	v_exp_f32_e32 v156, v156
	v_exp_f32_e32 v157, v157
	v_rcp_f32_e32 v154, v154
	v_rcp_f32_e32 v155, v155
	v_add_f32_e32 v156, 1.0, v156
	v_add_f32_e32 v157, 1.0, v157
	v_rcp_f32_e32 v156, v156
	v_rcp_f32_e32 v157, v157
	v_pk_mul_f32 v[144:145], v[144:145], v[154:155]
	s_nop 0
	v_pk_mul_f32 v[144:145], v[148:149], v[144:145]
	s_nop 0
	v_cvt_pk_bf16_f32 v154, v144, v145
	v_pk_mul_f32 v[144:145], v[146:147], v[156:157]
	s_nop 0
	v_pk_mul_f32 v[144:145], v[150:151], v[144:145]
	s_nop 0
	v_cvt_pk_bf16_f32 v155, v144, v145
	v_mov_b64_e32 v[144:145], s[20:21]
	v_mad_i64_i32 v[144:145], s[14:15], v190, s75, v[144:145]
	v_lshl_add_u64 v[144:145], v[180:181], 1, v[144:145]
	global_store_dwordx4 v[144:145], v[152:155], off

; #define PG8_STAGE(bufoff, gbase, voff) do { _Pragma("unroll") for (int _i = 0; _i < 2; ++_i) \
;     __builtin_amdgcn_global_load_lds((const unsigned*)((const char*)(gbase) + (voff)[_i]), (LAS unsigned*)(lds + (bufoff) + ldsw + _i * 8192), 16, 0, 0); } while (0)
; #define PG8_LDA(dst, b, h) do { _Pragma("unroll") for (int m = 0; m < 4; ++m) _Pragma("unroll") for (int k = 0; k < 2; ++k) dst[m][k] = *(const LAS bf16x8*)(lds + PG8_SA(b, h) + aoff + m * 2048 + k * 1024); } while (0)
; #define PG8_LDB(dst, b, h) do { _Pragma("unroll") for (int n = 0; n < 2; ++n) _Pragma("unroll") for (int k = 0; k < 2; ++k) dst[n][k] = *(const LAS bf16x8*)(lds + PG8_SB(b, h) + boff + n * 2048 + k * 1024); } while (0)
; #define PG8_MMA(ai, bj, At, Bt) do { __builtin_amdgcn_s_setprio(1); _Pragma("unroll") for (int m = 0; m < 4; ++m) _Pragma("unroll") for (int n = 0; n < 2; ++n) _Pragma("unroll") for (int k = 0; k < 2; ++k) \
;     acc[ai][bj][m][n] = __builtin_amdgcn_mfma_f32_16x16x32_bf16(Bt[n][k], At[m][k], acc[ai][bj][m][n], 0, 0, 0); __builtin_amdgcn_s_setprio(0); } while (0)
; #define PG8_WAIT_V(n) asm volatile("s_waitcnt vmcnt(" #n ")" ::: "memory")
; #define PG8_WAIT_L(n) asm volatile("s_waitcnt lgkmcnt(" #n ")" ::: "memory")
; #define PG8_BAR __builtin_amdgcn_s_barrier()
; #define PG8_SCHED __builtin_amdgcn_sched_barrier(0)
; template <class Epi, class Sched = StaticOrder>
; DI void gemm_phase(LAS unsigned char* lds, const Gemm g, const Sched& S, const Epi& E) {
;     ...
;     for (int t = 0; t < nt; t += 2) {
;       const bool last = (t == nt - 2);
;       const char* a1 = cA + (size_t)(t + 1) * kstep;
;       const char* a2 = last ? nA : cA + (size_t)(t + 2) * kstep; const char* b2 = last ? nB : cB + (size_t)(t + 2) * kstep;
;       const char* a3 = a2 + kstep; const char* b3 = b2 + kstep;
;       PG8_LDB(B0, 0, 0); PG8_SCHED; PG8_LDA(At, 0, 0); PG8_STAGE(PG8_SA(1, 1), a1 + hstep, voffA);
;       PG8_WAIT_L(8); PG8_BAR; PG8_WAIT_L(0); PG8_MMA(0, 0, At, B0); PG8_BAR; PG8_SCHED;
;       PG8_LDB(B1, 0, 1); PG8_STAGE(PG8_SB(0, 0), b2, voffB);
;       PG8_BAR; PG8_WAIT_L(0); PG8_MMA(0, 1, At, B1); PG8_BAR;
;       PG8_LDA(At, 0, 1); PG8_STAGE(PG8_SA(0, 0), a2, voffA);
;       PG8_BAR; PG8_WAIT_L(0); PG8_MMA(1, 0, At, B0); PG8_BAR; PG8_SCHED;
;       PG8_STAGE(PG8_SB(0, 1), b2 + hstep, voffB);
;       PG8_WAIT_V(6); PG8_BAR; PG8_MMA(1, 1, At, B1); PG8_BAR;
.LBB0_1424:
	s_add_u32 s18, s16, 0xffea0080
	s_addc_u32 s19, s17, -1
	s_cmpk_eq_i32 s47, 0x54
	s_cselect_b32 s21, s3, s19
	s_cselect_b32 s20, s2, s18
	s_cselect_b32 s19, s5, s46
	s_cselect_b32 s18, s4, s45
	s_add_i32 m0, s30, 0xc000
	ds_read_b128 v[166:169], v160
	ds_read_b128 v[170:173], v160 offset:1024
	ds_read_b128 v[174:177], v160 offset:2048
	ds_read_b128 v[178:181], v160 offset:3072
	ds_read_b128 v[182:185], v160 offset:4096
	ds_read_b128 v[186:189], v160 offset:5120
	ds_read_b128 v[190:193], v160 offset:6144
	ds_read_b128 v[194:197], v160 offset:7168
	global_load_lds_dwordx4 v136, s[16:17]
	s_add_i32 m0, s30, 0xe000
	s_nop 0
	global_load_lds_dwordx4 v138, s[16:17]
	s_waitcnt lgkmcnt(0)
	s_setprio 1
	s_barrier
	v_mfma_f32_16x16x32_bf16 v[124:127], v[144:147], v[166:169], v[124:127]
	v_mfma_f32_16x16x32_bf16 v[120:123], v[152:155], v[166:169], v[120:123]
	v_mfma_f32_16x16x32_bf16 v[116:119], v[144:147], v[174:177], v[116:119]
	v_mfma_f32_16x16x32_bf16 v[112:115], v[152:155], v[174:177], v[112:115]
	v_mfma_f32_16x16x32_bf16 v[104:107], v[144:147], v[182:185], v[104:107]
	v_mfma_f32_16x16x32_bf16 v[96:99], v[152:155], v[182:185], v[96:99]
	v_mfma_f32_16x16x32_bf16 v[88:91], v[144:147], v[190:193], v[88:91]
	v_mfma_f32_16x16x32_bf16 v[80:83], v[152:155], v[190:193], v[80:83]
	v_mfma_f32_16x16x32_bf16 v[124:127], v[148:151], v[170:173], v[124:127]
	v_mfma_f32_16x16x32_bf16 v[120:123], v[162:165], v[170:173], v[120:123]
	v_mfma_f32_16x16x32_bf16 v[116:119], v[148:151], v[178:181], v[116:119]
	v_mfma_f32_16x16x32_bf16 v[112:115], v[162:165], v[178:181], v[112:115]
	v_mfma_f32_16x16x32_bf16 v[104:107], v[148:151], v[186:189], v[104:107]
	v_mfma_f32_16x16x32_bf16 v[96:99], v[162:165], v[186:189], v[96:99]
	v_mfma_f32_16x16x32_bf16 v[88:91], v[148:151], v[194:197], v[88:91]
	v_mfma_f32_16x16x32_bf16 v[80:83], v[162:165], v[194:197], v[80:83]
	s_barrier
	s_setprio 0
	s_add_i32 s48, s39, s28
	s_add_u32 s98, s18, 0x80
	s_addc_u32 s99, s19, 0
	s_mov_b32 m0, s48
	ds_read_b128 v[198:201], v161
	ds_read_b128 v[202:205], v161 offset:1024
	ds_read_b128 v[206:209], v161 offset:2048
	ds_read_b128 v[210:213], v161 offset:3072
	global_load_lds_dwordx4 v132, s[18:19]
	s_add_i32 m0, s48, 0x2000
	s_nop 0
	global_load_lds_dwordx4 v128, s[18:19]
	s_waitcnt lgkmcnt(0)
	s_setprio 1
	s_barrier
	v_mfma_f32_16x16x32_bf16 v[108:111], v[198:201], v[166:169], v[108:111]
	v_mfma_f32_16x16x32_bf16 v[100:103], v[206:209], v[166:169], v[100:103]
	v_mfma_f32_16x16x32_bf16 v[92:95], v[198:201], v[174:177], v[92:95]
	v_mfma_f32_16x16x32_bf16 v[84:87], v[206:209], v[174:177], v[84:87]
	v_mfma_f32_16x16x32_bf16 v[76:79], v[198:201], v[182:185], v[76:79]
	v_mfma_f32_16x16x32_bf16 v[72:75], v[206:209], v[182:185], v[72:75]
	v_mfma_f32_16x16x32_bf16 v[68:71], v[198:201], v[190:193], v[68:71]
	v_mfma_f32_16x16x32_bf16 v[64:67], v[206:209], v[190:193], v[64:67]
	v_mfma_f32_16x16x32_bf16 v[108:111], v[202:205], v[170:173], v[108:111]
	v_mfma_f32_16x16x32_bf16 v[100:103], v[210:213], v[170:173], v[100:103]
	v_mfma_f32_16x16x32_bf16 v[92:95], v[202:205], v[178:181], v[92:95]
	v_mfma_f32_16x16x32_bf16 v[84:87], v[210:213], v[178:181], v[84:87]
	v_mfma_f32_16x16x32_bf16 v[76:79], v[202:205], v[186:189], v[76:79]
	v_mfma_f32_16x16x32_bf16 v[72:75], v[210:213], v[186:189], v[72:75]
	v_mfma_f32_16x16x32_bf16 v[68:71], v[202:205], v[194:197], v[68:71]
	v_mfma_f32_16x16x32_bf16 v[64:67], v[210:213], v[194:197], v[64:67]
	s_barrier
	s_setprio 0
	s_mov_b32 m0, s30
	s_add_u32 s100, s20, 0x80
	s_addc_u32 s101, s21, 0
	ds_read_b128 v[166:169], v160 offset:16384
	ds_read_b128 v[170:173], v160 offset:17408
	ds_read_b128 v[174:177], v160 offset:18432
	ds_read_b128 v[178:181], v160 offset:19456
	ds_read_b128 v[182:185], v160 offset:20480
	ds_read_b128 v[186:189], v160 offset:21504
	ds_read_b128 v[190:193], v160 offset:22528
	ds_read_b128 v[194:197], v160 offset:23552
	global_load_lds_dwordx4 v134, s[20:21]
	s_mov_b32 m0, s31
	s_nop 0
	global_load_lds_dwordx4 v130, s[20:21]
	s_waitcnt vmcnt(10)
	s_waitcnt lgkmcnt(0)
	s_setprio 1
	s_barrier
	v_mfma_f32_16x16x32_bf16 v[60:63], v[144:147], v[166:169], v[60:63]
	v_mfma_f32_16x16x32_bf16 v[56:59], v[152:155], v[166:169], v[56:59]
	v_mfma_f32_16x16x32_bf16 v[52:55], v[144:147], v[174:177], v[52:55]
	v_mfma_f32_16x16x32_bf16 v[44:47], v[152:155], v[174:177], v[44:47]
	v_mfma_f32_16x16x32_bf16 v[36:39], v[144:147], v[182:185], v[36:39]
	v_mfma_f32_16x16x32_bf16 v[28:31], v[152:155], v[182:185], v[28:31]
	v_mfma_f32_16x16x32_bf16 v[20:23], v[144:147], v[190:193], v[20:23]
	v_mfma_f32_16x16x32_bf16 v[12:15], v[152:155], v[190:193], v[12:15]
	v_mfma_f32_16x16x32_bf16 v[60:63], v[148:151], v[170:173], v[60:63]
	v_mfma_f32_16x16x32_bf16 v[56:59], v[162:165], v[170:173], v[56:59]
	v_mfma_f32_16x16x32_bf16 v[52:55], v[148:151], v[178:181], v[52:55]
	v_mfma_f32_16x16x32_bf16 v[44:47], v[162:165], v[178:181], v[44:47]
	v_mfma_f32_16x16x32_bf16 v[36:39], v[148:151], v[186:189], v[36:39]
	v_mfma_f32_16x16x32_bf16 v[28:31], v[162:165], v[186:189], v[28:31]
	v_mfma_f32_16x16x32_bf16 v[20:23], v[148:151], v[194:197], v[20:23]
	v_mfma_f32_16x16x32_bf16 v[12:15], v[162:165], v[194:197], v[12:15]
	s_barrier
	s_setprio 0
	s_add_u32 s48, s18, 0x160000
	s_addc_u32 s49, s19, 0
	s_add_i32 s50, s40, s28
	s_mov_b32 m0, s50
	s_nop 0
	global_load_lds_dwordx4 v132, s[48:49]
	s_add_i32 m0, s50, 0x2000
	s_nop 0
	global_load_lds_dwordx4 v128, s[48:49]
	s_add_i32 s48, 0, 0x18000
	v_add_u32_e32 v162, s48, v157
	ds_read_b128 v[144:147], v162
	ds_read_b128 v[148:151], v162 offset:1024
	ds_read_b128 v[152:155], v162 offset:2048
	ds_read_b128 v[162:165], v162 offset:3072
	s_waitcnt vmcnt(6)
	s_setprio 1
	s_barrier
; #define PG8_STAGE(bufoff, gbase, voff) do { _Pragma("unroll") for (int _i = 0; _i < 2; ++_i) \
;     __builtin_amdgcn_global_load_lds((const unsigned*)((const char*)(gbase) + (voff)[_i]), (LAS unsigned*)(lds + (bufoff) + ldsw + _i * 8192), 16, 0, 0); } while (0)
; #define PG8_LDA(dst, b, h) do { _Pragma("unroll") for (int m = 0; m < 4; ++m) _Pragma("unroll") for (int k = 0; k < 2; ++k) dst[m][k] = *(const LAS bf16x8*)(lds + PG8_SA(b, h) + aoff + m * 2048 + k * 1024); } while (0)
; #define PG8_LDB(dst, b, h) do { _Pragma("unroll") for (int n = 0; n < 2; ++n) _Pragma("unroll") for (int k = 0; k < 2; ++k) dst[n][k] = *(const LAS bf16x8*)(lds + PG8_SB(b, h) + boff + n * 2048 + k * 1024); } while (0)
; #define PG8_MMA(ai, bj, At, Bt) do { __builtin_amdgcn_s_setprio(1); _Pragma("unroll") for (int m = 0; m < 4; ++m) _Pragma("unroll") for (int n = 0; n < 2; ++n) _Pragma("unroll") for (int k = 0; k < 2; ++k) \
;     acc[ai][bj][m][n] = __builtin_amdgcn_mfma_f32_16x16x32_bf16(Bt[n][k], At[m][k], acc[ai][bj][m][n], 0, 0, 0); __builtin_amdgcn_s_setprio(0); } while (0)
; #define PG8_WAIT_V(n) asm volatile("s_waitcnt vmcnt(" #n ")" ::: "memory")
; #define PG8_WAIT_L(n) asm volatile("s_waitcnt lgkmcnt(" #n ")" ::: "memory")
; #define PG8_BAR __builtin_amdgcn_s_barrier()
; #define PG8_SCHED __builtin_amdgcn_sched_barrier(0)
; template <class Epi, class Sched = StaticOrder>
; DI void gemm_phase(LAS unsigned char* lds, const Gemm g, const Sched& S, const Epi& E) {
;     ...
;       PG8_BAR; PG8_WAIT_L(0); PG8_MMA(1, 0, At, B0); PG8_BAR; PG8_SCHED;
;       PG8_STAGE(PG8_SB(0, 1), b2 + hstep, voffB);
;       PG8_WAIT_V(6); PG8_BAR; PG8_MMA(1, 1, At, B1); PG8_BAR;
;       PG8_LDB(B0, 1, 0); PG8_SCHED; PG8_LDA(At, 1, 0); PG8_STAGE(PG8_SA(0, 1), a2 + hstep, voffA);
;       PG8_WAIT_L(8); PG8_BAR; PG8_WAIT_L(0); PG8_MMA(0, 0, At, B0); PG8_BAR; PG8_SCHED;
;       PG8_LDB(B1, 1, 1); PG8_STAGE(PG8_SB(1, 0), b3, voffB);
;       PG8_BAR; PG8_WAIT_L(0); PG8_MMA(0, 1, At, B1); PG8_BAR;
;       PG8_LDA(At, 1, 1); PG8_STAGE(PG8_SA(1, 0), a3, voffA);
;       PG8_BAR; PG8_WAIT_L(0); PG8_MMA(1, 0, At, B0); PG8_BAR; PG8_SCHED;
	v_mfma_f32_16x16x32_bf16 v[48:51], v[198:201], v[166:169], v[48:51]
	v_mfma_f32_16x16x32_bf16 v[40:43], v[206:209], v[166:169], v[40:43]
	v_mfma_f32_16x16x32_bf16 v[32:35], v[198:201], v[174:177], v[32:35]
	v_mfma_f32_16x16x32_bf16 v[24:27], v[206:209], v[174:177], v[24:27]
	v_mfma_f32_16x16x32_bf16 v[16:19], v[198:201], v[182:185], v[16:19]
	v_mfma_f32_16x16x32_bf16 v[8:11], v[206:209], v[182:185], v[8:11]
	v_mfma_f32_16x16x32_bf16 v[4:7], v[198:201], v[190:193], v[4:7]
	v_mfma_f32_16x16x32_bf16 v[0:3], v[206:209], v[190:193], v[0:3]
	v_mfma_f32_16x16x32_bf16 v[48:51], v[202:205], v[170:173], v[48:51]
	v_mfma_f32_16x16x32_bf16 v[40:43], v[210:213], v[170:173], v[40:43]
	v_mfma_f32_16x16x32_bf16 v[32:35], v[202:205], v[178:181], v[32:35]
	v_mfma_f32_16x16x32_bf16 v[24:27], v[210:213], v[178:181], v[24:27]
	v_mfma_f32_16x16x32_bf16 v[16:19], v[202:205], v[186:189], v[16:19]
	v_mfma_f32_16x16x32_bf16 v[8:11], v[210:213], v[186:189], v[8:11]
	v_mfma_f32_16x16x32_bf16 v[4:7], v[202:205], v[194:197], v[4:7]
	v_mfma_f32_16x16x32_bf16 v[0:3], v[210:213], v[194:197], v[0:3]
	s_barrier
	s_setprio 0
	s_add_u32 s20, s20, 0x160000
	s_addc_u32 s21, s21, 0
	s_mov_b32 m0, s33
	ds_read_b128 v[166:169], v160 offset:32768
	ds_read_b128 v[170:173], v160 offset:33792
	ds_read_b128 v[174:177], v160 offset:34816
	ds_read_b128 v[178:181], v160 offset:35840
	ds_read_b128 v[182:185], v160 offset:36864
	ds_read_b128 v[186:189], v160 offset:37888
	ds_read_b128 v[190:193], v160 offset:38912
	ds_read_b128 v[194:197], v160 offset:39936
	global_load_lds_dwordx4 v134, s[20:21]
	s_mov_b32 m0, s34
	s_nop 0
	global_load_lds_dwordx4 v130, s[20:21]
	s_waitcnt lgkmcnt(0)
	s_setprio 1
	s_barrier
	v_mfma_f32_16x16x32_bf16 v[124:127], v[144:147], v[166:169], v[124:127]
	v_mfma_f32_16x16x32_bf16 v[120:123], v[152:155], v[166:169], v[120:123]
	v_mfma_f32_16x16x32_bf16 v[116:119], v[144:147], v[174:177], v[116:119]
	v_mfma_f32_16x16x32_bf16 v[112:115], v[152:155], v[174:177], v[112:115]
	v_mfma_f32_16x16x32_bf16 v[104:107], v[144:147], v[182:185], v[104:107]
	v_mfma_f32_16x16x32_bf16 v[96:99], v[152:155], v[182:185], v[96:99]
	v_mfma_f32_16x16x32_bf16 v[88:91], v[144:147], v[190:193], v[88:91]
	v_mfma_f32_16x16x32_bf16 v[80:83], v[152:155], v[190:193], v[80:83]
	v_mfma_f32_16x16x32_bf16 v[124:127], v[148:151], v[170:173], v[124:127]
	v_mfma_f32_16x16x32_bf16 v[120:123], v[162:165], v[170:173], v[120:123]
	v_mfma_f32_16x16x32_bf16 v[116:119], v[148:151], v[178:181], v[116:119]
	v_mfma_f32_16x16x32_bf16 v[112:115], v[162:165], v[178:181], v[112:115]
	v_mfma_f32_16x16x32_bf16 v[104:107], v[148:151], v[186:189], v[104:107]
	v_mfma_f32_16x16x32_bf16 v[96:99], v[162:165], v[186:189], v[96:99]
	v_mfma_f32_16x16x32_bf16 v[88:91], v[148:151], v[194:197], v[88:91]
	v_mfma_f32_16x16x32_bf16 v[80:83], v[162:165], v[194:197], v[80:83]
	s_barrier
	s_setprio 0
	s_add_i32 s20, 0, 0x1c000
	s_add_i32 s21, s48, s28
	v_add_u32_e32 v210, s20, v157
	s_mov_b32 m0, s21
	ds_read_b128 v[198:201], v210
	ds_read_b128 v[202:205], v210 offset:1024
	ds_read_b128 v[206:209], v210 offset:2048
	ds_read_b128 v[210:213], v210 offset:3072
	global_load_lds_dwordx4 v132, s[98:99]
	s_add_i32 m0, s21, 0x2000
	s_nop 0
	global_load_lds_dwordx4 v128, s[98:99]
	s_waitcnt lgkmcnt(0)
	s_setprio 1
	s_barrier
	v_mfma_f32_16x16x32_bf16 v[108:111], v[198:201], v[166:169], v[108:111]
	v_mfma_f32_16x16x32_bf16 v[100:103], v[206:209], v[166:169], v[100:103]
	v_mfma_f32_16x16x32_bf16 v[92:95], v[198:201], v[174:177], v[92:95]
	v_mfma_f32_16x16x32_bf16 v[84:87], v[206:209], v[174:177], v[84:87]
	v_mfma_f32_16x16x32_bf16 v[76:79], v[198:201], v[182:185], v[76:79]
	v_mfma_f32_16x16x32_bf16 v[72:75], v[206:209], v[182:185], v[72:75]
	v_mfma_f32_16x16x32_bf16 v[68:71], v[198:201], v[190:193], v[68:71]
	v_mfma_f32_16x16x32_bf16 v[64:67], v[206:209], v[190:193], v[64:67]
	v_mfma_f32_16x16x32_bf16 v[108:111], v[202:205], v[170:173], v[108:111]
	v_mfma_f32_16x16x32_bf16 v[100:103], v[210:213], v[170:173], v[100:103]
	v_mfma_f32_16x16x32_bf16 v[92:95], v[202:205], v[178:181], v[92:95]
	v_mfma_f32_16x16x32_bf16 v[84:87], v[210:213], v[178:181], v[84:87]
	v_mfma_f32_16x16x32_bf16 v[76:79], v[202:205], v[186:189], v[76:79]
	v_mfma_f32_16x16x32_bf16 v[72:75], v[210:213], v[186:189], v[72:75]
	v_mfma_f32_16x16x32_bf16 v[68:71], v[202:205], v[194:197], v[68:71]
	v_mfma_f32_16x16x32_bf16 v[64:67], v[210:213], v[194:197], v[64:67]
	s_barrier
	s_setprio 0
	s_mov_b32 m0, s35
	ds_read_b128 v[166:169], v160 offset:49152
	ds_read_b128 v[170:173], v160 offset:50176
	ds_read_b128 v[174:177], v160 offset:51200
	ds_read_b128 v[178:181], v160 offset:52224
	ds_read_b128 v[182:185], v160 offset:53248
	ds_read_b128 v[186:189], v160 offset:54272
	ds_read_b128 v[190:193], v160 offset:55296
	ds_read_b128 v[194:197], v160 offset:56320
	global_load_lds_dwordx4 v134, s[100:101]
	s_mov_b32 m0, s36
	s_nop 0
	global_load_lds_dwordx4 v130, s[100:101]
	s_waitcnt vmcnt(10)
	s_waitcnt lgkmcnt(0)
	s_setprio 1
	s_barrier
	v_mfma_f32_16x16x32_bf16 v[60:63], v[144:147], v[166:169], v[60:63]
	v_mfma_f32_16x16x32_bf16 v[56:59], v[152:155], v[166:169], v[56:59]
	v_mfma_f32_16x16x32_bf16 v[52:55], v[144:147], v[174:177], v[52:55]
	v_mfma_f32_16x16x32_bf16 v[44:47], v[152:155], v[174:177], v[44:47]
	v_mfma_f32_16x16x32_bf16 v[36:39], v[144:147], v[182:185], v[36:39]
	v_mfma_f32_16x16x32_bf16 v[28:31], v[152:155], v[182:185], v[28:31]
	v_mfma_f32_16x16x32_bf16 v[20:23], v[144:147], v[190:193], v[20:23]
	v_mfma_f32_16x16x32_bf16 v[12:15], v[152:155], v[190:193], v[12:15]
	v_mfma_f32_16x16x32_bf16 v[60:63], v[148:151], v[170:173], v[60:63]
	v_mfma_f32_16x16x32_bf16 v[56:59], v[162:165], v[170:173], v[56:59]
	v_mfma_f32_16x16x32_bf16 v[52:55], v[148:151], v[178:181], v[52:55]
	v_mfma_f32_16x16x32_bf16 v[44:47], v[162:165], v[178:181], v[44:47]
	v_mfma_f32_16x16x32_bf16 v[36:39], v[148:151], v[186:189], v[36:39]
	v_mfma_f32_16x16x32_bf16 v[28:31], v[162:165], v[186:189], v[28:31]
	v_mfma_f32_16x16x32_bf16 v[20:23], v[148:151], v[194:197], v[20:23]
	v_mfma_f32_16x16x32_bf16 v[12:15], v[162:165], v[194:197], v[12:15]
	s_barrier
; #define PG8_STAGE(bufoff, gbase, voff) do { _Pragma("unroll") for (int _i = 0; _i < 2; ++_i) \
;     __builtin_amdgcn_global_load_lds((const unsigned*)((const char*)(gbase) + (voff)[_i]), (LAS unsigned*)(lds + (bufoff) + ldsw + _i * 8192), 16, 0, 0); } while (0)
; #define PG8_MMA(ai, bj, At, Bt) do { __builtin_amdgcn_s_setprio(1); _Pragma("unroll") for (int m = 0; m < 4; ++m) _Pragma("unroll") for (int n = 0; n < 2; ++n) _Pragma("unroll") for (int k = 0; k < 2; ++k) \
;     acc[ai][bj][m][n] = __builtin_amdgcn_mfma_f32_16x16x32_bf16(Bt[n][k], At[m][k], acc[ai][bj][m][n], 0, 0, 0); __builtin_amdgcn_s_setprio(0); } while (0)
; #define PG8_WAIT_V(n) asm volatile("s_waitcnt vmcnt(" #n ")" ::: "memory")
; #define PG8_WAIT_L(n) asm volatile("s_waitcnt lgkmcnt(" #n ")" ::: "memory")
; #define PG8_BAR __builtin_amdgcn_s_barrier()
; #define PG8_SCHED __builtin_amdgcn_sched_barrier(0)
;   DI void operator()(const f32x4 (&acc)[2][2][4][2], const Unit& u, int wr, int wc, int fr, int fq) const {
;     const int row0 = u.pm * BM + wr * 64 + fr, col0 = u.pn * BM + wc * 32 + 8 * fq;
; #pragma unroll
;     for (int ai = 0; ai < 2; ++ai) {
;       f32x4 bv[4][2][2];
; #pragma unroll
;       for (int m = 0; m < 4; ++m)
; #pragma unroll
;         for (int bj = 0; bj < 2; ++bj) {
;           const float* bp = base + (size_t)(row0 + ai * HALF + m * 16) * 2048 + col0 + bj * HALF;
;           bv[m][bj][0] = *(const f32x4*)bp; bv[m][bj][1] = *(const f32x4*)(bp + 4);
;         }
; template <class Epi, class Sched = StaticOrder>
; DI void gemm_phase(LAS unsigned char* lds, const Gemm g, const Sched& S, const Epi& E) {
;     ...
;       PG8_BAR; PG8_WAIT_L(0); PG8_MMA(1, 0, At, B0); PG8_BAR; PG8_SCHED;
;       PG8_STAGE(PG8_SB(1, 1), b3 + hstep, voffB);
;       PG8_WAIT_V(6); PG8_BAR; PG8_MMA(1, 1, At, B1); PG8_BAR;
;     }
	s_setprio 0
	s_add_u32 s18, s18, 0x160080
	s_addc_u32 s19, s19, 0
	s_add_i32 s20, s20, s28
	s_mov_b32 m0, s20
	s_nop 0
	global_load_lds_dwordx4 v132, s[18:19]
	s_add_i32 m0, s20, 0x2000
	s_nop 0
	global_load_lds_dwordx4 v128, s[18:19]
	ds_read_b128 v[144:147], v159
	ds_read_b128 v[148:151], v159 offset:1024
	ds_read_b128 v[152:155], v159 offset:2048
	ds_read_b128 v[162:165], v159 offset:3072
	s_waitcnt vmcnt(6)
	s_setprio 1
	s_barrier
	v_mfma_f32_16x16x32_bf16 v[48:51], v[198:201], v[166:169], v[48:51]
	v_mfma_f32_16x16x32_bf16 v[40:43], v[206:209], v[166:169], v[40:43]
	v_mfma_f32_16x16x32_bf16 v[32:35], v[198:201], v[174:177], v[32:35]
	v_mfma_f32_16x16x32_bf16 v[24:27], v[206:209], v[174:177], v[24:27]
	v_mfma_f32_16x16x32_bf16 v[16:19], v[198:201], v[182:185], v[16:19]
	v_mfma_f32_16x16x32_bf16 v[8:11], v[206:209], v[182:185], v[8:11]
	v_mfma_f32_16x16x32_bf16 v[4:7], v[198:201], v[190:193], v[4:7]
	v_mfma_f32_16x16x32_bf16 v[0:3], v[206:209], v[190:193], v[0:3]
	v_mfma_f32_16x16x32_bf16 v[48:51], v[202:205], v[170:173], v[48:51]
	v_mfma_f32_16x16x32_bf16 v[40:43], v[210:213], v[170:173], v[40:43]
	v_mfma_f32_16x16x32_bf16 v[32:35], v[202:205], v[178:181], v[32:35]
	v_mfma_f32_16x16x32_bf16 v[24:27], v[210:213], v[178:181], v[24:27]
	v_mfma_f32_16x16x32_bf16 v[16:19], v[202:205], v[186:189], v[16:19]
	v_mfma_f32_16x16x32_bf16 v[8:11], v[210:213], v[186:189], v[8:11]
	v_mfma_f32_16x16x32_bf16 v[4:7], v[202:205], v[194:197], v[4:7]
	v_mfma_f32_16x16x32_bf16 v[0:3], v[210:213], v[194:197], v[0:3]
	s_add_i32 s47, s47, 2
	s_add_u32 s16, s16, 0x100
	s_addc_u32 s17, s17, 0
	s_add_u32 s45, s45, 0x100
	s_addc_u32 s46, s46, 0
	s_cmpk_gt_u32 s47, 0x55
	s_barrier
	s_setprio 0
	s_cbranch_scc0 .LBB0_1424
	s_waitcnt lgkmcnt(0)
	v_lshl_or_b32 v144, s44, 8, v158
	v_lshl_add_u32 v154, s43, 8, v156
	v_ashrrev_i32_e32 v145, 31, v144
	v_lshlrev_b64 v[144:145], 2, v[144:145]
	v_ashrrev_i32_e32 v155, 31, v154
	v_lshl_add_u64 v[146:147], s[54:55], 0, v[144:145]
	v_lshlrev_b64 v[148:149], 13, v[154:155]
	v_or_b32_e32 v174, 16, v154
	v_lshl_add_u64 v[170:171], v[146:147], 0, v[148:149]
	v_ashrrev_i32_e32 v175, 31, v174
	global_load_dwordx4 v[150:153], v[170:171], off offset:16
	global_load_dwordx4 v[162:165], v[170:171], off
	global_load_dwordx4 v[166:169], v[170:171], off offset:528
	s_nop 0
	global_load_dwordx4 v[170:173], v[170:171], off offset:512
	v_lshlrev_b64 v[222:223], 13, v[174:175]
	v_or_b32_e32 v190, 32, v154
	v_lshl_add_u64 v[186:187], v[146:147], 0, v[222:223]
	v_ashrrev_i32_e32 v191, 31, v190
	global_load_dwordx4 v[174:177], v[186:187], off offset:16
	global_load_dwordx4 v[178:181], v[186:187], off
	global_load_dwordx4 v[182:185], v[186:187], off offset:528
	s_nop 0
	global_load_dwordx4 v[186:189], v[186:187], off offset:512
	v_lshlrev_b64 v[224:225], 13, v[190:191]
	v_or_b32_e32 v154, 48, v154
	v_lshl_add_u64 v[202:203], v[146:147], 0, v[224:225]
	v_ashrrev_i32_e32 v155, 31, v154
	global_load_dwordx4 v[190:193], v[202:203], off offset:16
	global_load_dwordx4 v[194:197], v[202:203], off
	global_load_dwordx4 v[198:201], v[202:203], off offset:528
	s_nop 0
	global_load_dwordx4 v[202:205], v[202:203], off offset:512
	v_lshlrev_b64 v[154:155], 13, v[154:155]
	v_lshl_add_u64 v[218:219], v[146:147], 0, v[154:155]
	global_load_dwordx4 v[206:209], v[218:219], off offset:16
	global_load_dwordx4 v[210:213], v[218:219], off
	global_load_dwordx4 v[214:217], v[218:219], off offset:528
	s_nop 0
	global_load_dwordx4 v[218:221], v[218:219], off offset:512
	s_and_b64 vcc, exec, s[0:1]
	s_mov_b32 s44, s41
	s_mov_b32 s43, s42
	s_mov_b64 s[18:19], s[4:5]
	s_mov_b64 s[16:17], s[2:3]
	s_waitcnt vmcnt(0)
; DI unsigned pack2(float lo, float hi) { f32x2 v = {lo, hi}; bf16v2 r = __builtin_convertvector(v, bf16v2); return __builtin_bit_cast(unsigned, r); }
; #define PG8_WAIT_V(n) asm volatile("s_waitcnt vmcnt(" #n ")" ::: "memory")
; #define PG8_BAR __builtin_amdgcn_s_barrier()
;   DI void operator()(const f32x4 (&acc)[2][2][4][2], const Unit& u, int wr, int wc, int fr, int fq) const {
;     ...
;       for (int m = 0; m < 4; ++m) {
;         const int row = row0 + ai * HALF + m * 16;
;         const size_t off = (size_t)row * 2048 + col0;
;         float ss = 0.f;
; #pragma unroll
;         for (int bj = 0; bj < 2; ++bj) {
;           const f32x4 v0 = acc[ai][bj][m][0] + bv[m][bj][0], v1 = acc[ai][bj][m][1] + bv[m][bj][1];
;           *(f32x4*)(C + off + bj * HALF) = v0; *(f32x4*)(C + off + bj * HALF + 4) = v1;
;           if (xb) {
;             u32x4 w; w.x = pack2(v0[0], v0[1]); w.y = pack2(v0[2], v0[3]); w.z = pack2(v1[0], v1[1]); w.w = pack2(v1[2], v1[3]);
;             *(u32x4*)(xb + off + bj * HALF) = w;
;             ss += v0[0] * v0[0] + v0[1] * v0[1] + v0[2] * v0[2] + v0[3] * v0[3] + v1[0] * v1[0] + v1[1] * v1[1] + v1[2] * v1[2] + v1[3] * v1[3];
;           }
;         }
;         if (xb) {
;           ss += __shfl_xor(ss, 16); ss += __shfl_xor(ss, 32);
;           if (fq == 0) ssq[(size_t)row * 32 + u.pn * 4 + wc] = ss;
;         }
; template <class Epi, class Sched = StaticOrder>
; DI void gemm_phase(LAS unsigned char* lds, const Gemm g, const Sched& S, const Epi& E) {
;     ...
;     E(acc, cur, wr, wc, fr, fq);
;     if (!has_next) break;
; #pragma unroll
;     for (int a = 0; a < 2; ++a)
; #pragma unroll
;       for (int b = 0; b < 2; ++b)
; #pragma unroll
;         for (int m = 0; m < 4; ++m)
; #pragma unroll
;           for (int n = 0; n < 2; ++n) acc[a][b][m][n] = (f32x4){0.f, 0.f, 0.f, 0.f};
;     cur = nxt; cA = nA; cB = nB; ++ui;
;   }
;   PG8_WAIT_V(0);
;   if (wr == 0) PG8_BAR;
;   PG8_BAR;
	v_pk_add_f32 v[120:121], v[120:121], v[150:151]
	v_lshl_add_u64 v[150:151], s[54:55], 0, v[148:149]
	v_pk_add_f32 v[126:127], v[126:127], v[164:165]
	v_pk_add_f32 v[124:125], v[124:125], v[162:163]
	v_lshl_add_u64 v[150:151], v[150:151], 0, v[144:145]
	v_pk_add_f32 v[110:111], v[110:111], v[172:173]
	v_pk_add_f32 v[108:109], v[108:109], v[170:171]
	v_pk_add_f32 v[122:123], v[122:123], v[152:153]
	global_store_dwordx4 v[150:151], v[124:127], off
	global_store_dwordx4 v[150:151], v[120:123], off offset:16
	v_pk_add_f32 v[102:103], v[102:103], v[168:169]
	v_pk_add_f32 v[100:101], v[100:101], v[166:167]
	global_store_dwordx4 v[150:151], v[108:111], off offset:512
	global_store_dwordx4 v[150:151], v[100:103], off offset:528
	v_pk_add_f32 v[94:95], v[94:95], v[188:189]
	v_pk_add_f32 v[108:109], v[112:113], v[174:175]
	v_lshl_add_u64 v[112:113], s[54:55], 0, v[222:223]
	v_pk_add_f32 v[102:103], v[118:119], v[180:181]
	v_pk_add_f32 v[100:101], v[116:117], v[178:179]
	v_lshl_add_u64 v[112:113], v[112:113], 0, v[144:145]
	v_pk_add_f32 v[92:93], v[92:93], v[186:187]
	v_pk_add_f32 v[110:111], v[114:115], v[176:177]
	global_store_dwordx4 v[112:113], v[100:103], off
	global_store_dwordx4 v[112:113], v[108:111], off offset:16
	v_pk_add_f32 v[86:87], v[86:87], v[184:185]
	v_pk_add_f32 v[84:85], v[84:85], v[182:183]
	global_store_dwordx4 v[112:113], v[92:95], off offset:512
	global_store_dwordx4 v[112:113], v[84:87], off offset:528
	v_pk_add_f32 v[78:79], v[78:79], v[204:205]
	v_pk_add_f32 v[92:93], v[96:97], v[190:191]
	v_lshl_add_u64 v[96:97], s[54:55], 0, v[224:225]
	v_pk_add_f32 v[86:87], v[106:107], v[196:197]
	v_pk_add_f32 v[84:85], v[104:105], v[194:195]
	v_lshl_add_u64 v[96:97], v[96:97], 0, v[144:145]
	v_pk_add_f32 v[76:77], v[76:77], v[202:203]
	v_pk_add_f32 v[94:95], v[98:99], v[192:193]
	global_store_dwordx4 v[96:97], v[84:87], off
	global_store_dwordx4 v[96:97], v[92:95], off offset:16
	v_pk_add_f32 v[74:75], v[74:75], v[200:201]
	v_pk_add_f32 v[72:73], v[72:73], v[198:199]
	global_store_dwordx4 v[96:97], v[76:79], off offset:512
	global_store_dwordx4 v[96:97], v[72:75], off offset:528
	v_pk_add_f32 v[70:71], v[70:71], v[220:221]
	v_pk_add_f32 v[76:77], v[80:81], v[206:207]
	v_lshl_add_u64 v[80:81], s[54:55], 0, v[154:155]
	v_pk_add_f32 v[74:75], v[90:91], v[212:213]
	v_pk_add_f32 v[72:73], v[88:89], v[210:211]
	v_lshl_add_u64 v[80:81], v[80:81], 0, v[144:145]
	v_pk_add_f32 v[68:69], v[68:69], v[218:219]
	v_pk_add_f32 v[64:65], v[64:65], v[214:215]
	v_lshl_add_u64 v[154:155], v[148:149], 0, s[10:11]
	v_pk_add_f32 v[78:79], v[82:83], v[208:209]
	global_store_dwordx4 v[80:81], v[72:75], off
	global_store_dwordx4 v[80:81], v[76:79], off offset:16
	v_pk_add_f32 v[66:67], v[66:67], v[216:217]
	global_store_dwordx4 v[80:81], v[68:71], off offset:512
	global_store_dwordx4 v[80:81], v[64:67], off offset:528
	v_lshl_add_u64 v[152:153], v[148:149], 0, s[12:13]
	v_lshl_add_u64 v[150:151], v[148:149], 0, s[14:15]
	v_lshl_add_u64 v[64:65], v[146:147], 0, v[154:155]
	global_load_dwordx4 v[108:111], v[64:65], off offset:16
	global_load_dwordx4 v[120:123], v[64:65], off
	global_load_dwordx4 v[92:95], v[64:65], off offset:528
	global_load_dwordx4 v[100:103], v[64:65], off offset:512
	v_lshl_add_u64 v[64:65], v[146:147], 0, v[152:153]
	global_load_dwordx4 v[88:91], v[64:65], off offset:16
	global_load_dwordx4 v[96:99], v[64:65], off
	global_load_dwordx4 v[76:79], v[64:65], off offset:528
	global_load_dwordx4 v[84:87], v[64:65], off offset:512
	v_lshl_add_u64 v[68:69], v[146:147], 0, v[150:151]
	global_load_dwordx4 v[72:75], v[68:69], off offset:16
	global_load_dwordx4 v[80:83], v[68:69], off
	global_load_dwordx4 v[64:67], v[68:69], off offset:528
	s_nop 0
	global_load_dwordx4 v[68:71], v[68:69], off offset:512
	v_lshl_add_u64 v[148:149], v[148:149], 0, s[6:7]
	v_lshl_add_u64 v[112:113], v[146:147], 0, v[148:149]
	global_load_dwordx4 v[116:119], v[112:113], off offset:16
	global_load_dwordx4 v[124:127], v[112:113], off
	global_load_dwordx4 v[104:107], v[112:113], off offset:528
	s_nop 0
	global_load_dwordx4 v[112:115], v[112:113], off offset:512
	s_waitcnt vmcnt(0)
	v_pk_add_f32 v[56:57], v[56:57], v[108:109]
	v_lshl_add_u64 v[108:109], s[54:55], 0, v[154:155]
	v_pk_add_f32 v[62:63], v[62:63], v[122:123]
	v_pk_add_f32 v[60:61], v[60:61], v[120:121]
	v_lshl_add_u64 v[108:109], v[108:109], 0, v[144:145]
	v_pk_add_f32 v[50:51], v[50:51], v[102:103]
	v_pk_add_f32 v[48:49], v[48:49], v[100:101]
	v_pk_add_f32 v[58:59], v[58:59], v[110:111]
	global_store_dwordx4 v[108:109], v[60:63], off
	global_store_dwordx4 v[108:109], v[56:59], off offset:16
	v_pk_add_f32 v[42:43], v[42:43], v[94:95]
	v_pk_add_f32 v[40:41], v[40:41], v[92:93]
	global_store_dwordx4 v[108:109], v[48:51], off offset:512
	global_store_dwordx4 v[108:109], v[40:43], off offset:528
	v_pk_add_f32 v[34:35], v[34:35], v[86:87]
	v_lshl_add_u64 v[48:49], s[54:55], 0, v[152:153]
	v_pk_add_f32 v[42:43], v[54:55], v[98:99]
	v_pk_add_f32 v[40:41], v[52:53], v[96:97]
	v_lshl_add_u64 v[48:49], v[48:49], 0, v[144:145]
	v_pk_add_f32 v[32:33], v[32:33], v[84:85]
	v_pk_add_f32 v[46:47], v[46:47], v[90:91]
	v_pk_add_f32 v[44:45], v[44:45], v[88:89]
	global_store_dwordx4 v[48:49], v[40:43], off
	global_store_dwordx4 v[48:49], v[44:47], off offset:16
	v_pk_add_f32 v[26:27], v[26:27], v[78:79]
	v_pk_add_f32 v[24:25], v[24:25], v[76:77]
	global_store_dwordx4 v[48:49], v[32:35], off offset:512
	global_store_dwordx4 v[48:49], v[24:27], off offset:528
	v_pk_add_f32 v[18:19], v[18:19], v[70:71]
	v_lshl_add_u64 v[32:33], s[54:55], 0, v[150:151]
	v_pk_add_f32 v[26:27], v[38:39], v[82:83]
	v_pk_add_f32 v[24:25], v[36:37], v[80:81]
	v_lshl_add_u64 v[32:33], v[32:33], 0, v[144:145]
	v_pk_add_f32 v[16:17], v[16:17], v[68:69]
	v_pk_add_f32 v[30:31], v[30:31], v[74:75]
	v_pk_add_f32 v[28:29], v[28:29], v[72:73]
	global_store_dwordx4 v[32:33], v[24:27], off
	global_store_dwordx4 v[32:33], v[28:31], off offset:16
	v_pk_add_f32 v[10:11], v[10:11], v[66:67]
	v_pk_add_f32 v[8:9], v[8:9], v[64:65]
	global_store_dwordx4 v[32:33], v[16:19], off offset:512
	global_store_dwordx4 v[32:33], v[8:11], off offset:528
	v_pk_add_f32 v[6:7], v[6:7], v[114:115]
	v_lshl_add_u64 v[16:17], s[54:55], 0, v[148:149]
	v_pk_add_f32 v[10:11], v[22:23], v[126:127]
	v_pk_add_f32 v[8:9], v[20:21], v[124:125]
	v_lshl_add_u64 v[16:17], v[16:17], 0, v[144:145]
	v_pk_add_f32 v[4:5], v[4:5], v[112:113]
	v_pk_add_f32 v[14:15], v[14:15], v[118:119]
	v_pk_add_f32 v[12:13], v[12:13], v[116:117]
	global_store_dwordx4 v[16:17], v[8:11], off
	global_store_dwordx4 v[16:17], v[12:15], off offset:16
	v_pk_add_f32 v[2:3], v[2:3], v[106:107]
	v_pk_add_f32 v[0:1], v[0:1], v[104:105]
	global_store_dwordx4 v[16:17], v[4:7], off offset:512
	global_store_dwordx4 v[16:17], v[0:3], off offset:528
	s_cbranch_vccz .LBB0_1417
	s_waitcnt vmcnt(0)
	s_cmpk_gt_u32 s23, 0xff
	s_cbranch_scc1 .LBB0_1428
	s_barrier

; __global__ __launch_bounds__(512) void mega(Params p) {
;   extern __shared__ __attribute__((aligned(16))) unsigned char smem[];
	.amdhsa_kernel _Z4mega6Params
		.amdhsa_group_segment_fixed_size 0
		.amdhsa_private_segment_fixed_size 0
		.amdhsa_kernarg_size 464
		.amdhsa_user_sgpr_count 2
		.amdhsa_user_sgpr_dispatch_ptr 0
		.amdhsa_user_sgpr_queue_ptr 0
		.amdhsa_user_sgpr_kernarg_segment_ptr 1
		.amdhsa_user_sgpr_dispatch_id 0
		.amdhsa_user_sgpr_kernarg_preload_length 0
		.amdhsa_user_sgpr_kernarg_preload_offset 0
		.amdhsa_user_sgpr_private_segment_size 0
		.amdhsa_uses_dynamic_stack 0
		.amdhsa_enable_private_segment 0
		.amdhsa_system_sgpr_workgroup_id_x 1
		.amdhsa_system_sgpr_workgroup_id_y 0
		.amdhsa_system_sgpr_workgroup_id_z 0
		.amdhsa_system_sgpr_workgroup_info 0
		.amdhsa_system_vgpr_workitem_id 2
		.amdhsa_next_free_vgpr 244
		.amdhsa_next_free_sgpr 102
		.amdhsa_accum_offset 244
		.amdhsa_reserve_vcc 1
		.amdhsa_float_round_mode_32 0
		.amdhsa_float_round_mode_16_64 0
		.amdhsa_float_denorm_mode_32 3
		.amdhsa_float_denorm_mode_16_64 3
		.amdhsa_dx10_clamp 1
		.amdhsa_ieee_mode 1
		.amdhsa_fp16_overflow 0
		.amdhsa_tg_split 0
		.amdhsa_exception_fp_ieee_invalid_op 0
		.amdhsa_exception_fp_denorm_src 0
		.amdhsa_exception_fp_ieee_div_zero 0
		.amdhsa_exception_fp_ieee_overflow 0
		.amdhsa_exception_fp_ieee_underflow 0
		.amdhsa_exception_fp_ieee_inexact 0
		.amdhsa_exception_int_div_zero 0
	.end_amdhsa_kernel

; __global__ __launch_bounds__(512) void mega(Params p) {
;   extern __shared__ __attribute__((aligned(16))) unsigned char smem[];
amdhsa.kernels:
  - .agpr_count:     0
    .args:
      - .offset:         0
        .size:           208
        .value_kind:     by_value
      - .offset:         208
        .size:           4
        .value_kind:     hidden_block_count_x
      - .offset:         212
        .size:           4
        .value_kind:     hidden_block_count_y
      - .offset:         216
        .size:           4
        .value_kind:     hidden_block_count_z
      - .offset:         220
        .size:           2
        .value_kind:     hidden_group_size_x
      - .offset:         222
        .size:           2
        .value_kind:     hidden_group_size_y
      - .offset:         224
        .size:           2
        .value_kind:     hidden_group_size_z
      - .offset:         226
        .size:           2
        .value_kind:     hidden_remainder_x
      - .offset:         228
        .size:           2
        .value_kind:     hidden_remainder_y
      - .offset:         230
        .size:           2
        .value_kind:     hidden_remainder_z
      - .offset:         248
        .size:           8
        .value_kind:     hidden_global_offset_x
      - .offset:         256
        .size:           8
        .value_kind:     hidden_global_offset_y
      - .offset:         264
        .size:           8
        .value_kind:     hidden_global_offset_z
      - .offset:         272
        .size:           2
        .value_kind:     hidden_grid_dims
      - .offset:         296
        .size:           8
        .value_kind:     hidden_multigrid_sync_arg
      - .offset:         328
        .size:           4
        .value_kind:     hidden_dynamic_lds_size
    .group_segment_fixed_size: 0
    .kernarg_segment_align: 8
    .kernarg_segment_size: 464
    .language:       OpenCL C
    .language_version:
      - 2
      - 0
    .max_flat_workgroup_size: 512
    .name:           _Z4mega6Params
    .private_segment_fixed_size: 0
    .sgpr_count:     108
    .sgpr_spill_count: 125
    .symbol:         _Z4mega6Params.kd
    .uniform_work_group_size: 1
    .uses_dynamic_stack: false
    .vgpr_count:     244
    .vgpr_spill_count: 0
    .wavefront_size: 64
